# P10: the block's PEER sub-key table (one head: first product half complete, 5/8 of the second) staged once into LDS with a padded conflict-free layout; score MFMAs read fragments with ds_read_b128 ins
# speedup vs baseline: 1.1810x; 1.0141x over previous
; #define MFMA(a, b, c) __builtin_amdgcn_mfma_f32_16x16x32_bf16((a), (b), (c), 0, 0, 0)
; DI unsigned ordf(float f) { unsigned u = __float_as_uint(f); return (u & 0x80000000u) ? ~u : (u | 0x80000000u); }
; #define REP(ph) for (int rp_ = 0; rp_ < ((DBL == (ph)) ? 2 : 1); ++rp_)
; DI void peer_topk_wave(const Params& p, int item, unsigned* lds  ) {
;   const int lane = threadIdx.x & 63, r = lane & 15, kg = lane >> 4;
;   const int h = item & 7, row0 = (item >> 3) * 16;
;   unsigned win[2][16];
; #pragma unroll
;   for (int pp = 0; pp < 2; ++pp) {
;     bf16x8 qf[4];
; #pragma unroll
;     for (int ks = 0; ks < 4; ++ks) qf[ks] = *(const bf16x8*)&p.pq[(size_t)(row0 + r) * 2048 + h * 256 + pp * 128 + ks * 32 + kg * 8];
;     unsigned kk[32];
;     const u16* sk = p.subkb + (size_t)(h * 2 + pp) * 16384;
; #pragma unroll
;     for (int mt = 0; mt < 8; ++mt) {
;       f32x4 a = (f32x4){0.f, 0.f, 0.f, 0.f};
; #pragma unroll
;       for (int ks = 0; ks < 4; ++ks) {
;         bf16x8 kf = *(const bf16x8*)&sk[(mt * 16 + r) * 128 + ks * 32 + kg * 8];
;         a = MFMA(kf, qf[ks], a);
;       }
; #pragma unroll
;       for (int j = 0; j < 4; ++j) kk[mt * 4 + j] = (ordf(a[j]) & ~127u) | (unsigned)(mt * 16 + kg * 4 + j);
; __global__ void __launch_bounds__(256, 2) mega(Params pk) {
;     ...
;   REP(10) {
;     unsigned* lds = (unsigned*)smem + w * 512;
;     for (int it = blockIdx.x * 4 + w; it < 2056 * 8; it += gridDim.x * 4) peer_topk_wave(p, it, lds);
.LBB0_1087:
	s_or_b64 exec, exec, s[2:3]
	s_movk_i32 s0, 0x4040
	v_cmp_gt_i32_e32 vcc, s0, v163
	s_waitcnt lgkmcnt(0)
	s_barrier
	s_and_saveexec_b64 s[72:73], vcc
	s_cbranch_execz .LBB0_1304
	v_mov_b32_e32 v3, 0x61
	v_cmp_eq_u32_e64 s[10:11], 2, v175
	v_mov_b32_e32 v5, 0x42
	v_lshlrev_b32_e32 v1, 7, v134
	v_cndmask_b32_e64 v97, v3, 32, s[10:11]
	v_mov_b32_e32 v3, 0x70
	v_cndmask_b32_e64 v98, v3, 33, s[10:11]
	v_mov_b32_e32 v3, 0x71
	v_cndmask_b32_e64 v99, v3, 34, s[10:11]
	v_mov_b32_e32 v3, 0x80
	v_cndmask_b32_e64 v100, v3, 35, s[10:11]
	v_mov_b32_e32 v3, 0x90
	v_cndmask_b32_e64 v101, v3, 36, s[10:11]
	v_mov_b32_e32 v3, 0xa0
	v_cndmask_b32_e64 v102, v3, 48, s[10:11]
	v_mov_b32_e32 v3, 0xb0
	v_cndmask_b32_e64 v103, v3, 49, s[10:11]
	v_mov_b32_e32 v3, 0xc0
	v_cndmask_b32_e64 v104, v3, 50, s[10:11]
	v_mov_b32_e32 v3, 0xd0
	v_cndmask_b32_e64 v105, v3, 51, s[10:11]
	v_mov_b32_e32 v3, 0xe0
	v_cndmask_b32_e64 v106, v3, v5, s[10:11]
	v_mov_b32_e32 v3, 0xf0
	v_mov_b32_e32 v5, 0x50
	v_cndmask_b32_e64 v107, v3, v5, s[10:11]
	v_mov_b32_e32 v3, 0x51
	v_cndmask_b32_e64 v108, 0, v3, s[10:11]
	v_mov_b32_e32 v3, 0x60
	v_cndmask_b32_e64 v109, 0, v3, s[10:11]
	v_lshlrev_b32_e32 v3, 11, v174
	v_add_u32_e32 v110, v3, v1
	v_and_b32_e32 v3, 64, v128
	v_or_b32_e32 v0, v171, v1
	v_xor_b32_e32 v1, 16, v128
	v_add_u32_e32 v3, 64, v3
	v_cmp_lt_i32_e32 vcc, v1, v3
	v_mov_b32_e32 v17, 0
	v_or_b32_e32 v2, 32, v0
	v_cndmask_b32_e32 v1, v128, v1, vcc
	v_lshlrev_b32_e32 v111, 2, v1
	v_xor_b32_e32 v1, 32, v128
	v_cmp_lt_i32_e32 vcc, v1, v3
	v_or_b32_e32 v4, 64, v0
	v_or_b32_e32 v6, 0x60, v0
	v_cndmask_b32_e32 v1, v128, v1, vcc
	v_or_b32_e32 v8, 0x800, v0
	v_or_b32_e32 v10, 0x820, v0
	v_or_b32_e32 v12, 0x840, v0
	v_or_b32_e32 v14, 0x860, v0
	v_or_b32_e32 v16, 0x1000, v0
	v_or_b32_e32 v32, 0x1020, v0
	v_or_b32_e32 v34, 0x1040, v0
	v_or_b32_e32 v36, 0x1060, v0
	v_or_b32_e32 v38, 0x1800, v0
	v_or_b32_e32 v40, 0x1820, v0
	v_or_b32_e32 v42, 0x1840, v0
	v_or_b32_e32 v44, 0x1860, v0
	v_or_b32_e32 v46, 0x2000, v0
	v_or_b32_e32 v48, 0x2020, v0
	v_or_b32_e32 v50, 0x2040, v0
	v_or_b32_e32 v52, 0x2060, v0
	v_or_b32_e32 v54, 0x2800, v0
	v_or_b32_e32 v56, 0x2820, v0
	v_or_b32_e32 v58, 0x2840, v0
	v_or_b32_e32 v60, 0x2860, v0
	v_or_b32_e32 v62, 0x3000, v0
	v_or_b32_e32 v64, 0x3020, v0
	v_or_b32_e32 v66, 0x3040, v0
	v_or_b32_e32 v68, 0x3060, v0
	v_or_b32_e32 v70, 0x3800, v0
	v_or_b32_e32 v72, 0x3820, v0
	v_or_b32_e32 v74, 0x3840, v0
	v_or_b32_e32 v76, 0x3860, v0
	v_lshlrev_b32_e32 v112, 2, v1
	v_lshlrev_b32_e32 v1, 1, v174
	v_or_b32_e32 v90, 16, v170
	v_or_b32_e32 v91, 32, v170
	v_or_b32_e32 v92, 48, v170
	v_or_b32_e32 v93, 64, v170
	v_or_b32_e32 v94, 0x50, v170
	v_or_b32_e32 v95, 0x60, v170
	v_or_b32_e32 v96, 0x70, v170
	v_cmp_gt_u32_e64 s[4:5], 2, v175
	v_cmp_eq_u32_e64 s[12:13], 3, v175
	v_or_b32_e32 v113, 1, v170
	v_or_b32_e32 v114, 2, v170
	v_or_b32_e32 v115, 3, v170
	v_or_b32_e32 v116, 17, v170
	v_or_b32_e32 v117, 18, v170
	v_or_b32_e32 v118, 19, v170
	v_or_b32_e32 v119, 33, v170
	v_or_b32_e32 v120, 34, v170
	v_or_b32_e32 v121, 35, v170
	v_or_b32_e32 v122, 49, v170
	v_or_b32_e32 v123, 50, v170
	v_or_b32_e32 v124, 51, v170
	v_or_b32_e32 v125, 0x41, v170
	v_or_b32_e32 v126, 0x42, v170
	v_or_b32_e32 v127, 0x43, v170
	v_or_b32_e32 v129, 0x51, v170
	v_or_b32_e32 v130, 0x52, v170
	v_or_b32_e32 v131, 0x53, v170
	v_or_b32_e32 v135, 0x61, v170
	v_or_b32_e32 v136, 0x62, v170
	v_or_b32_e32 v137, 0x63, v170
	v_or_b32_e32 v138, 0x71, v170
	v_or_b32_e32 v139, 0x72, v170
	v_or_b32_e32 v140, 0x73, v170
	s_lshr_b32 s89, s86, 3
	s_lshl_b32 s89, s89, 2
	v_add_u32_e32 v141, s89, v174
	v_lshlrev_b32_e32 v141, 3, v141
	s_and_b32 s89, s86, 7
	v_or_b32_e32 v141, s89, v141
	v_mov_b32_e32 v238, v141
	v_lshlrev_b32_e32 v141, 1, v141
	s_lshl_b32 s79, s84, 3
	s_mov_b64 s[74:75], 0
	s_mov_b32 s88, 0
	s_mov_b64 s[90:91], 0x1000000
	v_mov_b32_e32 v142, 0x10178
	v_lshlrev_b32_e32 v18, 1, v171
	v_mov_b32_e32 v19, v17
	v_mov_b32_e32 v143, 0x10110
	v_lshlrev_b32_e32 v20, 1, v0
	v_mov_b32_e32 v21, v17
	s_movk_i32 s80, 0xff80
	v_lshlrev_b32_e32 v22, 1, v8
	v_mov_b32_e32 v23, v17
	v_lshlrev_b32_e32 v24, 1, v10
	v_mov_b32_e32 v25, v17
	v_lshlrev_b32_e32 v26, 1, v12
	v_mov_b32_e32 v27, v17
	v_lshlrev_b32_e32 v28, 1, v14
	v_mov_b32_e32 v29, v17
	v_lshlrev_b32_e32 v30, 1, v16
	v_mov_b32_e32 v31, v17
	v_lshlrev_b32_e32 v32, 1, v32
	v_mov_b32_e32 v33, v17
	v_lshlrev_b32_e32 v34, 1, v34
	v_mov_b32_e32 v35, v17
	v_lshlrev_b32_e32 v36, 1, v36
	v_mov_b32_e32 v37, v17
	v_lshlrev_b32_e32 v38, 1, v38
	v_mov_b32_e32 v39, v17
	v_lshlrev_b32_e32 v40, 1, v40
	v_mov_b32_e32 v41, v17
	v_lshlrev_b32_e32 v42, 1, v42
	v_mov_b32_e32 v43, v17
	v_lshlrev_b32_e32 v44, 1, v44
	v_mov_b32_e32 v45, v17
	v_lshlrev_b32_e32 v46, 1, v46
	v_mov_b32_e32 v47, v17
	v_lshlrev_b32_e32 v48, 1, v48
	v_mov_b32_e32 v49, v17
	v_lshlrev_b32_e32 v50, 1, v50
	v_mov_b32_e32 v51, v17
	v_lshlrev_b32_e32 v52, 1, v52
	v_mov_b32_e32 v53, v17
	v_lshlrev_b32_e32 v54, 1, v54
	v_mov_b32_e32 v55, v17
	v_lshlrev_b32_e32 v56, 1, v56
	v_mov_b32_e32 v57, v17
	v_lshlrev_b32_e32 v58, 1, v58
	v_mov_b32_e32 v59, v17
	v_lshlrev_b32_e32 v60, 1, v60
	v_mov_b32_e32 v61, v17
	v_lshlrev_b32_e32 v62, 1, v62
	v_mov_b32_e32 v63, v17
	v_lshlrev_b32_e32 v64, 1, v64
	v_mov_b32_e32 v65, v17
	v_lshlrev_b32_e32 v66, 1, v66
	v_mov_b32_e32 v67, v17
	v_lshlrev_b32_e32 v68, 1, v68
	v_mov_b32_e32 v69, v17
	v_lshlrev_b32_e32 v70, 1, v70
	v_mov_b32_e32 v71, v17
	v_lshlrev_b32_e32 v72, 1, v72
	v_mov_b32_e32 v73, v17
	v_lshlrev_b32_e32 v74, 1, v74
	v_mov_b32_e32 v75, v17
	v_lshlrev_b32_e32 v76, 1, v76
	v_mov_b32_e32 v77, v17
	s_mov_b64 s[76:77], 0x8000
	v_lshlrev_b32_e32 v78, 1, v2
	v_mov_b32_e32 v79, v17
	v_lshlrev_b32_e32 v80, 1, v4
	v_mov_b32_e32 v81, v17
	v_lshlrev_b32_e32 v82, 1, v6
	v_mov_b32_e32 v83, v17
	s_movk_i32 s81, 0x7f
	s_movk_i32 s82, 0xff00
	s_movk_i32 s83, 0xff
	v_mov_b32_e32 v144, 0x101b0
	s_movk_i32 s86, 0x403f
	v_mov_b32_e32 v145, v238
	v_lshl_add_u32 v239, v174, 6, v128
	v_lshrrev_b32_e32 v240, 4, v239
	v_lshlrev_b32_e32 v239, 4, v239
	v_lshl_add_u32 v240, v240, 4, v239
	v_add_u32_e32 v240, 0x2000, v240
	v_and_b32_e32 v241, 15, v128
	v_mul_u32_u24_e32 v241, 0x110, v241
	v_lshrrev_b32_e32 v242, 4, v128
	v_lshl_add_u32 v241, v242, 4, v241
	v_add_u32_e32 v241, 0x2000, v241
	v_mov_b32_e32 v242, 0x10110
	ds_read_b64 v[242:243], v242
	s_lshl_b32 s92, s89, 16
	s_waitcnt lgkmcnt(0)
; DI void peer_topk_wave(const Params& p, int item, unsigned* lds  ) {
;     ...
;     const u16* sk = p.subkb + (size_t)(h * 2 + pp) * 16384;
; #pragma unroll
;     for (int mt = 0; mt < 8; ++mt) {
;       f32x4 a = (f32x4){0.f, 0.f, 0.f, 0.f};
; #pragma unroll
;       for (int ks = 0; ks < 4; ++ks) {
;         bf16x8 kf = *(const bf16x8*)&sk[(mt * 16 + r) * 128 + ks * 32 + kg * 8];
	v_readfirstlane_b32 s96, v242
	v_readfirstlane_b32 s97, v243
	s_nop 3
	s_add_u32 s96, s96, s92
	s_addc_u32 s97, s97, 0
	s_add_u32 s92, s96, 0x0
	s_addc_u32 s93, s97, 0
	global_load_dwordx4 v[24:27], v239, s[92:93]
	s_add_u32 s92, s96, 0x1000
	s_addc_u32 s93, s97, 0
	global_load_dwordx4 v[28:31], v239, s[92:93]
	s_add_u32 s92, s96, 0x2000
	s_addc_u32 s93, s97, 0
	global_load_dwordx4 v[32:35], v239, s[92:93]
	s_add_u32 s92, s96, 0x3000
	s_addc_u32 s93, s97, 0
	global_load_dwordx4 v[36:39], v239, s[92:93]
	s_add_u32 s92, s96, 0x4000
	s_addc_u32 s93, s97, 0
	global_load_dwordx4 v[40:43], v239, s[92:93]
	s_add_u32 s92, s96, 0x5000
	s_addc_u32 s93, s97, 0
	global_load_dwordx4 v[44:47], v239, s[92:93]
	s_add_u32 s92, s96, 0x6000
	s_addc_u32 s93, s97, 0
	global_load_dwordx4 v[48:51], v239, s[92:93]
	s_add_u32 s92, s96, 0x7000
	s_addc_u32 s93, s97, 0
	global_load_dwordx4 v[52:55], v239, s[92:93]
	s_add_u32 s92, s96, 0x8000
	s_addc_u32 s93, s97, 0
	global_load_dwordx4 v[56:59], v239, s[92:93]
	s_add_u32 s92, s96, 0x9000
	s_addc_u32 s93, s97, 0
	global_load_dwordx4 v[60:63], v239, s[92:93]
	s_add_u32 s92, s96, 0xa000
	s_addc_u32 s93, s97, 0
	global_load_dwordx4 v[64:67], v239, s[92:93]
	s_add_u32 s92, s96, 0xb000
	s_addc_u32 s93, s97, 0
	global_load_dwordx4 v[68:71], v239, s[92:93]
	s_add_u32 s92, s96, 0xc000
	s_addc_u32 s93, s97, 0
	global_load_dwordx4 v[72:75], v239, s[92:93]
	s_waitcnt vmcnt(0)
	ds_write_b128 v240, v[24:27] offset:0
	ds_write_b128 v240, v[28:31] offset:4352
	ds_write_b128 v240, v[32:35] offset:8704
	ds_write_b128 v240, v[36:39] offset:13056
	ds_write_b128 v240, v[40:43] offset:17408
	ds_write_b128 v240, v[44:47] offset:21760
	ds_write_b128 v240, v[48:51] offset:26112
	ds_write_b128 v240, v[52:55] offset:30464
	ds_write_b128 v240, v[56:59] offset:34816
	ds_write_b128 v240, v[60:63] offset:39168
	ds_write_b128 v240, v[64:67] offset:43520
	ds_write_b128 v240, v[68:71] offset:47872
	ds_write_b128 v240, v[72:75] offset:52224
	s_waitcnt lgkmcnt(0)
	s_barrier
	s_branch .LBB0_1091

; DI void peer_topk_wave(const Params& p, int item, unsigned* lds  ) {
;     ...
;     bf16x8 qf[4];
; #pragma unroll
;     for (int ks = 0; ks < 4; ++ks) qf[ks] = *(const bf16x8*)&p.pq[(size_t)(row0 + r) * 2048 + h * 256 + pp * 128 + ks * 32 + kg * 8];
.LBB0_1091:
	ds_read_b64 v[0:1], v142
	ds_read_b64 v[86:87], v143
	v_and_or_b32 v84, v141, -16, v134
	v_ashrrev_i32_e32 v85, 31, v84
	v_and_b32_e32 v146, 7, v145
	v_lshlrev_b64 v[2:3], 12, v[84:85]
	s_waitcnt lgkmcnt(0)
	v_lshl_add_u64 v[0:1], v[0:1], 0, v[2:3]
	v_lshlrev_b32_e32 v16, 9, v146
	v_lshl_add_u64 v[0:1], v[0:1], 0, v[16:17]
	v_lshlrev_b32_e32 v16, 16, v146
	v_lshl_add_u64 v[86:87], v[86:87], 0, v[16:17]
	v_lshl_add_u64 v[88:89], v[0:1], 0, v[18:19]
	v_lshl_add_u64 v[156:157], v[86:87], 0, v[20:21]
	s_cmp_lg_u32 s88, 0
	s_cbranch_scc1 .Lp10q_mov0
	global_load_dwordx4 v[12:15], v[88:89], off
	global_load_dwordx4 v[8:11], v[88:89], off offset:64
	global_load_dwordx4 v[4:7], v[88:89], off offset:128
	global_load_dwordx4 v[0:3], v[88:89], off offset:192
	s_branch .Lp10q_done0

; #define MFMA(a, b, c) __builtin_amdgcn_mfma_f32_16x16x32_bf16((a), (b), (c), 0, 0, 0)
; DI unsigned ordf(float f) { unsigned u = __float_as_uint(f); return (u & 0x80000000u) ? ~u : (u | 0x80000000u); }
; DI void peer_topk_wave(const Params& p, int item, unsigned* lds  ) {
;     ...
; #pragma unroll
;     for (int mt = 0; mt < 8; ++mt) {
;       f32x4 a = (f32x4){0.f, 0.f, 0.f, 0.f};
; #pragma unroll
;       for (int ks = 0; ks < 4; ++ks) {
;         bf16x8 kf = *(const bf16x8*)&sk[(mt * 16 + r) * 128 + ks * 32 + kg * 8];
;         a = MFMA(kf, qf[ks], a);
;       }
; #pragma unroll
;       for (int j = 0; j < 4; ++j) kk[mt * 4 + j] = (ordf(a[j]) & ~127u) | (unsigned)(mt * 16 + kg * 4 + j);
;     }
.Lp10q_done0:
	v_readfirstlane_b32 s0, v86
	v_readfirstlane_b32 s1, v87
	s_nop 3
	s_add_u32 s2, s0, 0x0
	s_addc_u32 s3, s1, 0
	ds_read_b128 v[24:27], v241 offset:0
	ds_read_b128 v[28:31], v241 offset:64
	ds_read_b128 v[32:35], v241 offset:128
	ds_read_b128 v[36:39], v241 offset:192
	s_add_u32 s2, s0, 0x1000
	s_addc_u32 s3, s1, 0
	ds_read_b128 v[40:43], v241 offset:4352
	ds_read_b128 v[44:47], v241 offset:4416
	ds_read_b128 v[48:51], v241 offset:4480
	ds_read_b128 v[52:55], v241 offset:4544
	s_add_u32 s2, s0, 0x2000
	s_addc_u32 s3, s1, 0
	ds_read_b128 v[56:59], v241 offset:8704
	ds_read_b128 v[60:63], v241 offset:8768
	ds_read_b128 v[64:67], v241 offset:8832
	ds_read_b128 v[68:71], v241 offset:8896
	s_add_u32 s2, s0, 0x3000
	s_addc_u32 s3, s1, 0
	ds_read_b128 v[72:75], v241 offset:13056
	ds_read_b128 v[76:79], v241 offset:13120
	ds_read_b128 v[80:83], v241 offset:13184
	s_waitcnt vmcnt(0) lgkmcnt(11)
	v_mfma_f32_16x16x32_bf16 v[190:193], v[24:27], v[12:15], 0
	v_mfma_f32_16x16x32_bf16 v[190:193], v[28:31], v[8:11], v[190:193]
	v_mfma_f32_16x16x32_bf16 v[190:193], v[32:35], v[4:7], v[190:193]
	v_mfma_f32_16x16x32_bf16 v[190:193], v[36:39], v[0:3], v[190:193]
	ds_read_b128 v[24:27], v241 offset:13248
	s_add_u32 s2, s0, 0x4000
	s_addc_u32 s3, s1, 0
	ds_read_b128 v[28:31], v241 offset:17408
	ds_read_b128 v[32:35], v241 offset:17472
	ds_read_b128 v[36:39], v241 offset:17536
	s_waitcnt lgkmcnt(11)
	v_mfma_f32_16x16x32_bf16 v[198:201], v[40:43], v[12:15], 0
	v_mfma_f32_16x16x32_bf16 v[198:201], v[44:47], v[8:11], v[198:201]
	v_mfma_f32_16x16x32_bf16 v[198:201], v[48:51], v[4:7], v[198:201]
	v_mfma_f32_16x16x32_bf16 v[198:201], v[52:55], v[0:3], v[198:201]
	ds_read_b128 v[40:43], v241 offset:17600
	s_add_u32 s2, s0, 0x5000
	s_addc_u32 s3, s1, 0
	ds_read_b128 v[44:47], v241 offset:21760
	ds_read_b128 v[48:51], v241 offset:21824
	ds_read_b128 v[52:55], v241 offset:21888
	s_nop 7
	s_nop 3
	v_ashrrev_i32_e32 v197, 31, v190
	v_or_b32_e32 v197, 0x80000000, v197
	v_xor_b32_e32 v197, v190, v197
	v_and_or_b32 v147, v197, s80, v170
	v_ashrrev_i32_e32 v202, 31, v191
	v_or_b32_e32 v202, 0x80000000, v202
	v_xor_b32_e32 v202, v191, v202
	v_and_or_b32 v148, v202, s80, v113
	v_ashrrev_i32_e32 v197, 31, v192
	v_or_b32_e32 v197, 0x80000000, v197
	v_xor_b32_e32 v197, v192, v197
	v_and_or_b32 v149, v197, s80, v114
	v_ashrrev_i32_e32 v202, 31, v193
	v_or_b32_e32 v202, 0x80000000, v202
	v_xor_b32_e32 v202, v193, v202
	v_and_or_b32 v150, v202, s80, v115
	s_waitcnt lgkmcnt(11)
	v_mfma_f32_16x16x32_bf16 v[190:193], v[56:59], v[12:15], 0
	v_mfma_f32_16x16x32_bf16 v[190:193], v[60:63], v[8:11], v[190:193]
	v_mfma_f32_16x16x32_bf16 v[190:193], v[64:67], v[4:7], v[190:193]
	v_mfma_f32_16x16x32_bf16 v[190:193], v[68:71], v[0:3], v[190:193]
	ds_read_b128 v[56:59], v241 offset:21952
	s_add_u32 s2, s0, 0x6000
	s_addc_u32 s3, s1, 0
	ds_read_b128 v[60:63], v241 offset:26112
	ds_read_b128 v[64:67], v241 offset:26176
	ds_read_b128 v[68:71], v241 offset:26240
	s_nop 7
	s_nop 3
	v_ashrrev_i32_e32 v197, 31, v198
	v_or_b32_e32 v197, 0x80000000, v197
	v_xor_b32_e32 v197, v198, v197
	v_and_or_b32 v151, v197, s80, v90
	v_ashrrev_i32_e32 v202, 31, v199
	v_or_b32_e32 v202, 0x80000000, v202
	v_xor_b32_e32 v202, v199, v202
	v_and_or_b32 v152, v202, s80, v116
	v_ashrrev_i32_e32 v197, 31, v200
	v_or_b32_e32 v197, 0x80000000, v197
	v_xor_b32_e32 v197, v200, v197
	v_and_or_b32 v153, v197, s80, v117
	v_ashrrev_i32_e32 v202, 31, v201
	v_or_b32_e32 v202, 0x80000000, v202
	v_xor_b32_e32 v202, v201, v202
	v_and_or_b32 v154, v202, s80, v118
	s_waitcnt lgkmcnt(11)
	v_mfma_f32_16x16x32_bf16 v[198:201], v[72:75], v[12:15], 0
	v_mfma_f32_16x16x32_bf16 v[198:201], v[76:79], v[8:11], v[198:201]
	v_mfma_f32_16x16x32_bf16 v[198:201], v[80:83], v[4:7], v[198:201]
	v_mfma_f32_16x16x32_bf16 v[198:201], v[24:27], v[0:3], v[198:201]
	ds_read_b128 v[72:75], v241 offset:26304
	s_add_u32 s2, s0, 0x7000
	s_addc_u32 s3, s1, 0
	ds_read_b128 v[76:79], v241 offset:30464
	ds_read_b128 v[80:83], v241 offset:30528
	ds_read_b128 v[24:27], v241 offset:30592
	s_nop 7
	s_nop 3
	v_ashrrev_i32_e32 v197, 31, v190
	v_or_b32_e32 v197, 0x80000000, v197
	v_xor_b32_e32 v197, v190, v197
	v_and_or_b32 v155, v197, s80, v91
	v_ashrrev_i32_e32 v202, 31, v191
	v_or_b32_e32 v202, 0x80000000, v202
	v_xor_b32_e32 v202, v191, v202
	v_and_or_b32 v156, v202, s80, v119
	v_ashrrev_i32_e32 v197, 31, v192
	v_or_b32_e32 v197, 0x80000000, v197
	v_xor_b32_e32 v197, v192, v197
	v_and_or_b32 v157, v197, s80, v120
	v_ashrrev_i32_e32 v202, 31, v193
	v_or_b32_e32 v202, 0x80000000, v202
	v_xor_b32_e32 v202, v193, v202
	v_and_or_b32 v158, v202, s80, v121
	s_waitcnt lgkmcnt(11)
	v_mfma_f32_16x16x32_bf16 v[190:193], v[28:31], v[12:15], 0
	v_mfma_f32_16x16x32_bf16 v[190:193], v[32:35], v[8:11], v[190:193]
	v_mfma_f32_16x16x32_bf16 v[190:193], v[36:39], v[4:7], v[190:193]
	v_mfma_f32_16x16x32_bf16 v[190:193], v[40:43], v[0:3], v[190:193]
	ds_read_b128 v[28:31], v241 offset:30656
	s_nop 7
	s_nop 3
	v_ashrrev_i32_e32 v197, 31, v198
	v_or_b32_e32 v197, 0x80000000, v197
	v_xor_b32_e32 v197, v198, v197
	v_and_or_b32 v159, v197, s80, v92
	v_ashrrev_i32_e32 v202, 31, v199
	v_or_b32_e32 v202, 0x80000000, v202
	v_xor_b32_e32 v202, v199, v202
	v_and_or_b32 v160, v202, s80, v122
	v_ashrrev_i32_e32 v197, 31, v200
	v_or_b32_e32 v197, 0x80000000, v197
	v_xor_b32_e32 v197, v200, v197
	v_and_or_b32 v161, v197, s80, v123
	v_ashrrev_i32_e32 v202, 31, v201
	v_or_b32_e32 v202, 0x80000000, v202
	v_xor_b32_e32 v202, v201, v202
	v_and_or_b32 v162, v202, s80, v124
	s_waitcnt lgkmcnt(8)
; #define MFMA(a, b, c) __builtin_amdgcn_mfma_f32_16x16x32_bf16((a), (b), (c), 0, 0, 0)
; DI unsigned ordf(float f) { unsigned u = __float_as_uint(f); return (u & 0x80000000u) ? ~u : (u | 0x80000000u); }
; DI void peer_topk_wave(const Params& p, int item, unsigned* lds  ) {
;     ...
; #pragma unroll
;     for (int mt = 0; mt < 8; ++mt) {
;       f32x4 a = (f32x4){0.f, 0.f, 0.f, 0.f};
; #pragma unroll
;       for (int ks = 0; ks < 4; ++ks) {
;         bf16x8 kf = *(const bf16x8*)&sk[(mt * 16 + r) * 128 + ks * 32 + kg * 8];
;         a = MFMA(kf, qf[ks], a);
;       }
; #pragma unroll
;       for (int j = 0; j < 4; ++j) kk[mt * 4 + j] = (ordf(a[j]) & ~127u) | (unsigned)(mt * 16 + kg * 4 + j);
;     }
; #pragma unroll
;     for (int rr = 0; rr < 16; ++rr) {
;       unsigned m = 0;
; #pragma unroll
;       for (int i = 0; i < 32; ++i) m = umax(m, kk[i]);
;       m = umax(m, (unsigned)__shfl_xor((int)m, 16));
;       m = umax(m, (unsigned)__shfl_xor((int)m, 32));
;       win[pp][rr] = m;
; #pragma unroll
;       for (int i = 0; i < 32; ++i) kk[i] = (kk[i] == m) ? 0u : kk[i];
;     }
	v_mfma_f32_16x16x32_bf16 v[198:201], v[44:47], v[12:15], 0
	v_mfma_f32_16x16x32_bf16 v[198:201], v[48:51], v[8:11], v[198:201]
	v_mfma_f32_16x16x32_bf16 v[198:201], v[52:55], v[4:7], v[198:201]
	v_mfma_f32_16x16x32_bf16 v[198:201], v[56:59], v[0:3], v[198:201]
	s_nop 7
	s_nop 3
	v_ashrrev_i32_e32 v197, 31, v190
	v_or_b32_e32 v197, 0x80000000, v197
	v_xor_b32_e32 v197, v190, v197
	v_and_or_b32 v164, v197, s80, v93
	v_ashrrev_i32_e32 v202, 31, v191
	v_or_b32_e32 v202, 0x80000000, v202
	v_xor_b32_e32 v202, v191, v202
	v_and_or_b32 v165, v202, s80, v125
	v_ashrrev_i32_e32 v197, 31, v192
	v_or_b32_e32 v197, 0x80000000, v197
	v_xor_b32_e32 v197, v192, v197
	v_and_or_b32 v166, v197, s80, v126
	v_ashrrev_i32_e32 v202, 31, v193
	v_or_b32_e32 v202, 0x80000000, v202
	v_xor_b32_e32 v202, v193, v202
	v_and_or_b32 v167, v202, s80, v127
	s_waitcnt lgkmcnt(4)
	v_mfma_f32_16x16x32_bf16 v[190:193], v[60:63], v[12:15], 0
	v_mfma_f32_16x16x32_bf16 v[190:193], v[64:67], v[8:11], v[190:193]
	v_mfma_f32_16x16x32_bf16 v[190:193], v[68:71], v[4:7], v[190:193]
	v_mfma_f32_16x16x32_bf16 v[190:193], v[72:75], v[0:3], v[190:193]
	s_nop 7
	s_nop 3
	v_ashrrev_i32_e32 v197, 31, v198
	v_or_b32_e32 v197, 0x80000000, v197
	v_xor_b32_e32 v197, v198, v197
	v_and_or_b32 v168, v197, s80, v94
	v_ashrrev_i32_e32 v202, 31, v199
	v_or_b32_e32 v202, 0x80000000, v202
	v_xor_b32_e32 v202, v199, v202
	v_and_or_b32 v169, v202, s80, v129
	v_ashrrev_i32_e32 v197, 31, v200
	v_or_b32_e32 v197, 0x80000000, v197
	v_xor_b32_e32 v197, v200, v197
	v_and_or_b32 v171, v197, s80, v130
	v_ashrrev_i32_e32 v202, 31, v201
	v_or_b32_e32 v202, 0x80000000, v202
	v_xor_b32_e32 v202, v201, v202
	v_and_or_b32 v172, v202, s80, v131
	s_waitcnt lgkmcnt(0)
	v_mfma_f32_16x16x32_bf16 v[198:201], v[76:79], v[12:15], 0
	v_mfma_f32_16x16x32_bf16 v[198:201], v[80:83], v[8:11], v[198:201]
	v_mfma_f32_16x16x32_bf16 v[198:201], v[24:27], v[4:7], v[198:201]
	v_mfma_f32_16x16x32_bf16 v[198:201], v[28:31], v[0:3], v[198:201]
	s_nop 7
	s_nop 3
	v_ashrrev_i32_e32 v197, 31, v190
	v_or_b32_e32 v197, 0x80000000, v197
	v_xor_b32_e32 v197, v190, v197
	v_and_or_b32 v173, v197, s80, v95
	v_ashrrev_i32_e32 v202, 31, v191
	v_or_b32_e32 v202, 0x80000000, v202
	v_xor_b32_e32 v202, v191, v202
	v_and_or_b32 v180, v202, s80, v135
	v_ashrrev_i32_e32 v197, 31, v192
	v_or_b32_e32 v197, 0x80000000, v197
	v_xor_b32_e32 v197, v192, v197
	v_and_or_b32 v181, v197, s80, v136
	v_ashrrev_i32_e32 v202, 31, v193
	v_or_b32_e32 v202, 0x80000000, v202
	v_xor_b32_e32 v202, v193, v202
	v_and_or_b32 v182, v202, s80, v137
	s_nop 7
	s_nop 3
	v_ashrrev_i32_e32 v197, 31, v198
	v_or_b32_e32 v197, 0x80000000, v197
	v_xor_b32_e32 v197, v198, v197
	v_and_or_b32 v0, v197, s80, v96
	v_ashrrev_i32_e32 v202, 31, v199
	v_or_b32_e32 v202, 0x80000000, v202
	v_xor_b32_e32 v202, v199, v202
	v_and_or_b32 v1, v202, s80, v138
	v_ashrrev_i32_e32 v197, 31, v200
	v_or_b32_e32 v197, 0x80000000, v197
	v_xor_b32_e32 v197, v200, v197
	v_and_or_b32 v2, v197, s80, v139
	v_ashrrev_i32_e32 v202, 31, v201
	v_or_b32_e32 v202, 0x80000000, v202
	v_xor_b32_e32 v202, v201, v202
	v_and_or_b32 v3, v202, s80, v140
	v_max_u32_e32 v4, v147, v148
	v_max3_u32 v4, v4, v149, v150
	v_max3_u32 v4, v4, v151, v152
	v_max3_u32 v4, v4, v153, v154
	v_max3_u32 v4, v4, v155, v156
	v_max3_u32 v4, v4, v157, v158
	v_max3_u32 v4, v4, v159, v160
	v_max3_u32 v4, v4, v161, v162
	v_max3_u32 v4, v4, v164, v165
	v_max3_u32 v4, v4, v166, v167
	v_max3_u32 v4, v4, v168, v169
	v_max3_u32 v4, v4, v171, v172
	v_max3_u32 v4, v4, v173, v180
	v_max3_u32 v4, v4, v181, v182
	v_and_or_b32 v3, v3, s80, v140
	v_max3_u32 v4, v4, v0, v1
	v_max3_u32 v4, v4, v2, v3
	v_mov_b32_e32 v5, v4
	s_nop 1
	v_permlane16_swap_b32 v4, v5
	s_nop 1
	s_waitcnt lgkmcnt(0)
	v_max_u32_e32 v4, v4, v5
	v_mov_b32_e32 v5, v4
	s_nop 1
	v_permlane32_swap_b32 v4, v5
	s_nop 1
	s_waitcnt lgkmcnt(0)
	v_max_u32_e32 v16, v4, v5
	v_cmp_ne_u32_e32 vcc, v147, v16
	v_cmp_ne_u32_e64 s[98:99], v148, v16
	v_cmp_ne_u32_e64 s[100:101], v149, v16
	v_cndmask_b32_e32 v4, 0, v147, vcc
	v_cndmask_b32_e64 v5, 0, v148, s[98:99]
	v_max_u32_e32 v147, v4, v5
	v_cndmask_b32_e64 v6, 0, v149, s[100:101]
	v_cmp_ne_u32_e32 vcc, v150, v16
	v_cmp_ne_u32_e64 s[98:99], v151, v16
	v_cmp_ne_u32_e64 s[100:101], v152, v16
	v_cndmask_b32_e32 v7, 0, v150, vcc
	v_max3_u32 v147, v147, v6, v7
	v_cndmask_b32_e64 v8, 0, v151, s[98:99]
	v_cndmask_b32_e64 v9, 0, v152, s[100:101]
	v_cmp_ne_u32_e32 vcc, v153, v16
	v_max3_u32 v147, v147, v8, v9
	v_cmp_ne_u32_e64 s[98:99], v154, v16
	v_cndmask_b32_e32 v10, 0, v153, vcc
	v_cmp_ne_u32_e64 s[100:101], v155, v16
	v_cndmask_b32_e64 v11, 0, v154, s[98:99]
	v_max3_u32 v147, v147, v10, v11
	v_cndmask_b32_e64 v12, 0, v155, s[100:101]
	v_cmp_ne_u32_e32 vcc, v156, v16
	v_cmp_ne_u32_e64 s[98:99], v157, v16
	v_cmp_ne_u32_e64 s[100:101], v158, v16
	v_cndmask_b32_e32 v13, 0, v156, vcc
	v_max3_u32 v147, v147, v12, v13
	v_cndmask_b32_e64 v14, 0, v157, s[98:99]
	v_cndmask_b32_e64 v15, 0, v158, s[100:101]
	v_cmp_ne_u32_e32 vcc, v159, v16
	v_max3_u32 v147, v147, v14, v15
	v_cmp_ne_u32_e64 s[98:99], v160, v16
	v_cndmask_b32_e32 v148, 0, v159, vcc
	v_cmp_ne_u32_e64 s[100:101], v161, v16
	v_cndmask_b32_e64 v149, 0, v160, s[98:99]
	v_max3_u32 v147, v147, v148, v149
	v_cndmask_b32_e64 v150, 0, v161, s[100:101]
	v_cmp_ne_u32_e32 vcc, v162, v16
	v_cmp_ne_u32_e64 s[98:99], v164, v16
	v_cmp_ne_u32_e64 s[100:101], v165, v16
	v_cndmask_b32_e32 v151, 0, v162, vcc
	v_max3_u32 v147, v147, v150, v151
	v_cndmask_b32_e64 v152, 0, v164, s[98:99]
	v_cndmask_b32_e64 v153, 0, v165, s[100:101]
	v_cmp_ne_u32_e32 vcc, v166, v16
	v_max3_u32 v147, v147, v152, v153
	v_cmp_ne_u32_e64 s[98:99], v167, v16
	v_cndmask_b32_e32 v154, 0, v166, vcc
	v_cmp_ne_u32_e64 s[100:101], v168, v16
	v_cndmask_b32_e64 v155, 0, v167, s[98:99]
	v_max3_u32 v147, v147, v154, v155
	v_cndmask_b32_e64 v156, 0, v168, s[100:101]
	v_cmp_ne_u32_e32 vcc, v169, v16
	v_cmp_ne_u32_e64 s[98:99], v171, v16
	v_cmp_ne_u32_e64 s[100:101], v172, v16
	v_cndmask_b32_e32 v157, 0, v169, vcc
	v_max3_u32 v147, v147, v156, v157
	v_cndmask_b32_e64 v158, 0, v171, s[98:99]
	v_cndmask_b32_e64 v159, 0, v172, s[100:101]
	v_cmp_ne_u32_e32 vcc, v173, v16
	v_max3_u32 v147, v147, v158, v159
	v_cmp_ne_u32_e64 s[98:99], v180, v16
	v_cndmask_b32_e32 v160, 0, v173, vcc
	v_cmp_ne_u32_e64 s[100:101], v181, v16
	v_cndmask_b32_e64 v161, 0, v180, s[98:99]
	v_max3_u32 v147, v147, v160, v161
	v_cndmask_b32_e64 v162, 0, v181, s[100:101]
	v_cmp_ne_u32_e32 vcc, v182, v16
	v_cmp_ne_u32_e64 s[98:99], v0, v16
	v_cmp_ne_u32_e64 s[100:101], v1, v16
	v_cndmask_b32_e32 v164, 0, v182, vcc
	v_max3_u32 v147, v147, v162, v164
	v_cndmask_b32_e64 v0, 0, v0, s[98:99]
	v_cndmask_b32_e64 v1, 0, v1, s[100:101]
	v_cmp_ne_u32_e32 vcc, v2, v16
	v_max3_u32 v147, v147, v0, v1
	v_cmp_ne_u32_e64 s[98:99], v3, v16
	v_cndmask_b32_e32 v2, 0, v2, vcc
	s_nop 0
	v_cndmask_b32_e64 v3, 0, v3, s[98:99]
	v_max3_u32 v147, v147, v2, v3
	v_mov_b32_e32 v165, v147
	s_nop 1
	v_permlane16_swap_b32 v147, v165
	s_nop 1
	s_waitcnt lgkmcnt(0)
; DI void peer_topk_wave(const Params& p, int item, unsigned* lds  ) {
;     ...
; #pragma unroll
;     for (int rr = 0; rr < 16; ++rr) {
;       unsigned m = 0;
; #pragma unroll
;       for (int i = 0; i < 32; ++i) m = umax(m, kk[i]);
;       m = umax(m, (unsigned)__shfl_xor((int)m, 16));
;       m = umax(m, (unsigned)__shfl_xor((int)m, 32));
;       win[pp][rr] = m;
; #pragma unroll
;       for (int i = 0; i < 32; ++i) kk[i] = (kk[i] == m) ? 0u : kk[i];
;     }
	v_max_u32_e32 v147, v147, v165
	v_mov_b32_e32 v165, v147
	s_nop 1
	v_permlane32_swap_b32 v147, v165
	s_nop 1
	s_waitcnt lgkmcnt(0)
	v_max_u32_e32 v147, v147, v165
	v_cmp_ne_u32_e32 vcc, v4, v147
	v_cmp_ne_u32_e64 s[98:99], v5, v147
	v_cmp_ne_u32_e64 s[100:101], v6, v147
	v_cndmask_b32_e32 v4, 0, v4, vcc
	v_cndmask_b32_e64 v5, 0, v5, s[98:99]
	v_cndmask_b32_e64 v6, 0, v6, s[100:101]
	v_cmp_ne_u32_e32 vcc, v7, v147
	v_cmp_ne_u32_e64 s[98:99], v8, v147
	v_cmp_ne_u32_e64 s[100:101], v9, v147
	v_cndmask_b32_e32 v7, 0, v7, vcc
	v_cndmask_b32_e64 v8, 0, v8, s[98:99]
	v_cndmask_b32_e64 v9, 0, v9, s[100:101]
	v_cmp_ne_u32_e32 vcc, v10, v147
	v_cmp_ne_u32_e64 s[98:99], v11, v147
	v_cmp_ne_u32_e64 s[100:101], v12, v147
	v_cndmask_b32_e32 v10, 0, v10, vcc
	v_cndmask_b32_e64 v11, 0, v11, s[98:99]
	v_cndmask_b32_e64 v12, 0, v12, s[100:101]
	v_cmp_ne_u32_e32 vcc, v13, v147
	v_cmp_ne_u32_e64 s[98:99], v14, v147
	v_cmp_ne_u32_e64 s[100:101], v15, v147
	v_cndmask_b32_e32 v13, 0, v13, vcc
	v_cndmask_b32_e64 v14, 0, v14, s[98:99]
	v_cndmask_b32_e64 v15, 0, v15, s[100:101]
	v_cmp_ne_u32_e32 vcc, v148, v147
	v_cmp_ne_u32_e64 s[98:99], v149, v147
	v_cmp_ne_u32_e64 s[100:101], v150, v147
	v_cndmask_b32_e32 v165, 0, v148, vcc
	v_max_u32_e32 v148, v4, v5
	v_max3_u32 v148, v148, v6, v7
	v_cndmask_b32_e64 v149, 0, v149, s[98:99]
	v_max3_u32 v148, v148, v8, v9
	v_max3_u32 v148, v148, v10, v11
	v_cndmask_b32_e64 v150, 0, v150, s[100:101]
	v_cmp_ne_u32_e32 vcc, v151, v147
	v_max3_u32 v148, v148, v12, v13
	v_max3_u32 v148, v148, v14, v15
	v_cndmask_b32_e32 v151, 0, v151, vcc
	v_cmp_ne_u32_e64 s[98:99], v152, v147
	v_max3_u32 v148, v148, v165, v149
	v_max3_u32 v148, v148, v150, v151
	v_cndmask_b32_e64 v152, 0, v152, s[98:99]
	v_cmp_ne_u32_e64 s[100:101], v153, v147
	v_cmp_ne_u32_e32 vcc, v154, v147
	v_cmp_ne_u32_e64 s[98:99], v155, v147
	v_cndmask_b32_e64 v153, 0, v153, s[100:101]
	v_max3_u32 v148, v148, v152, v153
	v_cndmask_b32_e32 v154, 0, v154, vcc
	v_cndmask_b32_e64 v155, 0, v155, s[98:99]
	v_cmp_ne_u32_e64 s[100:101], v156, v147
	v_max3_u32 v148, v148, v154, v155
	v_cmp_ne_u32_e32 vcc, v157, v147
	v_cndmask_b32_e64 v156, 0, v156, s[100:101]
	v_cmp_ne_u32_e64 s[98:99], v158, v147
	v_cndmask_b32_e32 v157, 0, v157, vcc
	v_max3_u32 v148, v148, v156, v157
	v_cndmask_b32_e64 v158, 0, v158, s[98:99]
	v_cmp_ne_u32_e64 s[100:101], v159, v147
	v_cmp_ne_u32_e32 vcc, v160, v147
	v_cmp_ne_u32_e64 s[98:99], v161, v147
	v_cndmask_b32_e64 v159, 0, v159, s[100:101]
	v_max3_u32 v148, v148, v158, v159
	v_cndmask_b32_e32 v160, 0, v160, vcc
	v_cndmask_b32_e64 v161, 0, v161, s[98:99]
	v_cmp_ne_u32_e64 s[100:101], v162, v147
	v_max3_u32 v148, v148, v160, v161
	v_cmp_ne_u32_e32 vcc, v164, v147
	v_cndmask_b32_e64 v162, 0, v162, s[100:101]
	v_cmp_ne_u32_e64 s[98:99], v0, v147
	v_cndmask_b32_e32 v164, 0, v164, vcc
	v_max3_u32 v148, v148, v162, v164
	v_cndmask_b32_e64 v0, 0, v0, s[98:99]
	v_cmp_ne_u32_e64 s[100:101], v1, v147
	v_cmp_ne_u32_e32 vcc, v2, v147
	v_cmp_ne_u32_e64 s[98:99], v3, v147
	v_cndmask_b32_e64 v1, 0, v1, s[100:101]
	v_max3_u32 v148, v148, v0, v1
	v_cndmask_b32_e32 v2, 0, v2, vcc
	v_cndmask_b32_e64 v3, 0, v3, s[98:99]
	v_max3_u32 v148, v148, v2, v3
	v_mov_b32_e32 v166, v148
	s_nop 1
	v_permlane16_swap_b32 v148, v166
	s_nop 1
	s_waitcnt lgkmcnt(0)
	v_max_u32_e32 v148, v148, v166
	v_mov_b32_e32 v166, v148
	s_nop 1
	v_permlane32_swap_b32 v148, v166
	s_nop 1
	s_waitcnt lgkmcnt(0)
	v_max_u32_e32 v148, v148, v166
	v_cmp_ne_u32_e32 vcc, v4, v148
	v_cmp_ne_u32_e64 s[98:99], v5, v148
	v_cmp_ne_u32_e64 s[100:101], v6, v148
	v_cndmask_b32_e32 v4, 0, v4, vcc
	v_cndmask_b32_e64 v5, 0, v5, s[98:99]
	v_cndmask_b32_e64 v6, 0, v6, s[100:101]
	v_cmp_ne_u32_e32 vcc, v7, v148
	v_cmp_ne_u32_e64 s[98:99], v8, v148
	v_cmp_ne_u32_e64 s[100:101], v9, v148
	v_cndmask_b32_e32 v7, 0, v7, vcc
	v_cndmask_b32_e64 v8, 0, v8, s[98:99]
	v_cndmask_b32_e64 v9, 0, v9, s[100:101]
	v_cmp_ne_u32_e32 vcc, v10, v148
	v_cmp_ne_u32_e64 s[98:99], v11, v148
	v_cmp_ne_u32_e64 s[100:101], v12, v148
	v_cndmask_b32_e32 v10, 0, v10, vcc
	v_cndmask_b32_e64 v11, 0, v11, s[98:99]
	v_cndmask_b32_e64 v12, 0, v12, s[100:101]
	v_cmp_ne_u32_e32 vcc, v13, v148
	v_cmp_ne_u32_e64 s[98:99], v14, v148
	v_cmp_ne_u32_e64 s[100:101], v15, v148
	v_cndmask_b32_e32 v13, 0, v13, vcc
	v_cndmask_b32_e64 v14, 0, v14, s[98:99]
	v_cndmask_b32_e64 v15, 0, v15, s[100:101]
	v_cmp_ne_u32_e32 vcc, v165, v148
	v_cmp_ne_u32_e64 s[98:99], v149, v148
	v_cmp_ne_u32_e64 s[100:101], v150, v148
	v_cndmask_b32_e32 v165, 0, v165, vcc
	v_cndmask_b32_e64 v166, 0, v149, s[98:99]
	v_max_u32_e32 v149, v4, v5
	v_max3_u32 v149, v149, v6, v7
	v_cndmask_b32_e64 v150, 0, v150, s[100:101]
	v_cmp_ne_u32_e32 vcc, v151, v148
	v_max3_u32 v149, v149, v8, v9
	v_max3_u32 v149, v149, v10, v11
	v_cndmask_b32_e32 v151, 0, v151, vcc
	v_cmp_ne_u32_e64 s[98:99], v152, v148
	v_max3_u32 v149, v149, v12, v13
	v_max3_u32 v149, v149, v14, v15
	v_cndmask_b32_e64 v152, 0, v152, s[98:99]
	v_cmp_ne_u32_e64 s[100:101], v153, v148
	v_max3_u32 v149, v149, v165, v166
	v_max3_u32 v149, v149, v150, v151
	v_cndmask_b32_e64 v153, 0, v153, s[100:101]
	v_cmp_ne_u32_e32 vcc, v154, v148
	v_max3_u32 v149, v149, v152, v153
	v_cmp_ne_u32_e64 s[98:99], v155, v148
	v_cndmask_b32_e32 v154, 0, v154, vcc
	v_cmp_ne_u32_e64 s[100:101], v156, v148
	v_cndmask_b32_e64 v155, 0, v155, s[98:99]
	v_max3_u32 v149, v149, v154, v155
	v_cndmask_b32_e64 v156, 0, v156, s[100:101]
	v_cmp_ne_u32_e32 vcc, v157, v148
	v_cmp_ne_u32_e64 s[98:99], v158, v148
	v_cmp_ne_u32_e64 s[100:101], v159, v148
	v_cndmask_b32_e32 v157, 0, v157, vcc
	v_max3_u32 v149, v149, v156, v157
	v_cndmask_b32_e64 v158, 0, v158, s[98:99]
	v_cndmask_b32_e64 v159, 0, v159, s[100:101]
	v_cmp_ne_u32_e32 vcc, v160, v148
	v_max3_u32 v149, v149, v158, v159
	v_cmp_ne_u32_e64 s[98:99], v161, v148
	v_cndmask_b32_e32 v160, 0, v160, vcc
	v_cmp_ne_u32_e64 s[100:101], v162, v148
	v_cndmask_b32_e64 v161, 0, v161, s[98:99]
	v_max3_u32 v149, v149, v160, v161
	v_cndmask_b32_e64 v162, 0, v162, s[100:101]
	v_cmp_ne_u32_e32 vcc, v164, v148
	v_cmp_ne_u32_e64 s[98:99], v0, v148
	v_cmp_ne_u32_e64 s[100:101], v1, v148
	v_cndmask_b32_e32 v164, 0, v164, vcc
	v_max3_u32 v149, v149, v162, v164
	v_cndmask_b32_e64 v0, 0, v0, s[98:99]
	v_cndmask_b32_e64 v1, 0, v1, s[100:101]
	v_cmp_ne_u32_e32 vcc, v2, v148
	v_max3_u32 v149, v149, v0, v1
	v_cmp_ne_u32_e64 s[98:99], v3, v148
	v_cndmask_b32_e32 v2, 0, v2, vcc
	s_nop 0
	v_cndmask_b32_e64 v3, 0, v3, s[98:99]
	v_max3_u32 v149, v149, v2, v3
	v_mov_b32_e32 v167, v149
	s_nop 1
	v_permlane16_swap_b32 v149, v167
	s_nop 1
	s_waitcnt lgkmcnt(0)
; DI void peer_topk_wave(const Params& p, int item, unsigned* lds  ) {
;     ...
; #pragma unroll
;     for (int rr = 0; rr < 16; ++rr) {
;       unsigned m = 0;
; #pragma unroll
;       for (int i = 0; i < 32; ++i) m = umax(m, kk[i]);
;       m = umax(m, (unsigned)__shfl_xor((int)m, 16));
;       m = umax(m, (unsigned)__shfl_xor((int)m, 32));
;       win[pp][rr] = m;
; #pragma unroll
;       for (int i = 0; i < 32; ++i) kk[i] = (kk[i] == m) ? 0u : kk[i];
;     }
	v_max_u32_e32 v149, v149, v167
	v_mov_b32_e32 v167, v149
	s_nop 1
	v_permlane32_swap_b32 v149, v167
	s_nop 1
	s_waitcnt lgkmcnt(0)
	v_max_u32_e32 v149, v149, v167
	v_cmp_ne_u32_e32 vcc, v4, v149
	v_cmp_ne_u32_e64 s[98:99], v5, v149
	v_cmp_ne_u32_e64 s[100:101], v6, v149
	v_cndmask_b32_e32 v4, 0, v4, vcc
	v_cndmask_b32_e64 v5, 0, v5, s[98:99]
	v_cndmask_b32_e64 v6, 0, v6, s[100:101]
	v_cmp_ne_u32_e32 vcc, v7, v149
	v_cmp_ne_u32_e64 s[98:99], v8, v149
	v_cmp_ne_u32_e64 s[100:101], v9, v149
	v_cndmask_b32_e32 v7, 0, v7, vcc
	v_cndmask_b32_e64 v8, 0, v8, s[98:99]
	v_cndmask_b32_e64 v9, 0, v9, s[100:101]
	v_cmp_ne_u32_e32 vcc, v10, v149
	v_cmp_ne_u32_e64 s[98:99], v11, v149
	v_cmp_ne_u32_e64 s[100:101], v12, v149
	v_cndmask_b32_e32 v10, 0, v10, vcc
	v_cndmask_b32_e64 v11, 0, v11, s[98:99]
	v_cndmask_b32_e64 v12, 0, v12, s[100:101]
	v_cmp_ne_u32_e32 vcc, v13, v149
	v_cmp_ne_u32_e64 s[98:99], v14, v149
	v_cmp_ne_u32_e64 s[100:101], v15, v149
	v_cndmask_b32_e32 v13, 0, v13, vcc
	v_cndmask_b32_e64 v14, 0, v14, s[98:99]
	v_cndmask_b32_e64 v15, 0, v15, s[100:101]
	v_cmp_ne_u32_e32 vcc, v165, v149
	v_cmp_ne_u32_e64 s[98:99], v166, v149
	v_cmp_ne_u32_e64 s[100:101], v150, v149
	v_cndmask_b32_e32 v165, 0, v165, vcc
	v_cndmask_b32_e64 v166, 0, v166, s[98:99]
	v_cndmask_b32_e64 v167, 0, v150, s[100:101]
	v_cmp_ne_u32_e32 vcc, v151, v149
	v_max_u32_e32 v150, v4, v5
	v_max3_u32 v150, v150, v6, v7
	v_cndmask_b32_e32 v151, 0, v151, vcc
	v_cmp_ne_u32_e64 s[98:99], v152, v149
	v_max3_u32 v150, v150, v8, v9
	v_max3_u32 v150, v150, v10, v11
	v_cndmask_b32_e64 v152, 0, v152, s[98:99]
	v_cmp_ne_u32_e64 s[100:101], v153, v149
	v_max3_u32 v150, v150, v12, v13
	v_max3_u32 v150, v150, v14, v15
	v_cndmask_b32_e64 v153, 0, v153, s[100:101]
	v_cmp_ne_u32_e32 vcc, v154, v149
	v_max3_u32 v150, v150, v165, v166
	v_max3_u32 v150, v150, v167, v151
	v_cndmask_b32_e32 v154, 0, v154, vcc
	v_cmp_ne_u32_e64 s[98:99], v155, v149
	v_max3_u32 v150, v150, v152, v153
	v_cmp_ne_u32_e64 s[100:101], v156, v149
	v_cndmask_b32_e64 v155, 0, v155, s[98:99]
	v_max3_u32 v150, v150, v154, v155
	v_cndmask_b32_e64 v156, 0, v156, s[100:101]
	v_cmp_ne_u32_e32 vcc, v157, v149
	v_cmp_ne_u32_e64 s[98:99], v158, v149
	v_cmp_ne_u32_e64 s[100:101], v159, v149
	v_cndmask_b32_e32 v157, 0, v157, vcc
	v_max3_u32 v150, v150, v156, v157
	v_cndmask_b32_e64 v158, 0, v158, s[98:99]
	v_cndmask_b32_e64 v159, 0, v159, s[100:101]
	v_cmp_ne_u32_e32 vcc, v160, v149
	v_max3_u32 v150, v150, v158, v159
	v_cmp_ne_u32_e64 s[98:99], v161, v149
	v_cndmask_b32_e32 v160, 0, v160, vcc
	v_cmp_ne_u32_e64 s[100:101], v162, v149
	v_cndmask_b32_e64 v161, 0, v161, s[98:99]
	v_max3_u32 v150, v150, v160, v161
	v_cndmask_b32_e64 v162, 0, v162, s[100:101]
	v_cmp_ne_u32_e32 vcc, v164, v149
	v_cmp_ne_u32_e64 s[98:99], v0, v149
	v_cmp_ne_u32_e64 s[100:101], v1, v149
	v_cndmask_b32_e32 v164, 0, v164, vcc
	v_max3_u32 v150, v150, v162, v164
	v_cndmask_b32_e64 v0, 0, v0, s[98:99]
	v_cndmask_b32_e64 v1, 0, v1, s[100:101]
	v_cmp_ne_u32_e32 vcc, v2, v149
	v_max3_u32 v150, v150, v0, v1
	v_cmp_ne_u32_e64 s[98:99], v3, v149
	v_cndmask_b32_e32 v2, 0, v2, vcc
	s_nop 0
	v_cndmask_b32_e64 v3, 0, v3, s[98:99]
	v_max3_u32 v150, v150, v2, v3
	v_mov_b32_e32 v168, v150
	s_nop 1
	v_permlane16_swap_b32 v150, v168
	s_nop 1
	s_waitcnt lgkmcnt(0)
	v_max_u32_e32 v150, v150, v168
	v_mov_b32_e32 v168, v150
	s_nop 1
	v_permlane32_swap_b32 v150, v168
	s_nop 1
	s_waitcnt lgkmcnt(0)
	v_max_u32_e32 v150, v150, v168
	v_cmp_ne_u32_e32 vcc, v4, v150
	v_cmp_ne_u32_e64 s[98:99], v5, v150
	v_cmp_ne_u32_e64 s[100:101], v6, v150
	v_cndmask_b32_e32 v4, 0, v4, vcc
	v_cndmask_b32_e64 v5, 0, v5, s[98:99]
	v_cndmask_b32_e64 v6, 0, v6, s[100:101]
	v_cmp_ne_u32_e32 vcc, v7, v150
	v_cmp_ne_u32_e64 s[98:99], v8, v150
	v_cmp_ne_u32_e64 s[100:101], v9, v150
	v_cndmask_b32_e32 v7, 0, v7, vcc
	v_cndmask_b32_e64 v8, 0, v8, s[98:99]
	v_cndmask_b32_e64 v9, 0, v9, s[100:101]
	v_cmp_ne_u32_e32 vcc, v10, v150
	v_cmp_ne_u32_e64 s[98:99], v11, v150
	v_cmp_ne_u32_e64 s[100:101], v12, v150
	v_cndmask_b32_e32 v10, 0, v10, vcc
	v_cndmask_b32_e64 v11, 0, v11, s[98:99]
	v_cndmask_b32_e64 v12, 0, v12, s[100:101]
	v_cmp_ne_u32_e32 vcc, v13, v150
	v_cmp_ne_u32_e64 s[98:99], v14, v150
	v_cmp_ne_u32_e64 s[100:101], v15, v150
	v_cndmask_b32_e32 v13, 0, v13, vcc
	v_cndmask_b32_e64 v14, 0, v14, s[98:99]
	v_cndmask_b32_e64 v15, 0, v15, s[100:101]
	v_cmp_ne_u32_e32 vcc, v165, v150
	v_cmp_ne_u32_e64 s[98:99], v166, v150
	v_cmp_ne_u32_e64 s[100:101], v167, v150
	v_cndmask_b32_e32 v165, 0, v165, vcc
	v_cndmask_b32_e64 v166, 0, v166, s[98:99]
	v_cndmask_b32_e64 v167, 0, v167, s[100:101]
	v_cmp_ne_u32_e32 vcc, v151, v150
	v_cmp_ne_u32_e64 s[98:99], v152, v150
	v_cmp_ne_u32_e64 s[100:101], v153, v150
	v_cndmask_b32_e32 v168, 0, v151, vcc
	v_max_u32_e32 v151, v4, v5
	v_max3_u32 v151, v151, v6, v7
	v_cndmask_b32_e64 v152, 0, v152, s[98:99]
	v_max3_u32 v151, v151, v8, v9
	v_max3_u32 v151, v151, v10, v11
	v_cndmask_b32_e64 v153, 0, v153, s[100:101]
	v_cmp_ne_u32_e32 vcc, v154, v150
	v_max3_u32 v151, v151, v12, v13
	v_max3_u32 v151, v151, v14, v15
	v_cndmask_b32_e32 v154, 0, v154, vcc
	v_cmp_ne_u32_e64 s[98:99], v155, v150
	v_max3_u32 v151, v151, v165, v166
	v_max3_u32 v151, v151, v167, v168
	v_cndmask_b32_e64 v155, 0, v155, s[98:99]
	v_cmp_ne_u32_e64 s[100:101], v156, v150
	v_max3_u32 v151, v151, v152, v153
	v_max3_u32 v151, v151, v154, v155
	v_cndmask_b32_e64 v156, 0, v156, s[100:101]
	v_cmp_ne_u32_e32 vcc, v157, v150
	v_cmp_ne_u32_e64 s[98:99], v158, v150
	v_cmp_ne_u32_e64 s[100:101], v159, v150
	v_cndmask_b32_e32 v157, 0, v157, vcc
	v_max3_u32 v151, v151, v156, v157
	v_cndmask_b32_e64 v158, 0, v158, s[98:99]
	v_cndmask_b32_e64 v159, 0, v159, s[100:101]
	v_cmp_ne_u32_e32 vcc, v160, v150
	v_max3_u32 v151, v151, v158, v159
	v_cmp_ne_u32_e64 s[98:99], v161, v150
	v_cndmask_b32_e32 v160, 0, v160, vcc
	v_cmp_ne_u32_e64 s[100:101], v162, v150
	v_cndmask_b32_e64 v161, 0, v161, s[98:99]
	v_max3_u32 v151, v151, v160, v161
	v_cndmask_b32_e64 v162, 0, v162, s[100:101]
	v_cmp_ne_u32_e32 vcc, v164, v150
	v_cmp_ne_u32_e64 s[98:99], v0, v150
	v_cmp_ne_u32_e64 s[100:101], v1, v150
	v_cndmask_b32_e32 v164, 0, v164, vcc
	v_max3_u32 v151, v151, v162, v164
	v_cndmask_b32_e64 v0, 0, v0, s[98:99]
	v_cndmask_b32_e64 v1, 0, v1, s[100:101]
	v_cmp_ne_u32_e32 vcc, v2, v150
	v_max3_u32 v151, v151, v0, v1
	v_cmp_ne_u32_e64 s[98:99], v3, v150
	v_cndmask_b32_e32 v2, 0, v2, vcc
	s_nop 0
	v_cndmask_b32_e64 v3, 0, v3, s[98:99]
	v_max3_u32 v151, v151, v2, v3
	v_mov_b32_e32 v169, v151
	s_nop 1
	v_permlane16_swap_b32 v151, v169
	s_nop 1
	s_waitcnt lgkmcnt(0)
; DI void peer_topk_wave(const Params& p, int item, unsigned* lds  ) {
;     ...
; #pragma unroll
;     for (int rr = 0; rr < 16; ++rr) {
;       unsigned m = 0;
; #pragma unroll
;       for (int i = 0; i < 32; ++i) m = umax(m, kk[i]);
;       m = umax(m, (unsigned)__shfl_xor((int)m, 16));
;       m = umax(m, (unsigned)__shfl_xor((int)m, 32));
;       win[pp][rr] = m;
; #pragma unroll
;       for (int i = 0; i < 32; ++i) kk[i] = (kk[i] == m) ? 0u : kk[i];
;     }
	v_max_u32_e32 v151, v151, v169
	v_mov_b32_e32 v169, v151
	s_nop 1
	v_permlane32_swap_b32 v151, v169
	s_nop 1
	s_waitcnt lgkmcnt(0)
	v_max_u32_e32 v151, v151, v169
	v_cmp_ne_u32_e32 vcc, v4, v151
	v_cmp_ne_u32_e64 s[98:99], v5, v151
	v_cmp_ne_u32_e64 s[100:101], v6, v151
	v_cndmask_b32_e32 v4, 0, v4, vcc
	v_cndmask_b32_e64 v5, 0, v5, s[98:99]
	v_cndmask_b32_e64 v6, 0, v6, s[100:101]
	v_cmp_ne_u32_e32 vcc, v7, v151
	v_cmp_ne_u32_e64 s[98:99], v8, v151
	v_cmp_ne_u32_e64 s[100:101], v9, v151
	v_cndmask_b32_e32 v7, 0, v7, vcc
	v_cndmask_b32_e64 v8, 0, v8, s[98:99]
	v_cndmask_b32_e64 v9, 0, v9, s[100:101]
	v_cmp_ne_u32_e32 vcc, v10, v151
	v_cmp_ne_u32_e64 s[98:99], v11, v151
	v_cmp_ne_u32_e64 s[100:101], v12, v151
	v_cndmask_b32_e32 v10, 0, v10, vcc
	v_cndmask_b32_e64 v11, 0, v11, s[98:99]
	v_cndmask_b32_e64 v12, 0, v12, s[100:101]
	v_cmp_ne_u32_e32 vcc, v13, v151
	v_cmp_ne_u32_e64 s[98:99], v14, v151
	v_cmp_ne_u32_e64 s[100:101], v15, v151
	v_cndmask_b32_e32 v13, 0, v13, vcc
	v_cndmask_b32_e64 v14, 0, v14, s[98:99]
	v_cndmask_b32_e64 v15, 0, v15, s[100:101]
	v_cmp_ne_u32_e32 vcc, v165, v151
	v_cmp_ne_u32_e64 s[98:99], v166, v151
	v_cmp_ne_u32_e64 s[100:101], v167, v151
	v_cndmask_b32_e32 v165, 0, v165, vcc
	v_cndmask_b32_e64 v166, 0, v166, s[98:99]
	v_cndmask_b32_e64 v167, 0, v167, s[100:101]
	v_cmp_ne_u32_e32 vcc, v168, v151
	v_cmp_ne_u32_e64 s[98:99], v152, v151
	v_cmp_ne_u32_e64 s[100:101], v153, v151
	v_cndmask_b32_e32 v168, 0, v168, vcc
	v_cndmask_b32_e64 v169, 0, v152, s[98:99]
	v_max_u32_e32 v152, v4, v5
	v_max3_u32 v152, v152, v6, v7
	v_cndmask_b32_e64 v153, 0, v153, s[100:101]
	v_cmp_ne_u32_e32 vcc, v154, v151
	v_max3_u32 v152, v152, v8, v9
	v_max3_u32 v152, v152, v10, v11
	v_cndmask_b32_e32 v154, 0, v154, vcc
	v_cmp_ne_u32_e64 s[98:99], v155, v151
	v_max3_u32 v152, v152, v12, v13
	v_max3_u32 v152, v152, v14, v15
	v_cndmask_b32_e64 v155, 0, v155, s[98:99]
	v_cmp_ne_u32_e64 s[100:101], v156, v151
	v_max3_u32 v152, v152, v165, v166
	v_max3_u32 v152, v152, v167, v168
	v_cndmask_b32_e64 v156, 0, v156, s[100:101]
	v_cmp_ne_u32_e32 vcc, v157, v151
	v_max3_u32 v152, v152, v169, v153
	v_max3_u32 v152, v152, v154, v155
	v_cndmask_b32_e32 v157, 0, v157, vcc
	v_cmp_ne_u32_e64 s[98:99], v158, v151
	v_max3_u32 v152, v152, v156, v157
	v_cmp_ne_u32_e64 s[100:101], v159, v151
	v_cndmask_b32_e64 v158, 0, v158, s[98:99]
	v_cmp_ne_u32_e32 vcc, v160, v151
	v_cndmask_b32_e64 v159, 0, v159, s[100:101]
	v_max3_u32 v152, v152, v158, v159
	v_cndmask_b32_e32 v160, 0, v160, vcc
	v_cmp_ne_u32_e64 s[98:99], v161, v151
	v_cmp_ne_u32_e64 s[100:101], v162, v151
	v_cmp_ne_u32_e32 vcc, v164, v151
	v_cndmask_b32_e64 v161, 0, v161, s[98:99]
	v_max3_u32 v152, v152, v160, v161
	v_cndmask_b32_e64 v162, 0, v162, s[100:101]
	v_cndmask_b32_e32 v164, 0, v164, vcc
	v_cmp_ne_u32_e64 s[98:99], v0, v151
	v_max3_u32 v152, v152, v162, v164
	v_cmp_ne_u32_e64 s[100:101], v1, v151
	v_cndmask_b32_e64 v0, 0, v0, s[98:99]
	v_cmp_ne_u32_e32 vcc, v2, v151
	v_cndmask_b32_e64 v1, 0, v1, s[100:101]
	v_max3_u32 v152, v152, v0, v1
	v_cndmask_b32_e32 v2, 0, v2, vcc
	v_cmp_ne_u32_e64 s[98:99], v3, v151
	s_nop 0
	s_nop 0
	v_cndmask_b32_e64 v3, 0, v3, s[98:99]
	v_max3_u32 v152, v152, v2, v3
	v_mov_b32_e32 v171, v152
	s_nop 1
	v_permlane16_swap_b32 v152, v171
	s_nop 1
	s_waitcnt lgkmcnt(0)
	v_max_u32_e32 v152, v152, v171
	v_mov_b32_e32 v171, v152
	s_nop 1
	v_permlane32_swap_b32 v152, v171
	s_nop 1
	s_waitcnt lgkmcnt(0)
	v_max_u32_e32 v152, v152, v171
	v_cmp_ne_u32_e32 vcc, v4, v152
	v_cmp_ne_u32_e64 s[98:99], v5, v152
	v_cmp_ne_u32_e64 s[100:101], v6, v152
	v_cndmask_b32_e32 v4, 0, v4, vcc
	v_cndmask_b32_e64 v5, 0, v5, s[98:99]
	v_cndmask_b32_e64 v6, 0, v6, s[100:101]
	v_cmp_ne_u32_e32 vcc, v7, v152
	v_cmp_ne_u32_e64 s[98:99], v8, v152
	v_cmp_ne_u32_e64 s[100:101], v9, v152
	v_cndmask_b32_e32 v7, 0, v7, vcc
	v_cndmask_b32_e64 v8, 0, v8, s[98:99]
	v_cndmask_b32_e64 v9, 0, v9, s[100:101]
	v_cmp_ne_u32_e32 vcc, v10, v152
	v_cmp_ne_u32_e64 s[98:99], v11, v152
	v_cmp_ne_u32_e64 s[100:101], v12, v152
	v_cndmask_b32_e32 v10, 0, v10, vcc
	v_cndmask_b32_e64 v11, 0, v11, s[98:99]
	v_cndmask_b32_e64 v12, 0, v12, s[100:101]
	v_cmp_ne_u32_e32 vcc, v13, v152
	v_cmp_ne_u32_e64 s[98:99], v14, v152
	v_cmp_ne_u32_e64 s[100:101], v15, v152
	v_cndmask_b32_e32 v13, 0, v13, vcc
	v_cndmask_b32_e64 v14, 0, v14, s[98:99]
	v_cndmask_b32_e64 v15, 0, v15, s[100:101]
	v_cmp_ne_u32_e32 vcc, v165, v152
	v_cmp_ne_u32_e64 s[98:99], v166, v152
	v_cmp_ne_u32_e64 s[100:101], v167, v152
	v_cndmask_b32_e32 v165, 0, v165, vcc
	v_cndmask_b32_e64 v166, 0, v166, s[98:99]
	v_cndmask_b32_e64 v167, 0, v167, s[100:101]
	v_cmp_ne_u32_e32 vcc, v168, v152
	v_cmp_ne_u32_e64 s[98:99], v169, v152
	v_cmp_ne_u32_e64 s[100:101], v153, v152
	v_cndmask_b32_e32 v168, 0, v168, vcc
	v_cndmask_b32_e64 v169, 0, v169, s[98:99]
	v_cndmask_b32_e64 v171, 0, v153, s[100:101]
	v_cmp_ne_u32_e32 vcc, v154, v152
	v_max_u32_e32 v153, v4, v5
	v_max3_u32 v153, v153, v6, v7
	v_cndmask_b32_e32 v154, 0, v154, vcc
	v_cmp_ne_u32_e64 s[98:99], v155, v152
	v_max3_u32 v153, v153, v8, v9
	v_max3_u32 v153, v153, v10, v11
	v_cndmask_b32_e64 v155, 0, v155, s[98:99]
	v_cmp_ne_u32_e64 s[100:101], v156, v152
	v_max3_u32 v153, v153, v12, v13
	v_max3_u32 v153, v153, v14, v15
	v_cndmask_b32_e64 v156, 0, v156, s[100:101]
	v_cmp_ne_u32_e32 vcc, v157, v152
	v_max3_u32 v153, v153, v165, v166
	v_max3_u32 v153, v153, v167, v168
	v_cndmask_b32_e32 v157, 0, v157, vcc
	v_cmp_ne_u32_e64 s[98:99], v158, v152
	v_max3_u32 v153, v153, v169, v171
	v_max3_u32 v153, v153, v154, v155
	v_cndmask_b32_e64 v158, 0, v158, s[98:99]
	v_cmp_ne_u32_e64 s[100:101], v159, v152
	v_max3_u32 v153, v153, v156, v157
	v_cmp_ne_u32_e32 vcc, v160, v152
	v_cndmask_b32_e64 v159, 0, v159, s[100:101]
	v_max3_u32 v153, v153, v158, v159
	v_cndmask_b32_e32 v160, 0, v160, vcc
	v_cmp_ne_u32_e64 s[98:99], v161, v152
	v_cmp_ne_u32_e64 s[100:101], v162, v152
	v_cmp_ne_u32_e32 vcc, v164, v152
	v_cndmask_b32_e64 v161, 0, v161, s[98:99]
	v_max3_u32 v153, v153, v160, v161
	v_cndmask_b32_e64 v162, 0, v162, s[100:101]
	v_cndmask_b32_e32 v164, 0, v164, vcc
	v_cmp_ne_u32_e64 s[98:99], v0, v152
	v_max3_u32 v153, v153, v162, v164
	v_cmp_ne_u32_e64 s[100:101], v1, v152
	v_cndmask_b32_e64 v0, 0, v0, s[98:99]
	v_cmp_ne_u32_e32 vcc, v2, v152
	v_cndmask_b32_e64 v1, 0, v1, s[100:101]
	v_max3_u32 v153, v153, v0, v1
	v_cndmask_b32_e32 v2, 0, v2, vcc
	v_cmp_ne_u32_e64 s[98:99], v3, v152
	s_nop 0
	s_nop 0
	v_cndmask_b32_e64 v3, 0, v3, s[98:99]
	v_max3_u32 v153, v153, v2, v3
	v_mov_b32_e32 v172, v153
	s_nop 1
	v_permlane16_swap_b32 v153, v172
	s_nop 1
	s_waitcnt lgkmcnt(0)
; DI void peer_topk_wave(const Params& p, int item, unsigned* lds  ) {
;     ...
; #pragma unroll
;     for (int rr = 0; rr < 16; ++rr) {
;       unsigned m = 0;
; #pragma unroll
;       for (int i = 0; i < 32; ++i) m = umax(m, kk[i]);
;       m = umax(m, (unsigned)__shfl_xor((int)m, 16));
;       m = umax(m, (unsigned)__shfl_xor((int)m, 32));
;       win[pp][rr] = m;
; #pragma unroll
;       for (int i = 0; i < 32; ++i) kk[i] = (kk[i] == m) ? 0u : kk[i];
;     }
	v_max_u32_e32 v153, v153, v172
	v_mov_b32_e32 v172, v153
	s_nop 1
	v_permlane32_swap_b32 v153, v172
	s_nop 1
	s_waitcnt lgkmcnt(0)
	v_max_u32_e32 v153, v153, v172
	v_cmp_ne_u32_e32 vcc, v4, v153
	v_cmp_ne_u32_e64 s[98:99], v5, v153
	v_cmp_ne_u32_e64 s[100:101], v6, v153
	v_cndmask_b32_e32 v4, 0, v4, vcc
	v_cndmask_b32_e64 v5, 0, v5, s[98:99]
	v_cndmask_b32_e64 v6, 0, v6, s[100:101]
	v_cmp_ne_u32_e32 vcc, v7, v153
	v_cmp_ne_u32_e64 s[98:99], v8, v153
	v_cmp_ne_u32_e64 s[100:101], v9, v153
	v_cndmask_b32_e32 v7, 0, v7, vcc
	v_cndmask_b32_e64 v8, 0, v8, s[98:99]
	v_cndmask_b32_e64 v9, 0, v9, s[100:101]
	v_cmp_ne_u32_e32 vcc, v10, v153
	v_cmp_ne_u32_e64 s[98:99], v11, v153
	v_cmp_ne_u32_e64 s[100:101], v12, v153
	v_cndmask_b32_e32 v10, 0, v10, vcc
	v_cndmask_b32_e64 v11, 0, v11, s[98:99]
	v_cndmask_b32_e64 v12, 0, v12, s[100:101]
	v_cmp_ne_u32_e32 vcc, v13, v153
	v_cmp_ne_u32_e64 s[98:99], v14, v153
	v_cmp_ne_u32_e64 s[100:101], v15, v153
	v_cndmask_b32_e32 v13, 0, v13, vcc
	v_cndmask_b32_e64 v14, 0, v14, s[98:99]
	v_cndmask_b32_e64 v15, 0, v15, s[100:101]
	v_cmp_ne_u32_e32 vcc, v165, v153
	v_cmp_ne_u32_e64 s[98:99], v166, v153
	v_cmp_ne_u32_e64 s[100:101], v167, v153
	v_cndmask_b32_e32 v165, 0, v165, vcc
	v_cndmask_b32_e64 v166, 0, v166, s[98:99]
	v_cndmask_b32_e64 v167, 0, v167, s[100:101]
	v_cmp_ne_u32_e32 vcc, v168, v153
	v_cmp_ne_u32_e64 s[98:99], v169, v153
	v_cmp_ne_u32_e64 s[100:101], v171, v153
	v_cndmask_b32_e32 v168, 0, v168, vcc
	v_cndmask_b32_e64 v169, 0, v169, s[98:99]
	v_cndmask_b32_e64 v171, 0, v171, s[100:101]
	v_cmp_ne_u32_e32 vcc, v154, v153
	v_cmp_ne_u32_e64 s[98:99], v155, v153
	v_cmp_ne_u32_e64 s[100:101], v156, v153
	v_cndmask_b32_e32 v172, 0, v154, vcc
	v_max_u32_e32 v154, v4, v5
	v_max3_u32 v154, v154, v6, v7
	v_max3_u32 v154, v154, v8, v9
	v_cndmask_b32_e64 v155, 0, v155, s[98:99]
	v_max3_u32 v154, v154, v10, v11
	v_max3_u32 v154, v154, v12, v13
	v_cndmask_b32_e64 v156, 0, v156, s[100:101]
	v_cmp_ne_u32_e32 vcc, v157, v153
	v_max3_u32 v154, v154, v14, v15
	v_max3_u32 v154, v154, v165, v166
	v_cndmask_b32_e32 v157, 0, v157, vcc
	v_cmp_ne_u32_e64 s[98:99], v158, v153
	v_max3_u32 v154, v154, v167, v168
	v_max3_u32 v154, v154, v169, v171
	v_cndmask_b32_e64 v158, 0, v158, s[98:99]
	v_cmp_ne_u32_e64 s[100:101], v159, v153
	v_max3_u32 v154, v154, v172, v155
	v_max3_u32 v154, v154, v156, v157
	v_cndmask_b32_e64 v159, 0, v159, s[100:101]
	v_cmp_ne_u32_e32 vcc, v160, v153
	v_max3_u32 v154, v154, v158, v159
	v_cmp_ne_u32_e64 s[98:99], v161, v153
	v_cndmask_b32_e32 v160, 0, v160, vcc
	v_cmp_ne_u32_e64 s[100:101], v162, v153
	v_cndmask_b32_e64 v161, 0, v161, s[98:99]
	v_max3_u32 v154, v154, v160, v161
	v_cndmask_b32_e64 v162, 0, v162, s[100:101]
	v_cmp_ne_u32_e32 vcc, v164, v153
	v_cmp_ne_u32_e64 s[98:99], v0, v153
	v_cmp_ne_u32_e64 s[100:101], v1, v153
	v_cndmask_b32_e32 v164, 0, v164, vcc
	v_max3_u32 v154, v154, v162, v164
	v_cndmask_b32_e64 v0, 0, v0, s[98:99]
	v_cndmask_b32_e64 v1, 0, v1, s[100:101]
	v_cmp_ne_u32_e32 vcc, v2, v153
	v_max3_u32 v154, v154, v0, v1
	v_cmp_ne_u32_e64 s[98:99], v3, v153
	v_cndmask_b32_e32 v2, 0, v2, vcc
	s_nop 0
	v_cndmask_b32_e64 v3, 0, v3, s[98:99]
	v_max3_u32 v154, v154, v2, v3
	v_mov_b32_e32 v173, v154
	s_nop 1
	v_permlane16_swap_b32 v154, v173
	s_nop 1
	s_waitcnt lgkmcnt(0)
	v_max_u32_e32 v154, v154, v173
	v_mov_b32_e32 v173, v154
	s_nop 1
	v_permlane32_swap_b32 v154, v173
	s_nop 1
	s_waitcnt lgkmcnt(0)
	v_max_u32_e32 v154, v154, v173
	v_cmp_ne_u32_e32 vcc, v4, v154
	v_cmp_ne_u32_e64 s[98:99], v5, v154
	v_cmp_ne_u32_e64 s[100:101], v6, v154
	v_cndmask_b32_e32 v4, 0, v4, vcc
	v_cndmask_b32_e64 v5, 0, v5, s[98:99]
	v_cndmask_b32_e64 v6, 0, v6, s[100:101]
	v_cmp_ne_u32_e32 vcc, v7, v154
	v_cmp_ne_u32_e64 s[98:99], v8, v154
	v_cmp_ne_u32_e64 s[100:101], v9, v154
	v_cndmask_b32_e32 v7, 0, v7, vcc
	v_cndmask_b32_e64 v8, 0, v8, s[98:99]
	v_cndmask_b32_e64 v9, 0, v9, s[100:101]
	v_cmp_ne_u32_e32 vcc, v10, v154
	v_cmp_ne_u32_e64 s[98:99], v11, v154
	v_cmp_ne_u32_e64 s[100:101], v12, v154
	v_cndmask_b32_e32 v10, 0, v10, vcc
	v_cndmask_b32_e64 v11, 0, v11, s[98:99]
	v_cndmask_b32_e64 v12, 0, v12, s[100:101]
	v_cmp_ne_u32_e32 vcc, v13, v154
	v_cmp_ne_u32_e64 s[98:99], v14, v154
	v_cmp_ne_u32_e64 s[100:101], v15, v154
	v_cndmask_b32_e32 v13, 0, v13, vcc
	v_cndmask_b32_e64 v14, 0, v14, s[98:99]
	v_cndmask_b32_e64 v15, 0, v15, s[100:101]
	v_cmp_ne_u32_e32 vcc, v165, v154
	v_cmp_ne_u32_e64 s[98:99], v166, v154
	v_cmp_ne_u32_e64 s[100:101], v167, v154
	v_cndmask_b32_e32 v165, 0, v165, vcc
	v_cndmask_b32_e64 v166, 0, v166, s[98:99]
	v_cndmask_b32_e64 v167, 0, v167, s[100:101]
	v_cmp_ne_u32_e32 vcc, v168, v154
	v_cmp_ne_u32_e64 s[98:99], v169, v154
	v_cmp_ne_u32_e64 s[100:101], v171, v154
	v_cndmask_b32_e32 v168, 0, v168, vcc
	v_cndmask_b32_e64 v169, 0, v169, s[98:99]
	v_cndmask_b32_e64 v171, 0, v171, s[100:101]
	v_cmp_ne_u32_e32 vcc, v172, v154
	v_cmp_ne_u32_e64 s[98:99], v155, v154
	v_cmp_ne_u32_e64 s[100:101], v156, v154
	v_cndmask_b32_e32 v172, 0, v172, vcc
	v_cndmask_b32_e64 v173, 0, v155, s[98:99]
	v_max_u32_e32 v155, v4, v5
	v_max3_u32 v155, v155, v6, v7
	v_max3_u32 v155, v155, v8, v9
	v_max3_u32 v155, v155, v10, v11
	v_cndmask_b32_e64 v156, 0, v156, s[100:101]
	v_cmp_ne_u32_e32 vcc, v157, v154
	v_max3_u32 v155, v155, v12, v13
	v_max3_u32 v155, v155, v14, v15
	v_cndmask_b32_e32 v157, 0, v157, vcc
	v_cmp_ne_u32_e64 s[98:99], v158, v154
	v_max3_u32 v155, v155, v165, v166
	v_max3_u32 v155, v155, v167, v168
	v_cndmask_b32_e64 v158, 0, v158, s[98:99]
	v_cmp_ne_u32_e64 s[100:101], v159, v154
	v_max3_u32 v155, v155, v169, v171
	v_max3_u32 v155, v155, v172, v173
	v_cndmask_b32_e64 v159, 0, v159, s[100:101]
	v_cmp_ne_u32_e32 vcc, v160, v154
	v_max3_u32 v155, v155, v156, v157
	v_max3_u32 v155, v155, v158, v159
	v_cndmask_b32_e32 v160, 0, v160, vcc
	v_cmp_ne_u32_e64 s[98:99], v161, v154
	v_cmp_ne_u32_e64 s[100:101], v162, v154
	v_cmp_ne_u32_e32 vcc, v164, v154
	v_cndmask_b32_e64 v161, 0, v161, s[98:99]
	v_max3_u32 v155, v155, v160, v161
	v_cndmask_b32_e64 v162, 0, v162, s[100:101]
	v_cndmask_b32_e32 v164, 0, v164, vcc
	v_cmp_ne_u32_e64 s[98:99], v0, v154
	v_max3_u32 v155, v155, v162, v164
	v_cmp_ne_u32_e64 s[100:101], v1, v154
	v_cndmask_b32_e64 v0, 0, v0, s[98:99]
	v_cmp_ne_u32_e32 vcc, v2, v154
	v_cndmask_b32_e64 v1, 0, v1, s[100:101]
	v_max3_u32 v155, v155, v0, v1
	v_cndmask_b32_e32 v2, 0, v2, vcc
	v_cmp_ne_u32_e64 s[98:99], v3, v154
	s_nop 0
	s_nop 0
	v_cndmask_b32_e64 v3, 0, v3, s[98:99]
	v_max3_u32 v155, v155, v2, v3
	v_mov_b32_e32 v176, v155
	s_nop 1
	v_permlane16_swap_b32 v155, v176
	s_nop 1
	s_waitcnt lgkmcnt(0)
; DI void peer_topk_wave(const Params& p, int item, unsigned* lds  ) {
;     ...
; #pragma unroll
;     for (int rr = 0; rr < 16; ++rr) {
;       unsigned m = 0;
; #pragma unroll
;       for (int i = 0; i < 32; ++i) m = umax(m, kk[i]);
;       m = umax(m, (unsigned)__shfl_xor((int)m, 16));
;       m = umax(m, (unsigned)__shfl_xor((int)m, 32));
;       win[pp][rr] = m;
; #pragma unroll
;       for (int i = 0; i < 32; ++i) kk[i] = (kk[i] == m) ? 0u : kk[i];
;     }
	v_max_u32_e32 v155, v155, v176
	v_mov_b32_e32 v176, v155
	s_nop 1
	v_permlane32_swap_b32 v155, v176
	s_nop 1
	s_waitcnt lgkmcnt(0)
	v_max_u32_e32 v155, v155, v176
	v_cmp_ne_u32_e32 vcc, v4, v155
	v_cmp_ne_u32_e64 s[98:99], v5, v155
	v_cmp_ne_u32_e64 s[100:101], v6, v155
	v_cndmask_b32_e32 v4, 0, v4, vcc
	v_cndmask_b32_e64 v5, 0, v5, s[98:99]
	v_cndmask_b32_e64 v6, 0, v6, s[100:101]
	v_cmp_ne_u32_e32 vcc, v7, v155
	v_cmp_ne_u32_e64 s[98:99], v8, v155
	v_cmp_ne_u32_e64 s[100:101], v9, v155
	v_cndmask_b32_e32 v7, 0, v7, vcc
	v_cndmask_b32_e64 v8, 0, v8, s[98:99]
	v_cndmask_b32_e64 v9, 0, v9, s[100:101]
	v_cmp_ne_u32_e32 vcc, v10, v155
	v_cmp_ne_u32_e64 s[98:99], v11, v155
	v_cmp_ne_u32_e64 s[100:101], v12, v155
	v_cndmask_b32_e32 v10, 0, v10, vcc
	v_cndmask_b32_e64 v11, 0, v11, s[98:99]
	v_cndmask_b32_e64 v12, 0, v12, s[100:101]
	v_cmp_ne_u32_e32 vcc, v13, v155
	v_cmp_ne_u32_e64 s[98:99], v14, v155
	v_cmp_ne_u32_e64 s[100:101], v15, v155
	v_cndmask_b32_e32 v13, 0, v13, vcc
	v_cndmask_b32_e64 v14, 0, v14, s[98:99]
	v_cndmask_b32_e64 v15, 0, v15, s[100:101]
	v_cmp_ne_u32_e32 vcc, v165, v155
	v_cmp_ne_u32_e64 s[98:99], v166, v155
	v_cmp_ne_u32_e64 s[100:101], v167, v155
	v_cndmask_b32_e32 v165, 0, v165, vcc
	v_cndmask_b32_e64 v166, 0, v166, s[98:99]
	v_cndmask_b32_e64 v167, 0, v167, s[100:101]
	v_cmp_ne_u32_e32 vcc, v168, v155
	v_cmp_ne_u32_e64 s[98:99], v169, v155
	v_cmp_ne_u32_e64 s[100:101], v171, v155
	v_cndmask_b32_e32 v168, 0, v168, vcc
	v_cndmask_b32_e64 v169, 0, v169, s[98:99]
	v_cndmask_b32_e64 v171, 0, v171, s[100:101]
	v_cmp_ne_u32_e32 vcc, v172, v155
	v_cmp_ne_u32_e64 s[98:99], v173, v155
	v_cmp_ne_u32_e64 s[100:101], v156, v155
	v_cndmask_b32_e32 v172, 0, v172, vcc
	v_cndmask_b32_e64 v173, 0, v173, s[98:99]
	v_cndmask_b32_e64 v176, 0, v156, s[100:101]
	v_max_u32_e32 v156, v4, v5
	v_max3_u32 v156, v156, v6, v7
	v_max3_u32 v156, v156, v8, v9
	v_cmp_ne_u32_e32 vcc, v157, v155
	v_max3_u32 v156, v156, v10, v11
	v_max3_u32 v156, v156, v12, v13
	v_cndmask_b32_e32 v157, 0, v157, vcc
	v_cmp_ne_u32_e64 s[98:99], v158, v155
	v_max3_u32 v156, v156, v14, v15
	v_max3_u32 v156, v156, v165, v166
	v_cndmask_b32_e64 v158, 0, v158, s[98:99]
	v_cmp_ne_u32_e64 s[100:101], v159, v155
	v_max3_u32 v156, v156, v167, v168
	v_max3_u32 v156, v156, v169, v171
	v_cndmask_b32_e64 v159, 0, v159, s[100:101]
	v_cmp_ne_u32_e32 vcc, v160, v155
	v_max3_u32 v156, v156, v172, v173
	v_max3_u32 v156, v156, v176, v157
	v_cndmask_b32_e32 v160, 0, v160, vcc
	v_cmp_ne_u32_e64 s[98:99], v161, v155
	v_max3_u32 v156, v156, v158, v159
	v_cmp_ne_u32_e64 s[100:101], v162, v155
	v_cndmask_b32_e64 v161, 0, v161, s[98:99]
	v_max3_u32 v156, v156, v160, v161
	v_cndmask_b32_e64 v162, 0, v162, s[100:101]
	v_cmp_ne_u32_e32 vcc, v164, v155
	v_cmp_ne_u32_e64 s[98:99], v0, v155
	v_cmp_ne_u32_e64 s[100:101], v1, v155
	v_cndmask_b32_e32 v164, 0, v164, vcc
	v_max3_u32 v156, v156, v162, v164
	v_cndmask_b32_e64 v0, 0, v0, s[98:99]
	v_cndmask_b32_e64 v1, 0, v1, s[100:101]
	v_cmp_ne_u32_e32 vcc, v2, v155
	v_max3_u32 v156, v156, v0, v1
	v_cmp_ne_u32_e64 s[98:99], v3, v155
	v_cndmask_b32_e32 v2, 0, v2, vcc
	s_nop 0
	v_cndmask_b32_e64 v3, 0, v3, s[98:99]
	v_max3_u32 v156, v156, v2, v3
	v_mov_b32_e32 v177, v156
	s_nop 1
	v_permlane16_swap_b32 v156, v177
	s_nop 1
	s_waitcnt lgkmcnt(0)
	v_max_u32_e32 v156, v156, v177
	v_mov_b32_e32 v177, v156
	s_nop 1
	v_permlane32_swap_b32 v156, v177
	s_nop 1
	s_waitcnt lgkmcnt(0)
	v_max_u32_e32 v156, v156, v177
	v_cmp_ne_u32_e32 vcc, v4, v156
	v_cmp_ne_u32_e64 s[98:99], v5, v156
	v_cmp_ne_u32_e64 s[100:101], v6, v156
	v_cndmask_b32_e32 v4, 0, v4, vcc
	v_cndmask_b32_e64 v5, 0, v5, s[98:99]
	v_cndmask_b32_e64 v6, 0, v6, s[100:101]
	v_cmp_ne_u32_e32 vcc, v7, v156
	v_cmp_ne_u32_e64 s[98:99], v8, v156
	v_cmp_ne_u32_e64 s[100:101], v9, v156
	v_cndmask_b32_e32 v7, 0, v7, vcc
	v_cndmask_b32_e64 v8, 0, v8, s[98:99]
	v_cndmask_b32_e64 v9, 0, v9, s[100:101]
	v_cmp_ne_u32_e32 vcc, v10, v156
	v_cmp_ne_u32_e64 s[98:99], v11, v156
	v_cmp_ne_u32_e64 s[100:101], v12, v156
	v_cndmask_b32_e32 v10, 0, v10, vcc
	v_cndmask_b32_e64 v11, 0, v11, s[98:99]
	v_cndmask_b32_e64 v12, 0, v12, s[100:101]
	v_cmp_ne_u32_e32 vcc, v13, v156
	v_cmp_ne_u32_e64 s[98:99], v14, v156
	v_cmp_ne_u32_e64 s[100:101], v15, v156
	v_cndmask_b32_e32 v13, 0, v13, vcc
	v_cndmask_b32_e64 v14, 0, v14, s[98:99]
	v_cndmask_b32_e64 v15, 0, v15, s[100:101]
	v_cmp_ne_u32_e32 vcc, v165, v156
	v_cmp_ne_u32_e64 s[98:99], v166, v156
	v_cmp_ne_u32_e64 s[100:101], v167, v156
	v_cndmask_b32_e32 v165, 0, v165, vcc
	v_cndmask_b32_e64 v166, 0, v166, s[98:99]
	v_cndmask_b32_e64 v167, 0, v167, s[100:101]
	v_cmp_ne_u32_e32 vcc, v168, v156
	v_cmp_ne_u32_e64 s[98:99], v169, v156
	v_cmp_ne_u32_e64 s[100:101], v171, v156
	v_cndmask_b32_e32 v168, 0, v168, vcc
	v_cndmask_b32_e64 v169, 0, v169, s[98:99]
	v_cndmask_b32_e64 v171, 0, v171, s[100:101]
	v_cmp_ne_u32_e32 vcc, v172, v156
	v_cmp_ne_u32_e64 s[98:99], v173, v156
	v_cmp_ne_u32_e64 s[100:101], v176, v156
	v_cndmask_b32_e32 v172, 0, v172, vcc
	v_cndmask_b32_e64 v173, 0, v173, s[98:99]
	v_cndmask_b32_e64 v176, 0, v176, s[100:101]
	v_cmp_ne_u32_e32 vcc, v157, v156
	v_cmp_ne_u32_e64 s[98:99], v158, v156
	v_cmp_ne_u32_e64 s[100:101], v159, v156
	v_cndmask_b32_e32 v177, 0, v157, vcc
	v_max_u32_e32 v157, v4, v5
	v_max3_u32 v157, v157, v6, v7
	v_max3_u32 v157, v157, v8, v9
	v_max3_u32 v157, v157, v10, v11
	v_max3_u32 v157, v157, v12, v13
	v_max3_u32 v157, v157, v14, v15
	v_cndmask_b32_e64 v158, 0, v158, s[98:99]
	v_max3_u32 v157, v157, v165, v166
	v_max3_u32 v157, v157, v167, v168
	v_cndmask_b32_e64 v159, 0, v159, s[100:101]
	v_cmp_ne_u32_e32 vcc, v160, v156
	v_max3_u32 v157, v157, v169, v171
	v_max3_u32 v157, v157, v172, v173
	v_cndmask_b32_e32 v160, 0, v160, vcc
	v_cmp_ne_u32_e64 s[98:99], v161, v156
	v_max3_u32 v157, v157, v176, v177
	v_max3_u32 v157, v157, v158, v159
	v_cndmask_b32_e64 v161, 0, v161, s[98:99]
	v_cmp_ne_u32_e64 s[100:101], v162, v156
	v_max3_u32 v157, v157, v160, v161
	v_cmp_ne_u32_e32 vcc, v164, v156
	v_cndmask_b32_e64 v162, 0, v162, s[100:101]
	v_cmp_ne_u32_e64 s[98:99], v0, v156
	v_cndmask_b32_e32 v164, 0, v164, vcc
	v_max3_u32 v157, v157, v162, v164
	v_cndmask_b32_e64 v0, 0, v0, s[98:99]
	v_cmp_ne_u32_e64 s[100:101], v1, v156
	v_cmp_ne_u32_e32 vcc, v2, v156
	v_cmp_ne_u32_e64 s[98:99], v3, v156
	v_cndmask_b32_e64 v1, 0, v1, s[100:101]
	v_max3_u32 v157, v157, v0, v1
	v_cndmask_b32_e32 v2, 0, v2, vcc
	v_cndmask_b32_e64 v3, 0, v3, s[98:99]
	v_max3_u32 v157, v157, v2, v3
	v_mov_b32_e32 v178, v157
	s_nop 1
	v_permlane16_swap_b32 v157, v178
	s_nop 1
	s_waitcnt lgkmcnt(0)
; DI void peer_topk_wave(const Params& p, int item, unsigned* lds  ) {
;     ...
; #pragma unroll
;     for (int rr = 0; rr < 16; ++rr) {
;       unsigned m = 0;
; #pragma unroll
;       for (int i = 0; i < 32; ++i) m = umax(m, kk[i]);
;       m = umax(m, (unsigned)__shfl_xor((int)m, 16));
;       m = umax(m, (unsigned)__shfl_xor((int)m, 32));
;       win[pp][rr] = m;
; #pragma unroll
;       for (int i = 0; i < 32; ++i) kk[i] = (kk[i] == m) ? 0u : kk[i];
;     }
	v_max_u32_e32 v157, v157, v178
	v_mov_b32_e32 v178, v157
	s_nop 1
	v_permlane32_swap_b32 v157, v178
	s_nop 1
	s_waitcnt lgkmcnt(0)
	v_max_u32_e32 v157, v157, v178
	v_cmp_ne_u32_e32 vcc, v4, v157
	v_cmp_ne_u32_e64 s[98:99], v5, v157
	v_cmp_ne_u32_e64 s[100:101], v6, v157
	v_cndmask_b32_e32 v4, 0, v4, vcc
	v_cndmask_b32_e64 v5, 0, v5, s[98:99]
	v_cndmask_b32_e64 v6, 0, v6, s[100:101]
	v_cmp_ne_u32_e32 vcc, v7, v157
	v_cmp_ne_u32_e64 s[98:99], v8, v157
	v_cmp_ne_u32_e64 s[100:101], v9, v157
	v_cndmask_b32_e32 v7, 0, v7, vcc
	v_cndmask_b32_e64 v8, 0, v8, s[98:99]
	v_cndmask_b32_e64 v9, 0, v9, s[100:101]
	v_cmp_ne_u32_e32 vcc, v10, v157
	v_cmp_ne_u32_e64 s[98:99], v11, v157
	v_cmp_ne_u32_e64 s[100:101], v12, v157
	v_cndmask_b32_e32 v10, 0, v10, vcc
	v_cndmask_b32_e64 v11, 0, v11, s[98:99]
	v_cndmask_b32_e64 v12, 0, v12, s[100:101]
	v_cmp_ne_u32_e32 vcc, v13, v157
	v_cmp_ne_u32_e64 s[98:99], v14, v157
	v_cmp_ne_u32_e64 s[100:101], v15, v157
	v_cndmask_b32_e32 v13, 0, v13, vcc
	v_cndmask_b32_e64 v14, 0, v14, s[98:99]
	v_cndmask_b32_e64 v15, 0, v15, s[100:101]
	v_cmp_ne_u32_e32 vcc, v165, v157
	v_cmp_ne_u32_e64 s[98:99], v166, v157
	v_cmp_ne_u32_e64 s[100:101], v167, v157
	v_cndmask_b32_e32 v165, 0, v165, vcc
	v_cndmask_b32_e64 v166, 0, v166, s[98:99]
	v_cndmask_b32_e64 v167, 0, v167, s[100:101]
	v_cmp_ne_u32_e32 vcc, v168, v157
	v_cmp_ne_u32_e64 s[98:99], v169, v157
	v_cmp_ne_u32_e64 s[100:101], v171, v157
	v_cndmask_b32_e32 v168, 0, v168, vcc
	v_cndmask_b32_e64 v169, 0, v169, s[98:99]
	v_cndmask_b32_e64 v171, 0, v171, s[100:101]
	v_cmp_ne_u32_e32 vcc, v172, v157
	v_cmp_ne_u32_e64 s[98:99], v173, v157
	v_cmp_ne_u32_e64 s[100:101], v176, v157
	v_cndmask_b32_e32 v172, 0, v172, vcc
	v_cndmask_b32_e64 v173, 0, v173, s[98:99]
	v_cndmask_b32_e64 v176, 0, v176, s[100:101]
	v_cmp_ne_u32_e32 vcc, v177, v157
	v_cmp_ne_u32_e64 s[98:99], v158, v157
	v_cmp_ne_u32_e64 s[100:101], v159, v157
	v_cndmask_b32_e32 v177, 0, v177, vcc
	v_cndmask_b32_e64 v178, 0, v158, s[98:99]
	v_max_u32_e32 v158, v4, v5
	v_max3_u32 v158, v158, v6, v7
	v_max3_u32 v158, v158, v8, v9
	v_max3_u32 v158, v158, v10, v11
	v_max3_u32 v158, v158, v12, v13
	v_max3_u32 v158, v158, v14, v15
	v_max3_u32 v158, v158, v165, v166
	v_cndmask_b32_e64 v159, 0, v159, s[100:101]
	v_cmp_ne_u32_e32 vcc, v160, v157
	v_max3_u32 v158, v158, v167, v168
	v_max3_u32 v158, v158, v169, v171
	v_cndmask_b32_e32 v160, 0, v160, vcc
	v_cmp_ne_u32_e64 s[98:99], v161, v157
	v_max3_u32 v158, v158, v172, v173
	v_max3_u32 v158, v158, v176, v177
	v_cndmask_b32_e64 v161, 0, v161, s[98:99]
	v_cmp_ne_u32_e64 s[100:101], v162, v157
	v_max3_u32 v158, v158, v178, v159
	v_max3_u32 v158, v158, v160, v161
	v_cndmask_b32_e64 v162, 0, v162, s[100:101]
	v_cmp_ne_u32_e32 vcc, v164, v157
	v_cmp_ne_u32_e64 s[98:99], v0, v157
	v_cmp_ne_u32_e64 s[100:101], v1, v157
	v_cndmask_b32_e32 v164, 0, v164, vcc
	v_max3_u32 v158, v158, v162, v164
	v_cndmask_b32_e64 v0, 0, v0, s[98:99]
	v_cndmask_b32_e64 v1, 0, v1, s[100:101]
	v_cmp_ne_u32_e32 vcc, v2, v157
	v_max3_u32 v158, v158, v0, v1
	v_cmp_ne_u32_e64 s[98:99], v3, v157
	v_cndmask_b32_e32 v2, 0, v2, vcc
	s_nop 0
	v_cndmask_b32_e64 v3, 0, v3, s[98:99]
	v_max3_u32 v158, v158, v2, v3
	v_mov_b32_e32 v179, v158
	s_nop 1
	v_permlane16_swap_b32 v158, v179
	s_nop 1
	s_waitcnt lgkmcnt(0)
	v_max_u32_e32 v158, v158, v179
	v_mov_b32_e32 v179, v158
	s_nop 1
	v_permlane32_swap_b32 v158, v179
	s_nop 1
	s_waitcnt lgkmcnt(0)
	v_max_u32_e32 v158, v158, v179
	v_cmp_ne_u32_e32 vcc, v4, v158
	v_cmp_ne_u32_e64 s[98:99], v5, v158
	v_cmp_ne_u32_e64 s[100:101], v6, v158
	v_cndmask_b32_e32 v4, 0, v4, vcc
	v_cndmask_b32_e64 v5, 0, v5, s[98:99]
	v_cndmask_b32_e64 v6, 0, v6, s[100:101]
	v_cmp_ne_u32_e32 vcc, v7, v158
	v_cmp_ne_u32_e64 s[98:99], v8, v158
	v_cmp_ne_u32_e64 s[100:101], v9, v158
	v_cndmask_b32_e32 v7, 0, v7, vcc
	v_cndmask_b32_e64 v8, 0, v8, s[98:99]
	v_cndmask_b32_e64 v9, 0, v9, s[100:101]
	v_cmp_ne_u32_e32 vcc, v10, v158
	v_cmp_ne_u32_e64 s[98:99], v11, v158
	v_cmp_ne_u32_e64 s[100:101], v12, v158
	v_cndmask_b32_e32 v10, 0, v10, vcc
	v_cndmask_b32_e64 v11, 0, v11, s[98:99]
	v_cndmask_b32_e64 v12, 0, v12, s[100:101]
	v_cmp_ne_u32_e32 vcc, v13, v158
	v_cmp_ne_u32_e64 s[98:99], v14, v158
	v_cmp_ne_u32_e64 s[100:101], v15, v158
	v_cndmask_b32_e32 v13, 0, v13, vcc
	v_cndmask_b32_e64 v14, 0, v14, s[98:99]
	v_cndmask_b32_e64 v15, 0, v15, s[100:101]
	v_cmp_ne_u32_e32 vcc, v165, v158
	v_cmp_ne_u32_e64 s[98:99], v166, v158
	v_cmp_ne_u32_e64 s[100:101], v167, v158
	v_cndmask_b32_e32 v165, 0, v165, vcc
	v_cndmask_b32_e64 v166, 0, v166, s[98:99]
	v_cndmask_b32_e64 v167, 0, v167, s[100:101]
	v_cmp_ne_u32_e32 vcc, v168, v158
	v_cmp_ne_u32_e64 s[98:99], v169, v158
	v_cmp_ne_u32_e64 s[100:101], v171, v158
	v_cndmask_b32_e32 v168, 0, v168, vcc
	v_cndmask_b32_e64 v169, 0, v169, s[98:99]
	v_cndmask_b32_e64 v171, 0, v171, s[100:101]
	v_cmp_ne_u32_e32 vcc, v172, v158
	v_cmp_ne_u32_e64 s[98:99], v173, v158
	v_cmp_ne_u32_e64 s[100:101], v176, v158
	v_cndmask_b32_e32 v172, 0, v172, vcc
	v_cndmask_b32_e64 v173, 0, v173, s[98:99]
	v_cndmask_b32_e64 v176, 0, v176, s[100:101]
	v_cmp_ne_u32_e32 vcc, v177, v158
	v_cmp_ne_u32_e64 s[98:99], v178, v158
	v_cmp_ne_u32_e64 s[100:101], v159, v158
	v_cndmask_b32_e32 v177, 0, v177, vcc
	v_cndmask_b32_e64 v178, 0, v178, s[98:99]
	v_cndmask_b32_e64 v179, 0, v159, s[100:101]
	v_max_u32_e32 v159, v4, v5
	v_max3_u32 v159, v159, v6, v7
	v_max3_u32 v159, v159, v8, v9
	v_max3_u32 v159, v159, v10, v11
	v_max3_u32 v159, v159, v12, v13
	v_max3_u32 v159, v159, v14, v15
	v_cmp_ne_u32_e32 vcc, v160, v158
	v_max3_u32 v159, v159, v165, v166
	v_max3_u32 v159, v159, v167, v168
	v_cndmask_b32_e32 v160, 0, v160, vcc
	v_cmp_ne_u32_e64 s[98:99], v161, v158
	v_max3_u32 v159, v159, v169, v171
	v_max3_u32 v159, v159, v172, v173
	v_cndmask_b32_e64 v161, 0, v161, s[98:99]
	v_cmp_ne_u32_e64 s[100:101], v162, v158
	v_max3_u32 v159, v159, v176, v177
	v_max3_u32 v159, v159, v178, v179
	v_cndmask_b32_e64 v162, 0, v162, s[100:101]
	v_cmp_ne_u32_e32 vcc, v164, v158
	v_max3_u32 v159, v159, v160, v161
	v_cmp_ne_u32_e64 s[98:99], v0, v158
	v_cndmask_b32_e32 v164, 0, v164, vcc
	v_max3_u32 v159, v159, v162, v164
	v_cndmask_b32_e64 v0, 0, v0, s[98:99]
	v_cmp_ne_u32_e64 s[100:101], v1, v158
	v_cmp_ne_u32_e32 vcc, v2, v158
	v_cmp_ne_u32_e64 s[98:99], v3, v158
	v_cndmask_b32_e64 v1, 0, v1, s[100:101]
	v_max3_u32 v159, v159, v0, v1
	v_cndmask_b32_e32 v2, 0, v2, vcc
	v_cndmask_b32_e64 v3, 0, v3, s[98:99]
	v_max3_u32 v159, v159, v2, v3
	v_mov_b32_e32 v180, v159
	s_nop 1
	v_permlane16_swap_b32 v159, v180
	s_nop 1
	s_waitcnt lgkmcnt(0)
; DI void peer_topk_wave(const Params& p, int item, unsigned* lds  ) {
;     ...
; #pragma unroll
;     for (int rr = 0; rr < 16; ++rr) {
;       unsigned m = 0;
; #pragma unroll
;       for (int i = 0; i < 32; ++i) m = umax(m, kk[i]);
;       m = umax(m, (unsigned)__shfl_xor((int)m, 16));
;       m = umax(m, (unsigned)__shfl_xor((int)m, 32));
;       win[pp][rr] = m;
; #pragma unroll
;       for (int i = 0; i < 32; ++i) kk[i] = (kk[i] == m) ? 0u : kk[i];
;     }
	v_max_u32_e32 v159, v159, v180
	v_mov_b32_e32 v180, v159
	s_nop 1
	v_permlane32_swap_b32 v159, v180
	s_nop 1
	s_waitcnt lgkmcnt(0)
	v_max_u32_e32 v159, v159, v180
	v_cmp_ne_u32_e32 vcc, v4, v159
	v_cmp_ne_u32_e64 s[98:99], v5, v159
	v_cmp_ne_u32_e64 s[100:101], v6, v159
	v_cndmask_b32_e32 v4, 0, v4, vcc
	v_cndmask_b32_e64 v5, 0, v5, s[98:99]
	v_cndmask_b32_e64 v6, 0, v6, s[100:101]
	v_cmp_ne_u32_e32 vcc, v7, v159
	v_cmp_ne_u32_e64 s[98:99], v8, v159
	v_cmp_ne_u32_e64 s[100:101], v9, v159
	v_cndmask_b32_e32 v7, 0, v7, vcc
	v_cndmask_b32_e64 v8, 0, v8, s[98:99]
	v_cndmask_b32_e64 v9, 0, v9, s[100:101]
	v_cmp_ne_u32_e32 vcc, v10, v159
	v_cmp_ne_u32_e64 s[98:99], v11, v159
	v_cmp_ne_u32_e64 s[100:101], v12, v159
	v_cndmask_b32_e32 v10, 0, v10, vcc
	v_cndmask_b32_e64 v11, 0, v11, s[98:99]
	v_cndmask_b32_e64 v12, 0, v12, s[100:101]
	v_cmp_ne_u32_e32 vcc, v13, v159
	v_cmp_ne_u32_e64 s[98:99], v14, v159
	v_cmp_ne_u32_e64 s[100:101], v15, v159
	v_cndmask_b32_e32 v13, 0, v13, vcc
	v_cndmask_b32_e64 v14, 0, v14, s[98:99]
	v_cndmask_b32_e64 v15, 0, v15, s[100:101]
	v_cmp_ne_u32_e32 vcc, v165, v159
	v_cmp_ne_u32_e64 s[98:99], v166, v159
	v_cmp_ne_u32_e64 s[100:101], v167, v159
	v_cndmask_b32_e32 v165, 0, v165, vcc
	v_cndmask_b32_e64 v166, 0, v166, s[98:99]
	v_cndmask_b32_e64 v167, 0, v167, s[100:101]
	v_cmp_ne_u32_e32 vcc, v168, v159
	v_cmp_ne_u32_e64 s[98:99], v169, v159
	v_cmp_ne_u32_e64 s[100:101], v171, v159
	v_cndmask_b32_e32 v168, 0, v168, vcc
	v_cndmask_b32_e64 v169, 0, v169, s[98:99]
	v_cndmask_b32_e64 v171, 0, v171, s[100:101]
	v_cmp_ne_u32_e32 vcc, v172, v159
	v_cmp_ne_u32_e64 s[98:99], v173, v159
	v_cmp_ne_u32_e64 s[100:101], v176, v159
	v_cndmask_b32_e32 v172, 0, v172, vcc
	v_cndmask_b32_e64 v173, 0, v173, s[98:99]
	v_cndmask_b32_e64 v176, 0, v176, s[100:101]
	v_cmp_ne_u32_e32 vcc, v177, v159
	v_cmp_ne_u32_e64 s[98:99], v178, v159
	v_cmp_ne_u32_e64 s[100:101], v179, v159
	v_cndmask_b32_e32 v177, 0, v177, vcc
	v_cndmask_b32_e64 v178, 0, v178, s[98:99]
	v_cndmask_b32_e64 v179, 0, v179, s[100:101]
	v_cmp_ne_u32_e32 vcc, v160, v159
	v_cmp_ne_u32_e64 s[98:99], v161, v159
	v_cmp_ne_u32_e64 s[100:101], v162, v159
	v_cndmask_b32_e32 v180, 0, v160, vcc
	v_max_u32_e32 v160, v4, v5
	v_max3_u32 v160, v160, v6, v7
	v_max3_u32 v160, v160, v8, v9
	v_max3_u32 v160, v160, v10, v11
	v_max3_u32 v160, v160, v12, v13
	v_max3_u32 v160, v160, v14, v15
	v_max3_u32 v160, v160, v165, v166
	v_max3_u32 v160, v160, v167, v168
	v_max3_u32 v160, v160, v169, v171
	v_cndmask_b32_e64 v161, 0, v161, s[98:99]
	v_max3_u32 v160, v160, v172, v173
	v_max3_u32 v160, v160, v176, v177
	v_cndmask_b32_e64 v162, 0, v162, s[100:101]
	v_cmp_ne_u32_e32 vcc, v164, v159
	v_max3_u32 v160, v160, v178, v179
	v_max3_u32 v160, v160, v180, v161
	v_cndmask_b32_e32 v164, 0, v164, vcc
	v_cmp_ne_u32_e64 s[98:99], v0, v159
	v_max3_u32 v160, v160, v162, v164
	v_cmp_ne_u32_e64 s[100:101], v1, v159
	v_cndmask_b32_e64 v0, 0, v0, s[98:99]
	v_cmp_ne_u32_e32 vcc, v2, v159
	v_cndmask_b32_e64 v1, 0, v1, s[100:101]
	v_max3_u32 v160, v160, v0, v1
	v_cndmask_b32_e32 v2, 0, v2, vcc
	v_cmp_ne_u32_e64 s[98:99], v3, v159
	s_nop 0
	s_nop 0
	v_cndmask_b32_e64 v3, 0, v3, s[98:99]
	v_max3_u32 v160, v160, v2, v3
	v_mov_b32_e32 v181, v160
	s_nop 1
	v_permlane16_swap_b32 v160, v181
	s_nop 1
	s_waitcnt lgkmcnt(0)
	v_max_u32_e32 v160, v160, v181
	v_mov_b32_e32 v181, v160
	s_nop 1
	v_permlane32_swap_b32 v160, v181
	s_nop 1
	s_waitcnt lgkmcnt(0)
	v_max_u32_e32 v160, v160, v181
	v_cmp_ne_u32_e64 s[0:1], v5, v160
	v_cmp_eq_u32_e32 vcc, v4, v160
	v_cmp_eq_u32_e64 s[2:3], v7, v160
	v_cndmask_b32_e64 v5, 0, v5, s[0:1]
	v_max_u32_e32 v4, v4, v5
	v_cndmask_b32_e32 v4, v4, v5, vcc
	v_cmp_eq_u32_e64 s[0:1], v6, v160
	v_max_u32_e32 v5, v4, v6
	v_cmp_eq_u32_e64 s[14:15], v8, v160
	v_cndmask_b32_e64 v4, v5, v4, s[0:1]
	v_max_u32_e32 v5, v4, v7
	v_cndmask_b32_e64 v4, v5, v4, s[2:3]
	v_max_u32_e32 v5, v4, v8
	v_cndmask_b32_e64 v4, v5, v4, s[14:15]
	v_cmp_eq_u32_e64 s[16:17], v9, v160
	v_max_u32_e32 v5, v4, v9
	v_cmp_eq_u32_e64 s[18:19], v10, v160
	v_cndmask_b32_e64 v4, v5, v4, s[16:17]
	v_max_u32_e32 v5, v4, v10
	v_cndmask_b32_e64 v4, v5, v4, s[18:19]
	v_cmp_eq_u32_e64 s[20:21], v11, v160
	v_max_u32_e32 v5, v4, v11
	v_cmp_eq_u32_e64 s[22:23], v12, v160
	v_cndmask_b32_e64 v4, v5, v4, s[20:21]
	v_max_u32_e32 v5, v4, v12
	v_cndmask_b32_e64 v4, v5, v4, s[22:23]
	v_cmp_eq_u32_e64 s[24:25], v13, v160
	v_max_u32_e32 v5, v4, v13
	v_cmp_eq_u32_e64 s[26:27], v14, v160
	v_cndmask_b32_e64 v4, v5, v4, s[24:25]
	v_max_u32_e32 v5, v4, v14
	v_cndmask_b32_e64 v4, v5, v4, s[26:27]
	v_cmp_eq_u32_e64 s[28:29], v15, v160
	v_max_u32_e32 v5, v4, v15
	v_cmp_eq_u32_e64 s[30:31], v165, v160
	v_cndmask_b32_e64 v4, v5, v4, s[28:29]
	v_max_u32_e32 v5, v4, v165
	v_cndmask_b32_e64 v4, v5, v4, s[30:31]
	v_cmp_eq_u32_e64 s[34:35], v166, v160
	v_max_u32_e32 v5, v4, v166
	v_cmp_eq_u32_e64 s[36:37], v167, v160
	v_cndmask_b32_e64 v4, v5, v4, s[34:35]
	v_max_u32_e32 v5, v4, v167
	v_cndmask_b32_e64 v4, v5, v4, s[36:37]
	v_cmp_eq_u32_e64 s[38:39], v168, v160
	v_max_u32_e32 v5, v4, v168
	v_cmp_eq_u32_e64 s[40:41], v169, v160
	v_cndmask_b32_e64 v4, v5, v4, s[38:39]
	v_max_u32_e32 v5, v4, v169
	v_cndmask_b32_e64 v4, v5, v4, s[40:41]
	v_cmp_eq_u32_e64 s[42:43], v171, v160
	v_max_u32_e32 v5, v4, v171
	v_cmp_eq_u32_e64 s[44:45], v172, v160
	v_cndmask_b32_e64 v4, v5, v4, s[42:43]
	v_max_u32_e32 v5, v4, v172
	v_cndmask_b32_e64 v4, v5, v4, s[44:45]
	v_cmp_eq_u32_e64 s[46:47], v173, v160
	v_max_u32_e32 v5, v4, v173
	v_cmp_eq_u32_e64 s[48:49], v176, v160
	v_cndmask_b32_e64 v4, v5, v4, s[46:47]
	v_max_u32_e32 v5, v4, v176
	v_cndmask_b32_e64 v4, v5, v4, s[48:49]
	v_cmp_eq_u32_e64 s[50:51], v177, v160
	v_max_u32_e32 v5, v4, v177
	v_cmp_eq_u32_e64 s[52:53], v178, v160
	v_cndmask_b32_e64 v4, v5, v4, s[50:51]
	v_max_u32_e32 v5, v4, v178
	v_cndmask_b32_e64 v4, v5, v4, s[52:53]
	v_cmp_eq_u32_e64 s[54:55], v179, v160
	v_max_u32_e32 v5, v4, v179
	v_cmp_eq_u32_e64 s[56:57], v180, v160
	v_cndmask_b32_e64 v4, v5, v4, s[54:55]
	v_max_u32_e32 v5, v4, v180
	v_cndmask_b32_e64 v4, v5, v4, s[56:57]
	v_cmp_eq_u32_e64 s[58:59], v161, v160
	v_max_u32_e32 v5, v4, v161
	v_cmp_eq_u32_e64 s[60:61], v162, v160
	v_cndmask_b32_e64 v4, v5, v4, s[58:59]
	v_max_u32_e32 v5, v4, v162
	v_cndmask_b32_e64 v4, v5, v4, s[60:61]
	v_cmp_eq_u32_e64 s[62:63], v164, v160
	v_max_u32_e32 v5, v4, v164
	v_cmp_eq_u32_e64 s[64:65], v0, v160
	v_cndmask_b32_e64 v4, v5, v4, s[62:63]
	v_max_u32_e32 v0, v4, v0
	v_cndmask_b32_e64 v0, v0, v4, s[64:65]
	v_cmp_eq_u32_e64 s[66:67], v1, v160
	v_max_u32_e32 v1, v0, v1
	v_cmp_eq_u32_e64 s[68:69], v2, v160
	v_cndmask_b32_e64 v0, v1, v0, s[66:67]
	v_max_u32_e32 v1, v0, v2
	v_cndmask_b32_e64 v0, v1, v0, s[68:69]
	v_cmp_eq_u32_e64 s[70:71], v3, v160
	v_max_u32_e32 v1, v0, v3
	v_lshl_add_u64 v[172:173], v[86:87], 0, v[24:25]
	v_cndmask_b32_e64 v0, v1, v0, s[70:71]
	v_mov_b32_e32 v1, v0
	s_nop 1
	v_permlane16_swap_b32 v0, v1
	s_nop 1
	s_waitcnt lgkmcnt(0)
	v_max_u32_e32 v161, v0, v1
	v_lshl_add_u64 v[236:237], v[88:89], 0, s[90:91]
	s_cmp_lg_u32 s88, 0
	s_cbranch_scc1 .Lp10q_mov1
; DI void peer_topk_wave(const Params& p, int item, unsigned* lds  ) {
;     ...
;     bf16x8 qf[4];
; #pragma unroll
;     for (int ks = 0; ks < 4; ++ks) qf[ks] = *(const bf16x8*)&p.pq[(size_t)(row0 + r) * 2048 + h * 256 + pp * 128 + ks * 32 + kg * 8];
	global_load_dwordx4 v[12:15], v[88:89], off offset:256
	global_load_dwordx4 v[8:11], v[88:89], off offset:320
	global_load_dwordx4 v[4:7], v[88:89], off offset:384
	global_load_dwordx4 v[0:3], v[88:89], off offset:448
	s_branch .Lp10q_done1

; #define MFMA(a, b, c) __builtin_amdgcn_mfma_f32_16x16x32_bf16((a), (b), (c), 0, 0, 0)
; DI unsigned ordf(float f) { unsigned u = __float_as_uint(f); return (u & 0x80000000u) ? ~u : (u | 0x80000000u); }
; DI void peer_topk_wave(const Params& p, int item, unsigned* lds  ) {
;     ...
; #pragma unroll
;     for (int mt = 0; mt < 8; ++mt) {
;       f32x4 a = (f32x4){0.f, 0.f, 0.f, 0.f};
; #pragma unroll
;       for (int ks = 0; ks < 4; ++ks) {
;         bf16x8 kf = *(const bf16x8*)&sk[(mt * 16 + r) * 128 + ks * 32 + kg * 8];
;         a = MFMA(kf, qf[ks], a);
;       }
; #pragma unroll
;       for (int j = 0; j < 4; ++j) kk[mt * 4 + j] = (ordf(a[j]) & ~127u) | (unsigned)(mt * 16 + kg * 4 + j);
;     }
.Lp10q_done1:
	ds_bpermute_b32 v162, v112, v161
	v_readfirstlane_b32 s0, v86
	v_readfirstlane_b32 s1, v87
	s_nop 3
	s_add_u32 s0, s0, 0x8000
	s_addc_u32 s1, s1, 0
	s_add_u32 s2, s0, 0x0
	s_addc_u32 s3, s1, 0
	ds_read_b128 v[24:27], v241 offset:34816
	ds_read_b128 v[28:31], v241 offset:34880
	ds_read_b128 v[32:35], v241 offset:34944
	ds_read_b128 v[36:39], v241 offset:35008
	s_add_u32 s2, s0, 0x1000
	s_addc_u32 s3, s1, 0
	ds_read_b128 v[40:43], v241 offset:39168
	ds_read_b128 v[44:47], v241 offset:39232
	ds_read_b128 v[48:51], v241 offset:39296
	ds_read_b128 v[52:55], v241 offset:39360
	s_add_u32 s2, s0, 0x2000
	s_addc_u32 s3, s1, 0
	ds_read_b128 v[56:59], v241 offset:43520
	ds_read_b128 v[60:63], v241 offset:43584
	ds_read_b128 v[64:67], v241 offset:43648
	ds_read_b128 v[68:71], v241 offset:43712
	s_add_u32 s2, s0, 0x3000
	s_addc_u32 s3, s1, 0
	ds_read_b128 v[72:75], v241 offset:47872
	ds_read_b128 v[76:79], v241 offset:47936
	ds_read_b128 v[80:83], v241 offset:48000
	s_waitcnt vmcnt(0) lgkmcnt(11)
	v_mfma_f32_16x16x32_bf16 v[190:193], v[24:27], v[12:15], 0
	v_mfma_f32_16x16x32_bf16 v[190:193], v[28:31], v[8:11], v[190:193]
	v_mfma_f32_16x16x32_bf16 v[190:193], v[32:35], v[4:7], v[190:193]
	v_mfma_f32_16x16x32_bf16 v[190:193], v[36:39], v[0:3], v[190:193]
	ds_read_b128 v[24:27], v241 offset:48064
	s_add_u32 s2, s0, 0x4000
	s_addc_u32 s3, s1, 0
	ds_read_b128 v[28:31], v241 offset:52224
	ds_read_b128 v[32:35], v241 offset:52288
	ds_read_b128 v[36:39], v241 offset:52352
	s_waitcnt lgkmcnt(11)
	v_mfma_f32_16x16x32_bf16 v[198:201], v[40:43], v[12:15], 0
	v_mfma_f32_16x16x32_bf16 v[198:201], v[44:47], v[8:11], v[198:201]
	v_mfma_f32_16x16x32_bf16 v[198:201], v[48:51], v[4:7], v[198:201]
	v_mfma_f32_16x16x32_bf16 v[198:201], v[52:55], v[0:3], v[198:201]
	ds_read_b128 v[40:43], v241 offset:52416
	s_add_u32 s2, s0, 0x5000
	s_addc_u32 s3, s1, 0
	global_load_dwordx4 v[44:47], v20, s[2:3]
	global_load_dwordx4 v[48:51], v20, s[2:3] offset:64
	global_load_dwordx4 v[52:55], v20, s[2:3] offset:128
	s_nop 7
	s_nop 3
	v_ashrrev_i32_e32 v197, 31, v190
	v_or_b32_e32 v197, 0x80000000, v197
	v_xor_b32_e32 v197, v190, v197
	v_and_or_b32 v88, v197, s80, v170
	v_ashrrev_i32_e32 v202, 31, v191
	v_or_b32_e32 v202, 0x80000000, v202
	v_xor_b32_e32 v202, v191, v202
	v_and_or_b32 v89, v202, s80, v113
	v_ashrrev_i32_e32 v197, 31, v192
	v_or_b32_e32 v197, 0x80000000, v197
	v_xor_b32_e32 v197, v192, v197
	v_and_or_b32 v164, v197, s80, v114
	v_ashrrev_i32_e32 v202, 31, v193
	v_or_b32_e32 v202, 0x80000000, v202
	v_xor_b32_e32 v202, v193, v202
	v_and_or_b32 v165, v202, s80, v115
	s_waitcnt lgkmcnt(8)
	v_mfma_f32_16x16x32_bf16 v[190:193], v[56:59], v[12:15], 0
	v_mfma_f32_16x16x32_bf16 v[190:193], v[60:63], v[8:11], v[190:193]
	v_mfma_f32_16x16x32_bf16 v[190:193], v[64:67], v[4:7], v[190:193]
	v_mfma_f32_16x16x32_bf16 v[190:193], v[68:71], v[0:3], v[190:193]
	global_load_dwordx4 v[56:59], v20, s[2:3] offset:192
	s_add_u32 s2, s0, 0x6000
	s_addc_u32 s3, s1, 0
	global_load_dwordx4 v[60:63], v20, s[2:3]
	global_load_dwordx4 v[64:67], v20, s[2:3] offset:64
	global_load_dwordx4 v[68:71], v20, s[2:3] offset:128
	s_nop 7
	s_nop 3
	v_ashrrev_i32_e32 v197, 31, v198
	v_or_b32_e32 v197, 0x80000000, v197
	v_xor_b32_e32 v197, v198, v197
	v_and_or_b32 v166, v197, s80, v90
	v_ashrrev_i32_e32 v202, 31, v199
	v_or_b32_e32 v202, 0x80000000, v202
	v_xor_b32_e32 v202, v199, v202
	v_and_or_b32 v167, v202, s80, v116
	v_ashrrev_i32_e32 v197, 31, v200
	v_or_b32_e32 v197, 0x80000000, v197
	v_xor_b32_e32 v197, v200, v197
	v_and_or_b32 v168, v197, s80, v117
	v_ashrrev_i32_e32 v202, 31, v201
	v_or_b32_e32 v202, 0x80000000, v202
	v_xor_b32_e32 v202, v201, v202
	v_and_or_b32 v169, v202, s80, v118
	s_waitcnt lgkmcnt(4)
	v_mfma_f32_16x16x32_bf16 v[198:201], v[72:75], v[12:15], 0
	v_mfma_f32_16x16x32_bf16 v[198:201], v[76:79], v[8:11], v[198:201]
	v_mfma_f32_16x16x32_bf16 v[198:201], v[80:83], v[4:7], v[198:201]
	v_mfma_f32_16x16x32_bf16 v[198:201], v[24:27], v[0:3], v[198:201]
	global_load_dwordx4 v[72:75], v20, s[2:3] offset:192
	s_add_u32 s2, s0, 0x7000
	s_addc_u32 s3, s1, 0
	global_load_dwordx4 v[76:79], v20, s[2:3]
	global_load_dwordx4 v[80:83], v20, s[2:3] offset:64
	global_load_dwordx4 v[24:27], v20, s[2:3] offset:128
	s_nop 7
	s_nop 3
	v_ashrrev_i32_e32 v197, 31, v190
	v_or_b32_e32 v197, 0x80000000, v197
	v_xor_b32_e32 v197, v190, v197
	v_and_or_b32 v171, v197, s80, v91
	v_ashrrev_i32_e32 v202, 31, v191
	v_or_b32_e32 v202, 0x80000000, v202
	v_xor_b32_e32 v202, v191, v202
	v_and_or_b32 v172, v202, s80, v119
	v_ashrrev_i32_e32 v197, 31, v192
	v_or_b32_e32 v197, 0x80000000, v197
	v_xor_b32_e32 v197, v192, v197
	v_and_or_b32 v173, v197, s80, v120
	v_ashrrev_i32_e32 v202, 31, v193
	v_or_b32_e32 v202, 0x80000000, v202
	v_xor_b32_e32 v202, v193, v202
	v_and_or_b32 v176, v202, s80, v121
	s_waitcnt lgkmcnt(0)
	v_mfma_f32_16x16x32_bf16 v[190:193], v[28:31], v[12:15], 0
	v_mfma_f32_16x16x32_bf16 v[190:193], v[32:35], v[8:11], v[190:193]
	v_mfma_f32_16x16x32_bf16 v[190:193], v[36:39], v[4:7], v[190:193]
	v_mfma_f32_16x16x32_bf16 v[190:193], v[40:43], v[0:3], v[190:193]
	global_load_dwordx4 v[28:31], v20, s[2:3] offset:192
	s_nop 7
	s_nop 3
	v_ashrrev_i32_e32 v197, 31, v198
	v_or_b32_e32 v197, 0x80000000, v197
	v_xor_b32_e32 v197, v198, v197
	v_and_or_b32 v177, v197, s80, v92
	v_ashrrev_i32_e32 v202, 31, v199
	v_or_b32_e32 v202, 0x80000000, v202
	v_xor_b32_e32 v202, v199, v202
	v_and_or_b32 v178, v202, s80, v122
	v_ashrrev_i32_e32 v197, 31, v200
	v_or_b32_e32 v197, 0x80000000, v197
	v_xor_b32_e32 v197, v200, v197
	v_and_or_b32 v179, v197, s80, v123
	v_ashrrev_i32_e32 v202, 31, v201
	v_or_b32_e32 v202, 0x80000000, v202
	v_xor_b32_e32 v202, v201, v202
	v_and_or_b32 v180, v202, s80, v124
	s_waitcnt vmcnt(8)
; #define MFMA(a, b, c) __builtin_amdgcn_mfma_f32_16x16x32_bf16((a), (b), (c), 0, 0, 0)
; DI unsigned ordf(float f) { unsigned u = __float_as_uint(f); return (u & 0x80000000u) ? ~u : (u | 0x80000000u); }
; DI void peer_topk_wave(const Params& p, int item, unsigned* lds  ) {
;     ...
; #pragma unroll
;     for (int mt = 0; mt < 8; ++mt) {
;       f32x4 a = (f32x4){0.f, 0.f, 0.f, 0.f};
; #pragma unroll
;       for (int ks = 0; ks < 4; ++ks) {
;         bf16x8 kf = *(const bf16x8*)&sk[(mt * 16 + r) * 128 + ks * 32 + kg * 8];
;         a = MFMA(kf, qf[ks], a);
;       }
; #pragma unroll
;       for (int j = 0; j < 4; ++j) kk[mt * 4 + j] = (ordf(a[j]) & ~127u) | (unsigned)(mt * 16 + kg * 4 + j);
;     }
; #pragma unroll
;     for (int rr = 0; rr < 16; ++rr) {
;       unsigned m = 0;
; #pragma unroll
;       for (int i = 0; i < 32; ++i) m = umax(m, kk[i]);
;       m = umax(m, (unsigned)__shfl_xor((int)m, 16));
;       m = umax(m, (unsigned)__shfl_xor((int)m, 32));
	v_mfma_f32_16x16x32_bf16 v[198:201], v[44:47], v[12:15], 0
	v_mfma_f32_16x16x32_bf16 v[198:201], v[48:51], v[8:11], v[198:201]
	v_mfma_f32_16x16x32_bf16 v[198:201], v[52:55], v[4:7], v[198:201]
	v_mfma_f32_16x16x32_bf16 v[198:201], v[56:59], v[0:3], v[198:201]
	s_nop 7
	s_nop 3
	v_ashrrev_i32_e32 v197, 31, v190
	v_or_b32_e32 v197, 0x80000000, v197
	v_xor_b32_e32 v197, v190, v197
	v_and_or_b32 v181, v197, s80, v93
	v_ashrrev_i32_e32 v202, 31, v191
	v_or_b32_e32 v202, 0x80000000, v202
	v_xor_b32_e32 v202, v191, v202
	v_and_or_b32 v182, v202, s80, v125
	v_ashrrev_i32_e32 v197, 31, v192
	v_or_b32_e32 v197, 0x80000000, v197
	v_xor_b32_e32 v197, v192, v197
	v_and_or_b32 v183, v197, s80, v126
	v_ashrrev_i32_e32 v202, 31, v193
	v_or_b32_e32 v202, 0x80000000, v202
	v_xor_b32_e32 v202, v193, v202
	v_and_or_b32 v184, v202, s80, v127
	s_waitcnt vmcnt(4)
	v_mfma_f32_16x16x32_bf16 v[190:193], v[60:63], v[12:15], 0
	v_mfma_f32_16x16x32_bf16 v[190:193], v[64:67], v[8:11], v[190:193]
	v_mfma_f32_16x16x32_bf16 v[190:193], v[68:71], v[4:7], v[190:193]
	v_mfma_f32_16x16x32_bf16 v[190:193], v[72:75], v[0:3], v[190:193]
	s_nop 7
	s_nop 3
	v_ashrrev_i32_e32 v197, 31, v198
	v_or_b32_e32 v197, 0x80000000, v197
	v_xor_b32_e32 v197, v198, v197
	v_and_or_b32 v185, v197, s80, v94
	v_ashrrev_i32_e32 v202, 31, v199
	v_or_b32_e32 v202, 0x80000000, v202
	v_xor_b32_e32 v202, v199, v202
	v_and_or_b32 v186, v202, s80, v129
	v_ashrrev_i32_e32 v197, 31, v200
	v_or_b32_e32 v197, 0x80000000, v197
	v_xor_b32_e32 v197, v200, v197
	v_and_or_b32 v187, v197, s80, v130
	v_ashrrev_i32_e32 v202, 31, v201
	v_or_b32_e32 v202, 0x80000000, v202
	v_xor_b32_e32 v202, v201, v202
	v_and_or_b32 v188, v202, s80, v131
	s_waitcnt vmcnt(0)
	v_mfma_f32_16x16x32_bf16 v[198:201], v[76:79], v[12:15], 0
	v_mfma_f32_16x16x32_bf16 v[198:201], v[80:83], v[8:11], v[198:201]
	v_mfma_f32_16x16x32_bf16 v[198:201], v[24:27], v[4:7], v[198:201]
	v_mfma_f32_16x16x32_bf16 v[198:201], v[28:31], v[0:3], v[198:201]
	s_nop 7
	s_nop 3
	v_ashrrev_i32_e32 v197, 31, v190
	v_or_b32_e32 v197, 0x80000000, v197
	v_xor_b32_e32 v197, v190, v197
	v_and_or_b32 v189, v197, s80, v95
	v_ashrrev_i32_e32 v202, 31, v191
	v_or_b32_e32 v202, 0x80000000, v202
	v_xor_b32_e32 v202, v191, v202
	v_and_or_b32 v194, v202, s80, v135
	v_ashrrev_i32_e32 v197, 31, v192
	v_or_b32_e32 v197, 0x80000000, v197
	v_xor_b32_e32 v197, v192, v197
	v_and_or_b32 v195, v197, s80, v136
	v_ashrrev_i32_e32 v202, 31, v193
	v_or_b32_e32 v202, 0x80000000, v202
	v_xor_b32_e32 v202, v193, v202
	v_and_or_b32 v196, v202, s80, v137
	s_nop 7
	s_nop 3
	v_ashrrev_i32_e32 v197, 31, v198
	v_or_b32_e32 v197, 0x80000000, v197
	v_xor_b32_e32 v197, v198, v197
	v_and_or_b32 v4, v197, s80, v96
	v_ashrrev_i32_e32 v202, 31, v199
	v_or_b32_e32 v202, 0x80000000, v202
	v_xor_b32_e32 v202, v199, v202
	v_and_or_b32 v1, v202, s80, v138
	v_ashrrev_i32_e32 v197, 31, v200
	v_or_b32_e32 v197, 0x80000000, v197
	v_xor_b32_e32 v197, v200, v197
	v_and_or_b32 v2, v197, s80, v139
	v_ashrrev_i32_e32 v202, 31, v201
	v_or_b32_e32 v202, 0x80000000, v202
	v_xor_b32_e32 v202, v201, v202
	v_and_or_b32 v3, v202, s80, v140
	global_load_dwordx4 v[204:207], v[236:237], off
	global_load_dwordx4 v[208:211], v[236:237], off offset:64
	global_load_dwordx4 v[212:215], v[236:237], off offset:128
	global_load_dwordx4 v[216:219], v[236:237], off offset:192
	global_load_dwordx4 v[220:223], v[236:237], off offset:256
	global_load_dwordx4 v[224:227], v[236:237], off offset:320
	global_load_dwordx4 v[228:231], v[236:237], off offset:384
	global_load_dwordx4 v[232:235], v[236:237], off offset:448
	s_mov_b32 s88, 1
	v_max_u32_e32 v0, v88, v89
	v_max3_u32 v0, v0, v164, v165
	v_max3_u32 v0, v0, v166, v167
	v_max3_u32 v0, v0, v168, v169
	v_max3_u32 v0, v0, v171, v172
	v_max3_u32 v0, v0, v173, v176
	v_max3_u32 v0, v0, v177, v178
	v_max3_u32 v0, v0, v179, v180
	v_max3_u32 v0, v0, v181, v182
	v_max3_u32 v0, v0, v183, v184
	v_max3_u32 v0, v0, v185, v186
	v_max3_u32 v0, v0, v187, v188
	v_max3_u32 v0, v0, v189, v194
	v_max3_u32 v0, v0, v195, v196
	v_max3_u32 v0, v0, v4, v1
	v_max3_u32 v0, v0, v2, v3
	v_mov_b32_e32 v5, v0
	s_nop 1
	v_permlane16_swap_b32 v0, v5
	s_nop 1
	s_waitcnt lgkmcnt(0)
	v_max_u32_e32 v0, v0, v5
	v_mov_b32_e32 v5, v0
	s_nop 1
	v_permlane32_swap_b32 v0, v5
	s_nop 1
	s_waitcnt lgkmcnt(0)
; DI void peer_topk_wave(const Params& p, int item, unsigned* lds  ) {
;     ...
; #pragma unroll
;     for (int rr = 0; rr < 16; ++rr) {
;       unsigned m = 0;
; #pragma unroll
;       for (int i = 0; i < 32; ++i) m = umax(m, kk[i]);
;       m = umax(m, (unsigned)__shfl_xor((int)m, 16));
;       m = umax(m, (unsigned)__shfl_xor((int)m, 32));
;       win[pp][rr] = m;
; #pragma unroll
;       for (int i = 0; i < 32; ++i) kk[i] = (kk[i] == m) ? 0u : kk[i];
;     }
	v_max_u32_e32 v0, v0, v5
	v_cmp_ne_u32_e32 vcc, v88, v0
	v_cmp_ne_u32_e64 s[98:99], v89, v0
	v_cmp_ne_u32_e64 s[100:101], v164, v0
	v_cndmask_b32_e32 v5, 0, v88, vcc
	v_cndmask_b32_e64 v6, 0, v89, s[98:99]
	v_cndmask_b32_e64 v7, 0, v164, s[100:101]
	v_cmp_ne_u32_e32 vcc, v165, v0
	v_cmp_ne_u32_e64 s[98:99], v166, v0
	v_cmp_ne_u32_e64 s[100:101], v167, v0
	v_cndmask_b32_e32 v8, 0, v165, vcc
	v_cndmask_b32_e64 v9, 0, v166, s[98:99]
	v_cndmask_b32_e64 v10, 0, v167, s[100:101]
	v_cmp_ne_u32_e32 vcc, v168, v0
	v_cmp_ne_u32_e64 s[98:99], v169, v0
	v_cmp_ne_u32_e64 s[100:101], v171, v0
	v_cndmask_b32_e32 v11, 0, v168, vcc
	v_cndmask_b32_e64 v12, 0, v169, s[98:99]
	v_cndmask_b32_e64 v13, 0, v171, s[100:101]
	v_cmp_ne_u32_e32 vcc, v172, v0
	v_cmp_ne_u32_e64 s[98:99], v173, v0
	v_cmp_ne_u32_e64 s[100:101], v176, v0
	v_cndmask_b32_e32 v14, 0, v172, vcc
	v_cndmask_b32_e64 v15, 0, v173, s[98:99]
	v_cndmask_b32_e64 v86, 0, v176, s[100:101]
	v_cmp_ne_u32_e32 vcc, v177, v0
	v_cmp_ne_u32_e64 s[98:99], v178, v0
	v_cmp_ne_u32_e64 s[100:101], v179, v0
	v_cndmask_b32_e32 v87, 0, v177, vcc
	v_cndmask_b32_e64 v88, 0, v178, s[98:99]
	v_cndmask_b32_e64 v89, 0, v179, s[100:101]
	v_cmp_ne_u32_e32 vcc, v180, v0
	v_cmp_ne_u32_e64 s[98:99], v181, v0
	v_cmp_ne_u32_e64 s[100:101], v182, v0
	v_cndmask_b32_e32 v164, 0, v180, vcc
	v_cndmask_b32_e64 v165, 0, v181, s[98:99]
	v_cndmask_b32_e64 v166, 0, v182, s[100:101]
	v_cmp_ne_u32_e32 vcc, v183, v0
	v_cmp_ne_u32_e64 s[98:99], v184, v0
	v_cmp_ne_u32_e64 s[100:101], v185, v0
	v_cndmask_b32_e32 v167, 0, v183, vcc
	v_cndmask_b32_e64 v168, 0, v184, s[98:99]
	v_cndmask_b32_e64 v169, 0, v185, s[100:101]
	v_cmp_ne_u32_e32 vcc, v186, v0
	v_cmp_ne_u32_e64 s[98:99], v187, v0
	v_cmp_ne_u32_e64 s[100:101], v188, v0
	v_cndmask_b32_e32 v171, 0, v186, vcc
	v_cndmask_b32_e64 v172, 0, v187, s[98:99]
	v_cndmask_b32_e64 v173, 0, v188, s[100:101]
	v_cmp_ne_u32_e32 vcc, v189, v0
	v_cmp_ne_u32_e64 s[98:99], v194, v0
	v_cmp_ne_u32_e64 s[100:101], v195, v0
	v_cndmask_b32_e32 v176, 0, v189, vcc
	v_cndmask_b32_e64 v177, 0, v194, s[98:99]
	v_cndmask_b32_e64 v178, 0, v195, s[100:101]
	v_cmp_ne_u32_e32 vcc, v196, v0
	v_cmp_ne_u32_e64 s[98:99], v4, v0
	v_cmp_ne_u32_e64 s[100:101], v1, v0
	v_cndmask_b32_e32 v179, 0, v196, vcc
	v_cndmask_b32_e64 v4, 0, v4, s[98:99]
	v_cndmask_b32_e64 v180, 0, v1, s[100:101]
	v_max_u32_e32 v1, v5, v6
	v_max3_u32 v1, v1, v7, v8
	v_max3_u32 v1, v1, v9, v10
	v_max3_u32 v1, v1, v11, v12
	v_max3_u32 v1, v1, v13, v14
	v_max3_u32 v1, v1, v15, v86
	v_max3_u32 v1, v1, v87, v88
	v_max3_u32 v1, v1, v89, v164
	v_max3_u32 v1, v1, v165, v166
	v_max3_u32 v1, v1, v167, v168
	v_max3_u32 v1, v1, v169, v171
	v_max3_u32 v1, v1, v172, v173
	v_cmp_ne_u32_e32 vcc, v2, v0
	v_max3_u32 v1, v1, v176, v177
	v_max3_u32 v1, v1, v178, v179
	v_cndmask_b32_e32 v2, 0, v2, vcc
	v_cmp_ne_u32_e64 s[98:99], v3, v0
	v_max3_u32 v1, v1, v4, v180
	s_nop 0
	v_cndmask_b32_e64 v3, 0, v3, s[98:99]
	v_max3_u32 v1, v1, v2, v3
	v_mov_b32_e32 v181, v1
	s_nop 1
	v_permlane16_swap_b32 v1, v181
	s_nop 1
	s_waitcnt lgkmcnt(0)
	v_max_u32_e32 v1, v1, v181
	v_mov_b32_e32 v181, v1
	s_nop 1
	v_permlane32_swap_b32 v1, v181
	s_nop 1
	s_waitcnt lgkmcnt(0)
	v_max_u32_e32 v1, v1, v181
	v_cmp_ne_u32_e32 vcc, v5, v1
	v_cmp_ne_u32_e64 s[98:99], v6, v1
	v_cmp_ne_u32_e64 s[100:101], v7, v1
	v_cndmask_b32_e32 v5, 0, v5, vcc
	v_cndmask_b32_e64 v6, 0, v6, s[98:99]
	v_cndmask_b32_e64 v7, 0, v7, s[100:101]
	v_cmp_ne_u32_e32 vcc, v8, v1
	v_cmp_ne_u32_e64 s[98:99], v9, v1
	v_cmp_ne_u32_e64 s[100:101], v10, v1
	v_cndmask_b32_e32 v8, 0, v8, vcc
	v_cndmask_b32_e64 v9, 0, v9, s[98:99]
	v_cndmask_b32_e64 v10, 0, v10, s[100:101]
	v_cmp_ne_u32_e32 vcc, v11, v1
	v_cmp_ne_u32_e64 s[98:99], v12, v1
	v_cmp_ne_u32_e64 s[100:101], v13, v1
	v_cndmask_b32_e32 v11, 0, v11, vcc
	v_cndmask_b32_e64 v12, 0, v12, s[98:99]
	v_cndmask_b32_e64 v13, 0, v13, s[100:101]
	v_cmp_ne_u32_e32 vcc, v14, v1
	v_cmp_ne_u32_e64 s[98:99], v15, v1
	v_cmp_ne_u32_e64 s[100:101], v86, v1
	v_cndmask_b32_e32 v14, 0, v14, vcc
	v_cndmask_b32_e64 v15, 0, v15, s[98:99]
	v_cndmask_b32_e64 v86, 0, v86, s[100:101]
	v_cmp_ne_u32_e32 vcc, v87, v1
	v_cmp_ne_u32_e64 s[98:99], v88, v1
	v_cmp_ne_u32_e64 s[100:101], v89, v1
	v_cndmask_b32_e32 v87, 0, v87, vcc
	v_cndmask_b32_e64 v88, 0, v88, s[98:99]
	v_cndmask_b32_e64 v89, 0, v89, s[100:101]
	v_cmp_ne_u32_e32 vcc, v164, v1
	v_cmp_ne_u32_e64 s[98:99], v165, v1
	v_cmp_ne_u32_e64 s[100:101], v166, v1
	v_cndmask_b32_e32 v164, 0, v164, vcc
	v_cndmask_b32_e64 v165, 0, v165, s[98:99]
	v_cndmask_b32_e64 v166, 0, v166, s[100:101]
	v_cmp_ne_u32_e32 vcc, v167, v1
	v_cmp_ne_u32_e64 s[98:99], v168, v1
	v_cmp_ne_u32_e64 s[100:101], v169, v1
	v_cndmask_b32_e32 v167, 0, v167, vcc
	v_cndmask_b32_e64 v168, 0, v168, s[98:99]
	v_cndmask_b32_e64 v169, 0, v169, s[100:101]
	v_cmp_ne_u32_e32 vcc, v171, v1
	v_cmp_ne_u32_e64 s[98:99], v172, v1
	v_cmp_ne_u32_e64 s[100:101], v173, v1
	v_cndmask_b32_e32 v171, 0, v171, vcc
	v_cndmask_b32_e64 v172, 0, v172, s[98:99]
	v_cndmask_b32_e64 v173, 0, v173, s[100:101]
	v_cmp_ne_u32_e32 vcc, v176, v1
	v_cmp_ne_u32_e64 s[98:99], v177, v1
	v_cmp_ne_u32_e64 s[100:101], v178, v1
	v_cndmask_b32_e32 v176, 0, v176, vcc
	v_cndmask_b32_e64 v177, 0, v177, s[98:99]
	v_cndmask_b32_e64 v178, 0, v178, s[100:101]
	v_cmp_ne_u32_e32 vcc, v179, v1
	v_cmp_ne_u32_e64 s[98:99], v4, v1
	v_cmp_ne_u32_e64 s[100:101], v180, v1
	v_cndmask_b32_e32 v179, 0, v179, vcc
	v_cndmask_b32_e64 v4, 0, v4, s[98:99]
	v_cndmask_b32_e64 v180, 0, v180, s[100:101]
	v_cmp_ne_u32_e32 vcc, v2, v1
	v_cmp_ne_u32_e64 s[98:99], v3, v1
	s_nop 0
	v_cndmask_b32_e32 v181, 0, v2, vcc
	v_max_u32_e32 v2, v5, v6
	v_max3_u32 v2, v2, v7, v8
	v_max3_u32 v2, v2, v9, v10
	v_max3_u32 v2, v2, v11, v12
	v_max3_u32 v2, v2, v13, v14
	v_max3_u32 v2, v2, v15, v86
	v_max3_u32 v2, v2, v87, v88
	v_max3_u32 v2, v2, v89, v164
	v_max3_u32 v2, v2, v165, v166
	v_max3_u32 v2, v2, v167, v168
	v_max3_u32 v2, v2, v169, v171
	v_max3_u32 v2, v2, v172, v173
	v_max3_u32 v2, v2, v176, v177
	v_max3_u32 v2, v2, v178, v179
	v_max3_u32 v2, v2, v4, v180
	v_cndmask_b32_e64 v3, 0, v3, s[98:99]
	v_max3_u32 v2, v2, v181, v3
	v_mov_b32_e32 v182, v2
	s_nop 1
	v_permlane16_swap_b32 v2, v182
	s_nop 1
	s_waitcnt lgkmcnt(0)
; DI void peer_topk_wave(const Params& p, int item, unsigned* lds  ) {
;     ...
; #pragma unroll
;     for (int rr = 0; rr < 16; ++rr) {
;       unsigned m = 0;
; #pragma unroll
;       for (int i = 0; i < 32; ++i) m = umax(m, kk[i]);
;       m = umax(m, (unsigned)__shfl_xor((int)m, 16));
;       m = umax(m, (unsigned)__shfl_xor((int)m, 32));
;       win[pp][rr] = m;
; #pragma unroll
;       for (int i = 0; i < 32; ++i) kk[i] = (kk[i] == m) ? 0u : kk[i];
;     }
	v_max_u32_e32 v2, v2, v182
	v_mov_b32_e32 v182, v2
	s_nop 1
	v_permlane32_swap_b32 v2, v182
	s_nop 1
	s_waitcnt lgkmcnt(0)
	v_max_u32_e32 v2, v2, v182
	v_cmp_ne_u32_e32 vcc, v5, v2
	v_cmp_ne_u32_e64 s[98:99], v6, v2
	v_cmp_ne_u32_e64 s[100:101], v7, v2
	v_cndmask_b32_e32 v5, 0, v5, vcc
	v_cndmask_b32_e64 v6, 0, v6, s[98:99]
	v_cndmask_b32_e64 v7, 0, v7, s[100:101]
	v_cmp_ne_u32_e32 vcc, v8, v2
	v_cmp_ne_u32_e64 s[98:99], v9, v2
	v_cmp_ne_u32_e64 s[100:101], v10, v2
	v_cndmask_b32_e32 v8, 0, v8, vcc
	v_cndmask_b32_e64 v9, 0, v9, s[98:99]
	v_cndmask_b32_e64 v10, 0, v10, s[100:101]
	v_cmp_ne_u32_e32 vcc, v11, v2
	v_cmp_ne_u32_e64 s[98:99], v12, v2
	v_cmp_ne_u32_e64 s[100:101], v13, v2
	v_cndmask_b32_e32 v11, 0, v11, vcc
	v_cndmask_b32_e64 v12, 0, v12, s[98:99]
	v_cndmask_b32_e64 v13, 0, v13, s[100:101]
	v_cmp_ne_u32_e32 vcc, v14, v2
	v_cmp_ne_u32_e64 s[98:99], v15, v2
	v_cmp_ne_u32_e64 s[100:101], v86, v2
	v_cndmask_b32_e32 v14, 0, v14, vcc
	v_cndmask_b32_e64 v15, 0, v15, s[98:99]
	v_cndmask_b32_e64 v86, 0, v86, s[100:101]
	v_cmp_ne_u32_e32 vcc, v87, v2
	v_cmp_ne_u32_e64 s[98:99], v88, v2
	v_cmp_ne_u32_e64 s[100:101], v89, v2
	v_cndmask_b32_e32 v87, 0, v87, vcc
	v_cndmask_b32_e64 v88, 0, v88, s[98:99]
	v_cndmask_b32_e64 v89, 0, v89, s[100:101]
	v_cmp_ne_u32_e32 vcc, v164, v2
	v_cmp_ne_u32_e64 s[98:99], v165, v2
	v_cmp_ne_u32_e64 s[100:101], v166, v2
	v_cndmask_b32_e32 v164, 0, v164, vcc
	v_cndmask_b32_e64 v165, 0, v165, s[98:99]
	v_cndmask_b32_e64 v166, 0, v166, s[100:101]
	v_cmp_ne_u32_e32 vcc, v167, v2
	v_cmp_ne_u32_e64 s[98:99], v168, v2
	v_cmp_ne_u32_e64 s[100:101], v169, v2
	v_cndmask_b32_e32 v167, 0, v167, vcc
	v_cndmask_b32_e64 v168, 0, v168, s[98:99]
	v_cndmask_b32_e64 v169, 0, v169, s[100:101]
	v_cmp_ne_u32_e32 vcc, v171, v2
	v_cmp_ne_u32_e64 s[98:99], v172, v2
	v_cmp_ne_u32_e64 s[100:101], v173, v2
	v_cndmask_b32_e32 v171, 0, v171, vcc
	v_cndmask_b32_e64 v172, 0, v172, s[98:99]
	v_cndmask_b32_e64 v173, 0, v173, s[100:101]
	v_cmp_ne_u32_e32 vcc, v176, v2
	v_cmp_ne_u32_e64 s[98:99], v177, v2
	v_cmp_ne_u32_e64 s[100:101], v178, v2
	v_cndmask_b32_e32 v176, 0, v176, vcc
	v_cndmask_b32_e64 v177, 0, v177, s[98:99]
	v_cndmask_b32_e64 v178, 0, v178, s[100:101]
	v_cmp_ne_u32_e32 vcc, v179, v2
	v_cmp_ne_u32_e64 s[98:99], v4, v2
	v_cmp_ne_u32_e64 s[100:101], v180, v2
	v_cndmask_b32_e32 v179, 0, v179, vcc
	v_cndmask_b32_e64 v4, 0, v4, s[98:99]
	v_cndmask_b32_e64 v180, 0, v180, s[100:101]
	v_cmp_ne_u32_e32 vcc, v181, v2
	v_cmp_ne_u32_e64 s[98:99], v3, v2
	s_nop 0
	v_cndmask_b32_e32 v181, 0, v181, vcc
	v_cndmask_b32_e64 v182, 0, v3, s[98:99]
	v_max_u32_e32 v3, v5, v6
	v_max3_u32 v3, v3, v7, v8
	v_max3_u32 v3, v3, v9, v10
	v_max3_u32 v3, v3, v11, v12
	v_max3_u32 v3, v3, v13, v14
	v_max3_u32 v3, v3, v15, v86
	v_max3_u32 v3, v3, v87, v88
	v_max3_u32 v3, v3, v89, v164
	v_max3_u32 v3, v3, v165, v166
	v_max3_u32 v3, v3, v167, v168
	v_max3_u32 v3, v3, v169, v171
	v_max3_u32 v3, v3, v172, v173
	v_max3_u32 v3, v3, v176, v177
	v_max3_u32 v3, v3, v178, v179
	v_max3_u32 v3, v3, v4, v180
	v_max3_u32 v3, v3, v181, v182
	v_mov_b32_e32 v183, v3
	s_nop 1
	v_permlane16_swap_b32 v3, v183
	s_nop 1
	s_waitcnt lgkmcnt(0)
	v_max_u32_e32 v3, v3, v183
	v_mov_b32_e32 v183, v3
	s_nop 1
	v_permlane32_swap_b32 v3, v183
	s_nop 1
	s_waitcnt lgkmcnt(0)
	v_max_u32_e32 v3, v3, v183
	v_cmp_ne_u32_e32 vcc, v5, v3
	v_cmp_ne_u32_e64 s[98:99], v6, v3
	v_cmp_ne_u32_e64 s[100:101], v7, v3
	v_cndmask_b32_e32 v5, 0, v5, vcc
	v_cndmask_b32_e64 v6, 0, v6, s[98:99]
	v_cndmask_b32_e64 v7, 0, v7, s[100:101]
	v_cmp_ne_u32_e32 vcc, v8, v3
	v_cmp_ne_u32_e64 s[98:99], v9, v3
	v_cmp_ne_u32_e64 s[100:101], v10, v3
	v_cndmask_b32_e32 v8, 0, v8, vcc
	v_cndmask_b32_e64 v9, 0, v9, s[98:99]
	v_cndmask_b32_e64 v10, 0, v10, s[100:101]
	v_cmp_ne_u32_e32 vcc, v11, v3
	v_cmp_ne_u32_e64 s[98:99], v12, v3
	v_cmp_ne_u32_e64 s[100:101], v13, v3
	v_cndmask_b32_e32 v11, 0, v11, vcc
	v_cndmask_b32_e64 v12, 0, v12, s[98:99]
	v_cndmask_b32_e64 v13, 0, v13, s[100:101]
	v_cmp_ne_u32_e32 vcc, v14, v3
	v_cmp_ne_u32_e64 s[98:99], v15, v3
	v_cmp_ne_u32_e64 s[100:101], v86, v3
	v_cndmask_b32_e32 v14, 0, v14, vcc
	v_cndmask_b32_e64 v15, 0, v15, s[98:99]
	v_cndmask_b32_e64 v86, 0, v86, s[100:101]
	v_cmp_ne_u32_e32 vcc, v87, v3
	v_cmp_ne_u32_e64 s[98:99], v88, v3
	v_cmp_ne_u32_e64 s[100:101], v89, v3
	v_cndmask_b32_e32 v87, 0, v87, vcc
	v_cndmask_b32_e64 v88, 0, v88, s[98:99]
	v_cndmask_b32_e64 v89, 0, v89, s[100:101]
	v_cmp_ne_u32_e32 vcc, v164, v3
	v_cmp_ne_u32_e64 s[98:99], v165, v3
	v_cmp_ne_u32_e64 s[100:101], v166, v3
	v_cndmask_b32_e32 v164, 0, v164, vcc
	v_cndmask_b32_e64 v165, 0, v165, s[98:99]
	v_cndmask_b32_e64 v166, 0, v166, s[100:101]
	v_cmp_ne_u32_e32 vcc, v167, v3
	v_cmp_ne_u32_e64 s[98:99], v168, v3
	v_cmp_ne_u32_e64 s[100:101], v169, v3
	v_cndmask_b32_e32 v167, 0, v167, vcc
	v_cndmask_b32_e64 v168, 0, v168, s[98:99]
	v_cndmask_b32_e64 v169, 0, v169, s[100:101]
	v_cmp_ne_u32_e32 vcc, v171, v3
	v_cmp_ne_u32_e64 s[98:99], v172, v3
	v_cmp_ne_u32_e64 s[100:101], v173, v3
	v_cndmask_b32_e32 v171, 0, v171, vcc
	v_cndmask_b32_e64 v172, 0, v172, s[98:99]
	v_cndmask_b32_e64 v173, 0, v173, s[100:101]
	v_cmp_ne_u32_e32 vcc, v176, v3
	v_cmp_ne_u32_e64 s[98:99], v177, v3
	v_cmp_ne_u32_e64 s[100:101], v178, v3
	v_cndmask_b32_e32 v176, 0, v176, vcc
	v_cndmask_b32_e64 v177, 0, v177, s[98:99]
	v_cndmask_b32_e64 v178, 0, v178, s[100:101]
	v_cmp_ne_u32_e32 vcc, v179, v3
	v_cmp_ne_u32_e64 s[98:99], v4, v3
	v_cmp_ne_u32_e64 s[100:101], v180, v3
	v_cndmask_b32_e32 v179, 0, v179, vcc
	v_cndmask_b32_e64 v183, 0, v4, s[98:99]
	v_max_u32_e32 v4, v5, v6
	v_max3_u32 v4, v4, v7, v8
	v_max3_u32 v4, v4, v9, v10
	v_max3_u32 v4, v4, v11, v12
	v_max3_u32 v4, v4, v13, v14
	v_max3_u32 v4, v4, v15, v86
	v_max3_u32 v4, v4, v87, v88
	v_max3_u32 v4, v4, v89, v164
	v_max3_u32 v4, v4, v165, v166
	v_max3_u32 v4, v4, v167, v168
	v_max3_u32 v4, v4, v169, v171
	v_max3_u32 v4, v4, v172, v173
	v_max3_u32 v4, v4, v176, v177
	v_cndmask_b32_e64 v180, 0, v180, s[100:101]
	v_cmp_ne_u32_e32 vcc, v181, v3
	v_max3_u32 v4, v4, v178, v179
	v_max3_u32 v4, v4, v183, v180
	v_cndmask_b32_e32 v181, 0, v181, vcc
	v_cmp_ne_u32_e64 s[98:99], v182, v3
	s_nop 0
	s_nop 0
	v_cndmask_b32_e64 v182, 0, v182, s[98:99]
	v_max3_u32 v4, v4, v181, v182
	v_mov_b32_e32 v184, v4
	s_nop 1
	v_permlane16_swap_b32 v4, v184
	s_nop 1
	s_waitcnt lgkmcnt(0)
; DI void peer_topk_wave(const Params& p, int item, unsigned* lds  ) {
;     ...
; #pragma unroll
;     for (int rr = 0; rr < 16; ++rr) {
;       unsigned m = 0;
; #pragma unroll
;       for (int i = 0; i < 32; ++i) m = umax(m, kk[i]);
;       m = umax(m, (unsigned)__shfl_xor((int)m, 16));
;       m = umax(m, (unsigned)__shfl_xor((int)m, 32));
;       win[pp][rr] = m;
; #pragma unroll
;       for (int i = 0; i < 32; ++i) kk[i] = (kk[i] == m) ? 0u : kk[i];
;     }
	v_max_u32_e32 v4, v4, v184
	v_mov_b32_e32 v184, v4
	s_nop 1
	v_permlane32_swap_b32 v4, v184
	s_nop 1
	s_waitcnt lgkmcnt(0)
	v_max_u32_e32 v4, v4, v184
	v_cmp_ne_u32_e32 vcc, v5, v4
	v_cmp_ne_u32_e64 s[98:99], v6, v4
	v_cmp_ne_u32_e64 s[100:101], v7, v4
	v_cndmask_b32_e32 v184, 0, v5, vcc
	v_cndmask_b32_e64 v6, 0, v6, s[98:99]
	v_max_u32_e32 v5, v184, v6
	v_cndmask_b32_e64 v7, 0, v7, s[100:101]
	v_cmp_ne_u32_e32 vcc, v8, v4
	v_cmp_ne_u32_e64 s[98:99], v9, v4
	v_cmp_ne_u32_e64 s[100:101], v10, v4
	v_cndmask_b32_e32 v8, 0, v8, vcc
	v_max3_u32 v5, v5, v7, v8
	v_cndmask_b32_e64 v9, 0, v9, s[98:99]
	v_cndmask_b32_e64 v10, 0, v10, s[100:101]
	v_cmp_ne_u32_e32 vcc, v11, v4
	v_max3_u32 v5, v5, v9, v10
	v_cmp_ne_u32_e64 s[98:99], v12, v4
	v_cndmask_b32_e32 v11, 0, v11, vcc
	v_cmp_ne_u32_e64 s[100:101], v13, v4
	v_cndmask_b32_e64 v12, 0, v12, s[98:99]
	v_max3_u32 v5, v5, v11, v12
	v_cndmask_b32_e64 v13, 0, v13, s[100:101]
	v_cmp_ne_u32_e32 vcc, v14, v4
	v_cmp_ne_u32_e64 s[98:99], v15, v4
	v_cmp_ne_u32_e64 s[100:101], v86, v4
	v_cndmask_b32_e32 v14, 0, v14, vcc
	v_max3_u32 v5, v5, v13, v14
	v_cndmask_b32_e64 v15, 0, v15, s[98:99]
	v_cndmask_b32_e64 v86, 0, v86, s[100:101]
	v_cmp_ne_u32_e32 vcc, v87, v4
	v_max3_u32 v5, v5, v15, v86
	v_cmp_ne_u32_e64 s[98:99], v88, v4
	v_cndmask_b32_e32 v87, 0, v87, vcc
	v_cmp_ne_u32_e64 s[100:101], v89, v4
	v_cndmask_b32_e64 v88, 0, v88, s[98:99]
	v_max3_u32 v5, v5, v87, v88
	v_cndmask_b32_e64 v89, 0, v89, s[100:101]
	v_cmp_ne_u32_e32 vcc, v164, v4
	v_cmp_ne_u32_e64 s[98:99], v165, v4
	v_cmp_ne_u32_e64 s[100:101], v166, v4
	v_cndmask_b32_e32 v164, 0, v164, vcc
	v_max3_u32 v5, v5, v89, v164
	v_cndmask_b32_e64 v165, 0, v165, s[98:99]
	v_cndmask_b32_e64 v166, 0, v166, s[100:101]
	v_cmp_ne_u32_e32 vcc, v167, v4
	v_max3_u32 v5, v5, v165, v166
	v_cmp_ne_u32_e64 s[98:99], v168, v4
	v_cndmask_b32_e32 v167, 0, v167, vcc
	v_cmp_ne_u32_e64 s[100:101], v169, v4
	v_cndmask_b32_e64 v168, 0, v168, s[98:99]
	v_max3_u32 v5, v5, v167, v168
	v_cndmask_b32_e64 v169, 0, v169, s[100:101]
	v_cmp_ne_u32_e32 vcc, v171, v4
	v_cmp_ne_u32_e64 s[98:99], v172, v4
	v_cmp_ne_u32_e64 s[100:101], v173, v4
	v_cndmask_b32_e32 v171, 0, v171, vcc
	v_max3_u32 v5, v5, v169, v171
	v_cndmask_b32_e64 v172, 0, v172, s[98:99]
	v_cndmask_b32_e64 v173, 0, v173, s[100:101]
	v_cmp_ne_u32_e32 vcc, v176, v4
	v_max3_u32 v5, v5, v172, v173
	v_cmp_ne_u32_e64 s[98:99], v177, v4
	v_cndmask_b32_e32 v176, 0, v176, vcc
	v_cmp_ne_u32_e64 s[100:101], v178, v4
	v_cndmask_b32_e64 v177, 0, v177, s[98:99]
	v_max3_u32 v5, v5, v176, v177
	v_cndmask_b32_e64 v178, 0, v178, s[100:101]
	v_cmp_ne_u32_e32 vcc, v179, v4
	v_cmp_ne_u32_e64 s[98:99], v183, v4
	v_cmp_ne_u32_e64 s[100:101], v180, v4
	v_cndmask_b32_e32 v179, 0, v179, vcc
	v_max3_u32 v5, v5, v178, v179
	v_cndmask_b32_e64 v183, 0, v183, s[98:99]
	v_cndmask_b32_e64 v180, 0, v180, s[100:101]
	v_cmp_ne_u32_e32 vcc, v181, v4
	v_max3_u32 v5, v5, v183, v180
	v_cmp_ne_u32_e64 s[98:99], v182, v4
	v_cndmask_b32_e32 v181, 0, v181, vcc
	s_nop 0
	v_cndmask_b32_e64 v182, 0, v182, s[98:99]
	v_max3_u32 v5, v5, v181, v182
	v_mov_b32_e32 v185, v5
	s_nop 1
	v_permlane16_swap_b32 v5, v185
	s_nop 1
	s_waitcnt lgkmcnt(0)
	v_max_u32_e32 v5, v5, v185
	v_mov_b32_e32 v185, v5
	s_nop 1
	v_permlane32_swap_b32 v5, v185
	s_nop 1
	s_waitcnt lgkmcnt(0)
	v_max_u32_e32 v5, v5, v185
	v_cmp_ne_u32_e32 vcc, v184, v5
	v_cmp_ne_u32_e64 s[98:99], v6, v5
	v_cmp_ne_u32_e64 s[100:101], v7, v5
	v_cndmask_b32_e32 v184, 0, v184, vcc
	v_cndmask_b32_e64 v185, 0, v6, s[98:99]
	v_max_u32_e32 v6, v184, v185
	v_cndmask_b32_e64 v7, 0, v7, s[100:101]
	v_cmp_ne_u32_e32 vcc, v8, v5
	v_cmp_ne_u32_e64 s[98:99], v9, v5
	v_cmp_ne_u32_e64 s[100:101], v10, v5
	v_cndmask_b32_e32 v8, 0, v8, vcc
	v_max3_u32 v6, v6, v7, v8
	v_cndmask_b32_e64 v9, 0, v9, s[98:99]
	v_cndmask_b32_e64 v10, 0, v10, s[100:101]
	v_cmp_ne_u32_e32 vcc, v11, v5
	v_max3_u32 v6, v6, v9, v10
	v_cmp_ne_u32_e64 s[98:99], v12, v5
	v_cndmask_b32_e32 v11, 0, v11, vcc
	v_cmp_ne_u32_e64 s[100:101], v13, v5
	v_cndmask_b32_e64 v12, 0, v12, s[98:99]
	v_max3_u32 v6, v6, v11, v12
	v_cndmask_b32_e64 v13, 0, v13, s[100:101]
	v_cmp_ne_u32_e32 vcc, v14, v5
	v_cmp_ne_u32_e64 s[98:99], v15, v5
	v_cmp_ne_u32_e64 s[100:101], v86, v5
	v_cndmask_b32_e32 v14, 0, v14, vcc
	v_max3_u32 v6, v6, v13, v14
	v_cndmask_b32_e64 v15, 0, v15, s[98:99]
	v_cndmask_b32_e64 v86, 0, v86, s[100:101]
	v_cmp_ne_u32_e32 vcc, v87, v5
	v_max3_u32 v6, v6, v15, v86
	v_cmp_ne_u32_e64 s[98:99], v88, v5
	v_cndmask_b32_e32 v87, 0, v87, vcc
	v_cmp_ne_u32_e64 s[100:101], v89, v5
	v_cndmask_b32_e64 v88, 0, v88, s[98:99]
	v_max3_u32 v6, v6, v87, v88
	v_cndmask_b32_e64 v89, 0, v89, s[100:101]
	v_cmp_ne_u32_e32 vcc, v164, v5
	v_cmp_ne_u32_e64 s[98:99], v165, v5
	v_cmp_ne_u32_e64 s[100:101], v166, v5
	v_cndmask_b32_e32 v164, 0, v164, vcc
	v_max3_u32 v6, v6, v89, v164
	v_cndmask_b32_e64 v165, 0, v165, s[98:99]
	v_cndmask_b32_e64 v166, 0, v166, s[100:101]
	v_cmp_ne_u32_e32 vcc, v167, v5
	v_max3_u32 v6, v6, v165, v166
	v_cmp_ne_u32_e64 s[98:99], v168, v5
	v_cndmask_b32_e32 v167, 0, v167, vcc
	v_cmp_ne_u32_e64 s[100:101], v169, v5
	v_cndmask_b32_e64 v168, 0, v168, s[98:99]
	v_max3_u32 v6, v6, v167, v168
	v_cndmask_b32_e64 v169, 0, v169, s[100:101]
	v_cmp_ne_u32_e32 vcc, v171, v5
	v_cmp_ne_u32_e64 s[98:99], v172, v5
	v_cmp_ne_u32_e64 s[100:101], v173, v5
	v_cndmask_b32_e32 v171, 0, v171, vcc
	v_max3_u32 v6, v6, v169, v171
	v_cndmask_b32_e64 v172, 0, v172, s[98:99]
	v_cndmask_b32_e64 v173, 0, v173, s[100:101]
	v_cmp_ne_u32_e32 vcc, v176, v5
	v_max3_u32 v6, v6, v172, v173
	v_cmp_ne_u32_e64 s[98:99], v177, v5
	v_cndmask_b32_e32 v176, 0, v176, vcc
	v_cmp_ne_u32_e64 s[100:101], v178, v5
	v_cndmask_b32_e64 v177, 0, v177, s[98:99]
	v_max3_u32 v6, v6, v176, v177
	v_cndmask_b32_e64 v178, 0, v178, s[100:101]
	v_cmp_ne_u32_e32 vcc, v179, v5
	v_cmp_ne_u32_e64 s[98:99], v183, v5
	v_cmp_ne_u32_e64 s[100:101], v180, v5
	v_cndmask_b32_e32 v179, 0, v179, vcc
	v_max3_u32 v6, v6, v178, v179
	v_cndmask_b32_e64 v183, 0, v183, s[98:99]
	v_cndmask_b32_e64 v180, 0, v180, s[100:101]
	v_cmp_ne_u32_e32 vcc, v181, v5
	v_max3_u32 v6, v6, v183, v180
	v_cmp_ne_u32_e64 s[98:99], v182, v5
	v_cndmask_b32_e32 v181, 0, v181, vcc
	s_nop 0
	v_cndmask_b32_e64 v182, 0, v182, s[98:99]
	v_max3_u32 v6, v6, v181, v182
	v_mov_b32_e32 v186, v6
	s_nop 1
	v_permlane16_swap_b32 v6, v186
	s_nop 1
	s_waitcnt lgkmcnt(0)
; DI void peer_topk_wave(const Params& p, int item, unsigned* lds  ) {
;     ...
; #pragma unroll
;     for (int rr = 0; rr < 16; ++rr) {
;       unsigned m = 0;
; #pragma unroll
;       for (int i = 0; i < 32; ++i) m = umax(m, kk[i]);
;       m = umax(m, (unsigned)__shfl_xor((int)m, 16));
;       m = umax(m, (unsigned)__shfl_xor((int)m, 32));
;       win[pp][rr] = m;
; #pragma unroll
;       for (int i = 0; i < 32; ++i) kk[i] = (kk[i] == m) ? 0u : kk[i];
;     }
	v_max_u32_e32 v6, v6, v186
	v_mov_b32_e32 v186, v6
	s_nop 1
	v_permlane32_swap_b32 v6, v186
	s_nop 1
	s_waitcnt lgkmcnt(0)
	v_max_u32_e32 v6, v6, v186
	v_cmp_ne_u32_e32 vcc, v184, v6
	v_cmp_ne_u32_e64 s[98:99], v185, v6
	v_cmp_ne_u32_e64 s[100:101], v7, v6
	v_cndmask_b32_e32 v184, 0, v184, vcc
	v_cndmask_b32_e64 v185, 0, v185, s[98:99]
	v_cndmask_b32_e64 v186, 0, v7, s[100:101]
	v_cmp_ne_u32_e32 vcc, v8, v6
	v_max_u32_e32 v7, v184, v185
	v_cmp_ne_u32_e64 s[98:99], v9, v6
	v_cndmask_b32_e32 v8, 0, v8, vcc
	v_max3_u32 v7, v7, v186, v8
	v_cndmask_b32_e64 v9, 0, v9, s[98:99]
	v_cmp_ne_u32_e64 s[100:101], v10, v6
	v_cmp_ne_u32_e32 vcc, v11, v6
	v_cmp_ne_u32_e64 s[98:99], v12, v6
	v_cndmask_b32_e64 v10, 0, v10, s[100:101]
	v_max3_u32 v7, v7, v9, v10
	v_cndmask_b32_e32 v11, 0, v11, vcc
	v_cndmask_b32_e64 v12, 0, v12, s[98:99]
	v_cmp_ne_u32_e64 s[100:101], v13, v6
	v_max3_u32 v7, v7, v11, v12
	v_cmp_ne_u32_e32 vcc, v14, v6
	v_cndmask_b32_e64 v13, 0, v13, s[100:101]
	v_cmp_ne_u32_e64 s[98:99], v15, v6
	v_cndmask_b32_e32 v14, 0, v14, vcc
	v_max3_u32 v7, v7, v13, v14
	v_cndmask_b32_e64 v15, 0, v15, s[98:99]
	v_cmp_ne_u32_e64 s[100:101], v86, v6
	v_cmp_ne_u32_e32 vcc, v87, v6
	v_cmp_ne_u32_e64 s[98:99], v88, v6
	v_cndmask_b32_e64 v86, 0, v86, s[100:101]
	v_max3_u32 v7, v7, v15, v86
	v_cndmask_b32_e32 v87, 0, v87, vcc
	v_cndmask_b32_e64 v88, 0, v88, s[98:99]
	v_cmp_ne_u32_e64 s[100:101], v89, v6
	v_max3_u32 v7, v7, v87, v88
	v_cmp_ne_u32_e32 vcc, v164, v6
	v_cndmask_b32_e64 v89, 0, v89, s[100:101]
	v_cmp_ne_u32_e64 s[98:99], v165, v6
	v_cndmask_b32_e32 v164, 0, v164, vcc
	v_max3_u32 v7, v7, v89, v164
	v_cndmask_b32_e64 v165, 0, v165, s[98:99]
	v_cmp_ne_u32_e64 s[100:101], v166, v6
	v_cmp_ne_u32_e32 vcc, v167, v6
	v_cmp_ne_u32_e64 s[98:99], v168, v6
	v_cndmask_b32_e64 v166, 0, v166, s[100:101]
	v_max3_u32 v7, v7, v165, v166
	v_cndmask_b32_e32 v167, 0, v167, vcc
	v_cndmask_b32_e64 v168, 0, v168, s[98:99]
	v_cmp_ne_u32_e64 s[100:101], v169, v6
	v_max3_u32 v7, v7, v167, v168
	v_cmp_ne_u32_e32 vcc, v171, v6
	v_cndmask_b32_e64 v169, 0, v169, s[100:101]
	v_cmp_ne_u32_e64 s[98:99], v172, v6
	v_cndmask_b32_e32 v171, 0, v171, vcc
	v_max3_u32 v7, v7, v169, v171
	v_cndmask_b32_e64 v172, 0, v172, s[98:99]
	v_cmp_ne_u32_e64 s[100:101], v173, v6
	v_cmp_ne_u32_e32 vcc, v176, v6
	v_cmp_ne_u32_e64 s[98:99], v177, v6
	v_cndmask_b32_e64 v173, 0, v173, s[100:101]
	v_max3_u32 v7, v7, v172, v173
	v_cndmask_b32_e32 v176, 0, v176, vcc
	v_cndmask_b32_e64 v177, 0, v177, s[98:99]
	v_cmp_ne_u32_e64 s[100:101], v178, v6
	v_max3_u32 v7, v7, v176, v177
	v_cmp_ne_u32_e32 vcc, v179, v6
	v_cndmask_b32_e64 v178, 0, v178, s[100:101]
	v_cmp_ne_u32_e64 s[98:99], v183, v6
	v_cndmask_b32_e32 v179, 0, v179, vcc
	v_max3_u32 v7, v7, v178, v179
	v_cndmask_b32_e64 v183, 0, v183, s[98:99]
	v_cmp_ne_u32_e64 s[100:101], v180, v6
	v_cmp_ne_u32_e32 vcc, v181, v6
	v_cmp_ne_u32_e64 s[98:99], v182, v6
	v_cndmask_b32_e64 v180, 0, v180, s[100:101]
	v_max3_u32 v7, v7, v183, v180
	v_cndmask_b32_e32 v181, 0, v181, vcc
	v_cndmask_b32_e64 v182, 0, v182, s[98:99]
	v_max3_u32 v7, v7, v181, v182
	v_mov_b32_e32 v187, v7
	s_nop 1
	v_permlane16_swap_b32 v7, v187
	s_nop 1
	s_waitcnt lgkmcnt(0)
	v_max_u32_e32 v7, v7, v187
	v_mov_b32_e32 v187, v7
	s_nop 1
	v_permlane32_swap_b32 v7, v187
	s_nop 1
	s_waitcnt lgkmcnt(0)
	v_max_u32_e32 v7, v7, v187
	v_cmp_ne_u32_e32 vcc, v184, v7
	v_cmp_ne_u32_e64 s[98:99], v185, v7
	v_cmp_ne_u32_e64 s[100:101], v186, v7
	v_cndmask_b32_e32 v184, 0, v184, vcc
	v_cndmask_b32_e64 v185, 0, v185, s[98:99]
	v_cndmask_b32_e64 v186, 0, v186, s[100:101]
	v_cmp_ne_u32_e32 vcc, v8, v7
	v_cmp_ne_u32_e64 s[98:99], v9, v7
	v_cmp_ne_u32_e64 s[100:101], v10, v7
	v_cndmask_b32_e32 v187, 0, v8, vcc
	v_max_u32_e32 v8, v184, v185
	v_max3_u32 v8, v8, v186, v187
	v_cndmask_b32_e64 v9, 0, v9, s[98:99]
	v_cndmask_b32_e64 v10, 0, v10, s[100:101]
	v_cmp_ne_u32_e32 vcc, v11, v7
	v_max3_u32 v8, v8, v9, v10
	v_cmp_ne_u32_e64 s[98:99], v12, v7
	v_cndmask_b32_e32 v11, 0, v11, vcc
	v_cmp_ne_u32_e64 s[100:101], v13, v7
	v_cndmask_b32_e64 v12, 0, v12, s[98:99]
	v_max3_u32 v8, v8, v11, v12
	v_cndmask_b32_e64 v13, 0, v13, s[100:101]
	v_cmp_ne_u32_e32 vcc, v14, v7
	v_cmp_ne_u32_e64 s[98:99], v15, v7
	v_cmp_ne_u32_e64 s[100:101], v86, v7
	v_cndmask_b32_e32 v14, 0, v14, vcc
	v_max3_u32 v8, v8, v13, v14
	v_cndmask_b32_e64 v15, 0, v15, s[98:99]
	v_cndmask_b32_e64 v86, 0, v86, s[100:101]
	v_cmp_ne_u32_e32 vcc, v87, v7
	v_max3_u32 v8, v8, v15, v86
	v_cmp_ne_u32_e64 s[98:99], v88, v7
	v_cndmask_b32_e32 v87, 0, v87, vcc
	v_cmp_ne_u32_e64 s[100:101], v89, v7
	v_cndmask_b32_e64 v88, 0, v88, s[98:99]
	v_max3_u32 v8, v8, v87, v88
	v_cndmask_b32_e64 v89, 0, v89, s[100:101]
	v_cmp_ne_u32_e32 vcc, v164, v7
	v_cmp_ne_u32_e64 s[98:99], v165, v7
	v_cmp_ne_u32_e64 s[100:101], v166, v7
	v_cndmask_b32_e32 v164, 0, v164, vcc
	v_max3_u32 v8, v8, v89, v164
	v_cndmask_b32_e64 v165, 0, v165, s[98:99]
	v_cndmask_b32_e64 v166, 0, v166, s[100:101]
	v_cmp_ne_u32_e32 vcc, v167, v7
	v_max3_u32 v8, v8, v165, v166
	v_cmp_ne_u32_e64 s[98:99], v168, v7
	v_cndmask_b32_e32 v167, 0, v167, vcc
	v_cmp_ne_u32_e64 s[100:101], v169, v7
	v_cndmask_b32_e64 v168, 0, v168, s[98:99]
	v_max3_u32 v8, v8, v167, v168
	v_cndmask_b32_e64 v169, 0, v169, s[100:101]
	v_cmp_ne_u32_e32 vcc, v171, v7
	v_cmp_ne_u32_e64 s[98:99], v172, v7
	v_cmp_ne_u32_e64 s[100:101], v173, v7
	v_cndmask_b32_e32 v171, 0, v171, vcc
	v_max3_u32 v8, v8, v169, v171
	v_cndmask_b32_e64 v172, 0, v172, s[98:99]
	v_cndmask_b32_e64 v173, 0, v173, s[100:101]
	v_cmp_ne_u32_e32 vcc, v176, v7
	v_max3_u32 v8, v8, v172, v173
	v_cmp_ne_u32_e64 s[98:99], v177, v7
	v_cndmask_b32_e32 v176, 0, v176, vcc
	v_cmp_ne_u32_e64 s[100:101], v178, v7
	v_cndmask_b32_e64 v177, 0, v177, s[98:99]
	v_max3_u32 v8, v8, v176, v177
	v_cndmask_b32_e64 v178, 0, v178, s[100:101]
	v_cmp_ne_u32_e32 vcc, v179, v7
	v_cmp_ne_u32_e64 s[98:99], v183, v7
	v_cmp_ne_u32_e64 s[100:101], v180, v7
	v_cndmask_b32_e32 v179, 0, v179, vcc
	v_max3_u32 v8, v8, v178, v179
	v_cndmask_b32_e64 v183, 0, v183, s[98:99]
	v_cndmask_b32_e64 v180, 0, v180, s[100:101]
	v_cmp_ne_u32_e32 vcc, v181, v7
	v_max3_u32 v8, v8, v183, v180
	v_cmp_ne_u32_e64 s[98:99], v182, v7
	v_cndmask_b32_e32 v181, 0, v181, vcc
	s_nop 0
	v_cndmask_b32_e64 v182, 0, v182, s[98:99]
	v_max3_u32 v8, v8, v181, v182
	v_mov_b32_e32 v188, v8
	s_nop 1
	v_permlane16_swap_b32 v8, v188
	s_nop 1
	s_waitcnt lgkmcnt(0)
; DI void peer_topk_wave(const Params& p, int item, unsigned* lds  ) {
;     ...
; #pragma unroll
;     for (int rr = 0; rr < 16; ++rr) {
;       unsigned m = 0;
; #pragma unroll
;       for (int i = 0; i < 32; ++i) m = umax(m, kk[i]);
;       m = umax(m, (unsigned)__shfl_xor((int)m, 16));
;       m = umax(m, (unsigned)__shfl_xor((int)m, 32));
;       win[pp][rr] = m;
; #pragma unroll
;       for (int i = 0; i < 32; ++i) kk[i] = (kk[i] == m) ? 0u : kk[i];
;     }
	v_max_u32_e32 v8, v8, v188
	v_mov_b32_e32 v188, v8
	s_nop 1
	v_permlane32_swap_b32 v8, v188
	s_nop 1
	s_waitcnt lgkmcnt(0)
	v_max_u32_e32 v8, v8, v188
	v_cmp_ne_u32_e32 vcc, v184, v8
	v_cmp_ne_u32_e64 s[98:99], v185, v8
	v_cmp_ne_u32_e64 s[100:101], v186, v8
	v_cndmask_b32_e32 v184, 0, v184, vcc
	v_cndmask_b32_e64 v185, 0, v185, s[98:99]
	v_cndmask_b32_e64 v186, 0, v186, s[100:101]
	v_cmp_ne_u32_e32 vcc, v187, v8
	v_cmp_ne_u32_e64 s[98:99], v9, v8
	v_cmp_ne_u32_e64 s[100:101], v10, v8
	v_cndmask_b32_e32 v187, 0, v187, vcc
	v_cndmask_b32_e64 v188, 0, v9, s[98:99]
	v_max_u32_e32 v9, v184, v185
	v_max3_u32 v9, v9, v186, v187
	v_cndmask_b32_e64 v10, 0, v10, s[100:101]
	v_cmp_ne_u32_e32 vcc, v11, v8
	v_max3_u32 v9, v9, v188, v10
	v_cmp_ne_u32_e64 s[98:99], v12, v8
	v_cndmask_b32_e32 v11, 0, v11, vcc
	v_cmp_ne_u32_e64 s[100:101], v13, v8
	v_cndmask_b32_e64 v12, 0, v12, s[98:99]
	v_max3_u32 v9, v9, v11, v12
	v_cndmask_b32_e64 v13, 0, v13, s[100:101]
	v_cmp_ne_u32_e32 vcc, v14, v8
	v_cmp_ne_u32_e64 s[98:99], v15, v8
	v_cmp_ne_u32_e64 s[100:101], v86, v8
	v_cndmask_b32_e32 v14, 0, v14, vcc
	v_max3_u32 v9, v9, v13, v14
	v_cndmask_b32_e64 v15, 0, v15, s[98:99]
	v_cndmask_b32_e64 v86, 0, v86, s[100:101]
	v_cmp_ne_u32_e32 vcc, v87, v8
	v_max3_u32 v9, v9, v15, v86
	v_cmp_ne_u32_e64 s[98:99], v88, v8
	v_cndmask_b32_e32 v87, 0, v87, vcc
	v_cmp_ne_u32_e64 s[100:101], v89, v8
	v_cndmask_b32_e64 v88, 0, v88, s[98:99]
	v_max3_u32 v9, v9, v87, v88
	v_cndmask_b32_e64 v89, 0, v89, s[100:101]
	v_cmp_ne_u32_e32 vcc, v164, v8
	v_cmp_ne_u32_e64 s[98:99], v165, v8
	v_cmp_ne_u32_e64 s[100:101], v166, v8
	v_cndmask_b32_e32 v164, 0, v164, vcc
	v_max3_u32 v9, v9, v89, v164
	v_cndmask_b32_e64 v165, 0, v165, s[98:99]
	v_cndmask_b32_e64 v166, 0, v166, s[100:101]
	v_cmp_ne_u32_e32 vcc, v167, v8
	v_max3_u32 v9, v9, v165, v166
	v_cmp_ne_u32_e64 s[98:99], v168, v8
	v_cndmask_b32_e32 v167, 0, v167, vcc
	v_cmp_ne_u32_e64 s[100:101], v169, v8
	v_cndmask_b32_e64 v168, 0, v168, s[98:99]
	v_max3_u32 v9, v9, v167, v168
	v_cndmask_b32_e64 v169, 0, v169, s[100:101]
	v_cmp_ne_u32_e32 vcc, v171, v8
	v_cmp_ne_u32_e64 s[98:99], v172, v8
	v_cmp_ne_u32_e64 s[100:101], v173, v8
	v_cndmask_b32_e32 v171, 0, v171, vcc
	v_max3_u32 v9, v9, v169, v171
	v_cndmask_b32_e64 v172, 0, v172, s[98:99]
	v_cndmask_b32_e64 v173, 0, v173, s[100:101]
	v_cmp_ne_u32_e32 vcc, v176, v8
	v_max3_u32 v9, v9, v172, v173
	v_cmp_ne_u32_e64 s[98:99], v177, v8
	v_cndmask_b32_e32 v176, 0, v176, vcc
	v_cmp_ne_u32_e64 s[100:101], v178, v8
	v_cndmask_b32_e64 v177, 0, v177, s[98:99]
	v_max3_u32 v9, v9, v176, v177
	v_cndmask_b32_e64 v178, 0, v178, s[100:101]
	v_cmp_ne_u32_e32 vcc, v179, v8
	v_cmp_ne_u32_e64 s[98:99], v183, v8
	v_cmp_ne_u32_e64 s[100:101], v180, v8
	v_cndmask_b32_e32 v179, 0, v179, vcc
	v_max3_u32 v9, v9, v178, v179
	v_cndmask_b32_e64 v183, 0, v183, s[98:99]
	v_cndmask_b32_e64 v180, 0, v180, s[100:101]
	v_cmp_ne_u32_e32 vcc, v181, v8
	v_max3_u32 v9, v9, v183, v180
	v_cmp_ne_u32_e64 s[98:99], v182, v8
	v_cndmask_b32_e32 v181, 0, v181, vcc
	s_nop 0
	v_cndmask_b32_e64 v182, 0, v182, s[98:99]
	v_max3_u32 v9, v9, v181, v182
	v_mov_b32_e32 v189, v9
	s_nop 1
	v_permlane16_swap_b32 v9, v189
	s_nop 1
	s_waitcnt lgkmcnt(0)
	v_max_u32_e32 v9, v9, v189
	v_mov_b32_e32 v189, v9
	s_nop 1
	v_permlane32_swap_b32 v9, v189
	s_nop 1
	s_waitcnt lgkmcnt(0)
	v_max_u32_e32 v9, v9, v189
	v_cmp_ne_u32_e32 vcc, v184, v9
	v_cmp_ne_u32_e64 s[98:99], v185, v9
	v_cmp_ne_u32_e64 s[100:101], v186, v9
	v_cndmask_b32_e32 v184, 0, v184, vcc
	v_cndmask_b32_e64 v185, 0, v185, s[98:99]
	v_cndmask_b32_e64 v186, 0, v186, s[100:101]
	v_cmp_ne_u32_e32 vcc, v187, v9
	v_cmp_ne_u32_e64 s[98:99], v188, v9
	v_cmp_ne_u32_e64 s[100:101], v10, v9
	v_cndmask_b32_e32 v187, 0, v187, vcc
	v_cndmask_b32_e64 v188, 0, v188, s[98:99]
	v_cndmask_b32_e64 v189, 0, v10, s[100:101]
	v_cmp_ne_u32_e32 vcc, v11, v9
	v_max_u32_e32 v10, v184, v185
	v_max3_u32 v10, v10, v186, v187
	v_cndmask_b32_e32 v11, 0, v11, vcc
	v_cmp_ne_u32_e64 s[98:99], v12, v9
	v_max3_u32 v10, v10, v188, v189
	v_cmp_ne_u32_e64 s[100:101], v13, v9
	v_cndmask_b32_e64 v12, 0, v12, s[98:99]
	v_max3_u32 v10, v10, v11, v12
	v_cndmask_b32_e64 v13, 0, v13, s[100:101]
	v_cmp_ne_u32_e32 vcc, v14, v9
	v_cmp_ne_u32_e64 s[98:99], v15, v9
	v_cmp_ne_u32_e64 s[100:101], v86, v9
	v_cndmask_b32_e32 v14, 0, v14, vcc
	v_max3_u32 v10, v10, v13, v14
	v_cndmask_b32_e64 v15, 0, v15, s[98:99]
	v_cndmask_b32_e64 v86, 0, v86, s[100:101]
	v_cmp_ne_u32_e32 vcc, v87, v9
	v_max3_u32 v10, v10, v15, v86
	v_cmp_ne_u32_e64 s[98:99], v88, v9
	v_cndmask_b32_e32 v87, 0, v87, vcc
	v_cmp_ne_u32_e64 s[100:101], v89, v9
	v_cndmask_b32_e64 v88, 0, v88, s[98:99]
	v_max3_u32 v10, v10, v87, v88
	v_cndmask_b32_e64 v89, 0, v89, s[100:101]
	v_cmp_ne_u32_e32 vcc, v164, v9
	v_cmp_ne_u32_e64 s[98:99], v165, v9
	v_cmp_ne_u32_e64 s[100:101], v166, v9
	v_cndmask_b32_e32 v164, 0, v164, vcc
	v_max3_u32 v10, v10, v89, v164
	v_cndmask_b32_e64 v165, 0, v165, s[98:99]
	v_cndmask_b32_e64 v166, 0, v166, s[100:101]
	v_cmp_ne_u32_e32 vcc, v167, v9
	v_max3_u32 v10, v10, v165, v166
	v_cmp_ne_u32_e64 s[98:99], v168, v9
	v_cndmask_b32_e32 v167, 0, v167, vcc
	v_cmp_ne_u32_e64 s[100:101], v169, v9
	v_cndmask_b32_e64 v168, 0, v168, s[98:99]
	v_max3_u32 v10, v10, v167, v168
	v_cndmask_b32_e64 v169, 0, v169, s[100:101]
	v_cmp_ne_u32_e32 vcc, v171, v9
	v_cmp_ne_u32_e64 s[98:99], v172, v9
	v_cmp_ne_u32_e64 s[100:101], v173, v9
	v_cndmask_b32_e32 v171, 0, v171, vcc
	v_max3_u32 v10, v10, v169, v171
	v_cndmask_b32_e64 v172, 0, v172, s[98:99]
	v_cndmask_b32_e64 v173, 0, v173, s[100:101]
	v_cmp_ne_u32_e32 vcc, v176, v9
	v_max3_u32 v10, v10, v172, v173
	v_cmp_ne_u32_e64 s[98:99], v177, v9
	v_cndmask_b32_e32 v176, 0, v176, vcc
	v_cmp_ne_u32_e64 s[100:101], v178, v9
	v_cndmask_b32_e64 v177, 0, v177, s[98:99]
	v_max3_u32 v10, v10, v176, v177
	v_cndmask_b32_e64 v178, 0, v178, s[100:101]
	v_cmp_ne_u32_e32 vcc, v179, v9
	v_cmp_ne_u32_e64 s[98:99], v183, v9
	v_cmp_ne_u32_e64 s[100:101], v180, v9
	v_cndmask_b32_e32 v179, 0, v179, vcc
	v_max3_u32 v10, v10, v178, v179
	v_cndmask_b32_e64 v183, 0, v183, s[98:99]
	v_cndmask_b32_e64 v180, 0, v180, s[100:101]
	v_cmp_ne_u32_e32 vcc, v181, v9
	v_max3_u32 v10, v10, v183, v180
	v_cmp_ne_u32_e64 s[98:99], v182, v9
	v_cndmask_b32_e32 v181, 0, v181, vcc
	s_nop 0
	v_cndmask_b32_e64 v182, 0, v182, s[98:99]
	v_max3_u32 v10, v10, v181, v182
	v_mov_b32_e32 v190, v10
	s_nop 1
	v_permlane16_swap_b32 v10, v190
	s_nop 1
	s_waitcnt lgkmcnt(0)
; DI void peer_topk_wave(const Params& p, int item, unsigned* lds  ) {
;     ...
; #pragma unroll
;     for (int rr = 0; rr < 16; ++rr) {
;       unsigned m = 0;
; #pragma unroll
;       for (int i = 0; i < 32; ++i) m = umax(m, kk[i]);
;       m = umax(m, (unsigned)__shfl_xor((int)m, 16));
;       m = umax(m, (unsigned)__shfl_xor((int)m, 32));
;       win[pp][rr] = m;
; #pragma unroll
;       for (int i = 0; i < 32; ++i) kk[i] = (kk[i] == m) ? 0u : kk[i];
;     }
	v_max_u32_e32 v10, v10, v190
	v_mov_b32_e32 v190, v10
	s_nop 1
	v_permlane32_swap_b32 v10, v190
	s_nop 1
	s_waitcnt lgkmcnt(0)
	v_max_u32_e32 v10, v10, v190
	v_cmp_ne_u32_e32 vcc, v184, v10
	v_cmp_ne_u32_e64 s[98:99], v185, v10
	v_cmp_ne_u32_e64 s[100:101], v186, v10
	v_cndmask_b32_e32 v184, 0, v184, vcc
	v_cndmask_b32_e64 v185, 0, v185, s[98:99]
	v_cndmask_b32_e64 v186, 0, v186, s[100:101]
	v_cmp_ne_u32_e32 vcc, v187, v10
	v_cmp_ne_u32_e64 s[98:99], v188, v10
	v_cmp_ne_u32_e64 s[100:101], v189, v10
	v_cndmask_b32_e32 v187, 0, v187, vcc
	v_cndmask_b32_e64 v188, 0, v188, s[98:99]
	v_cndmask_b32_e64 v189, 0, v189, s[100:101]
	v_cmp_ne_u32_e32 vcc, v11, v10
	v_cmp_ne_u32_e64 s[98:99], v12, v10
	v_cmp_ne_u32_e64 s[100:101], v13, v10
	v_cndmask_b32_e32 v190, 0, v11, vcc
	v_max_u32_e32 v11, v184, v185
	v_max3_u32 v11, v11, v186, v187
	v_cndmask_b32_e64 v12, 0, v12, s[98:99]
	v_max3_u32 v11, v11, v188, v189
	v_max3_u32 v11, v11, v190, v12
	v_cndmask_b32_e64 v13, 0, v13, s[100:101]
	v_cmp_ne_u32_e32 vcc, v14, v10
	v_cmp_ne_u32_e64 s[98:99], v15, v10
	v_cmp_ne_u32_e64 s[100:101], v86, v10
	v_cndmask_b32_e32 v14, 0, v14, vcc
	v_max3_u32 v11, v11, v13, v14
	v_cndmask_b32_e64 v15, 0, v15, s[98:99]
	v_cndmask_b32_e64 v86, 0, v86, s[100:101]
	v_cmp_ne_u32_e32 vcc, v87, v10
	v_max3_u32 v11, v11, v15, v86
	v_cmp_ne_u32_e64 s[98:99], v88, v10
	v_cndmask_b32_e32 v87, 0, v87, vcc
	v_cmp_ne_u32_e64 s[100:101], v89, v10
	v_cndmask_b32_e64 v88, 0, v88, s[98:99]
	v_max3_u32 v11, v11, v87, v88
	v_cndmask_b32_e64 v89, 0, v89, s[100:101]
	v_cmp_ne_u32_e32 vcc, v164, v10
	v_cmp_ne_u32_e64 s[98:99], v165, v10
	v_cmp_ne_u32_e64 s[100:101], v166, v10
	v_cndmask_b32_e32 v164, 0, v164, vcc
	v_max3_u32 v11, v11, v89, v164
	v_cndmask_b32_e64 v165, 0, v165, s[98:99]
	v_cndmask_b32_e64 v166, 0, v166, s[100:101]
	v_cmp_ne_u32_e32 vcc, v167, v10
	v_max3_u32 v11, v11, v165, v166
	v_cmp_ne_u32_e64 s[98:99], v168, v10
	v_cndmask_b32_e32 v167, 0, v167, vcc
	v_cmp_ne_u32_e64 s[100:101], v169, v10
	v_cndmask_b32_e64 v168, 0, v168, s[98:99]
	v_max3_u32 v11, v11, v167, v168
	v_cndmask_b32_e64 v169, 0, v169, s[100:101]
	v_cmp_ne_u32_e32 vcc, v171, v10
	v_cmp_ne_u32_e64 s[98:99], v172, v10
	v_cmp_ne_u32_e64 s[100:101], v173, v10
	v_cndmask_b32_e32 v171, 0, v171, vcc
	v_max3_u32 v11, v11, v169, v171
	v_cndmask_b32_e64 v172, 0, v172, s[98:99]
	v_cndmask_b32_e64 v173, 0, v173, s[100:101]
	v_cmp_ne_u32_e32 vcc, v176, v10
	v_max3_u32 v11, v11, v172, v173
	v_cmp_ne_u32_e64 s[98:99], v177, v10
	v_cndmask_b32_e32 v176, 0, v176, vcc
	v_cmp_ne_u32_e64 s[100:101], v178, v10
	v_cndmask_b32_e64 v177, 0, v177, s[98:99]
	v_max3_u32 v11, v11, v176, v177
	v_cndmask_b32_e64 v178, 0, v178, s[100:101]
	v_cmp_ne_u32_e32 vcc, v179, v10
	v_cmp_ne_u32_e64 s[98:99], v183, v10
	v_cmp_ne_u32_e64 s[100:101], v180, v10
	v_cndmask_b32_e32 v179, 0, v179, vcc
	v_max3_u32 v11, v11, v178, v179
	v_cndmask_b32_e64 v183, 0, v183, s[98:99]
	v_cndmask_b32_e64 v180, 0, v180, s[100:101]
	v_cmp_ne_u32_e32 vcc, v181, v10
	v_max3_u32 v11, v11, v183, v180
	v_cmp_ne_u32_e64 s[98:99], v182, v10
	v_cndmask_b32_e32 v181, 0, v181, vcc
	s_nop 0
	v_cndmask_b32_e64 v182, 0, v182, s[98:99]
	v_max3_u32 v11, v11, v181, v182
	v_mov_b32_e32 v191, v11
	s_nop 1
	v_permlane16_swap_b32 v11, v191
	s_nop 1
	s_waitcnt lgkmcnt(0)
	v_max_u32_e32 v11, v11, v191
	v_mov_b32_e32 v191, v11
	s_nop 1
	v_permlane32_swap_b32 v11, v191
	s_nop 1
	s_waitcnt lgkmcnt(0)
	v_max_u32_e32 v11, v11, v191
	v_cmp_ne_u32_e32 vcc, v184, v11
	v_cmp_ne_u32_e64 s[98:99], v185, v11
	v_cmp_ne_u32_e64 s[100:101], v186, v11
	v_cndmask_b32_e32 v184, 0, v184, vcc
	v_cndmask_b32_e64 v185, 0, v185, s[98:99]
	v_cndmask_b32_e64 v186, 0, v186, s[100:101]
	v_cmp_ne_u32_e32 vcc, v187, v11
	v_cmp_ne_u32_e64 s[98:99], v188, v11
	v_cmp_ne_u32_e64 s[100:101], v189, v11
	v_cndmask_b32_e32 v187, 0, v187, vcc
	v_cndmask_b32_e64 v188, 0, v188, s[98:99]
	v_cndmask_b32_e64 v189, 0, v189, s[100:101]
	v_cmp_ne_u32_e32 vcc, v190, v11
	v_cmp_ne_u32_e64 s[98:99], v12, v11
	v_cmp_ne_u32_e64 s[100:101], v13, v11
	v_cndmask_b32_e32 v190, 0, v190, vcc
	v_cndmask_b32_e64 v191, 0, v12, s[98:99]
	v_max_u32_e32 v12, v184, v185
	v_max3_u32 v12, v12, v186, v187
	v_cndmask_b32_e64 v13, 0, v13, s[100:101]
	v_cmp_ne_u32_e32 vcc, v14, v11
	v_max3_u32 v12, v12, v188, v189
	v_max3_u32 v12, v12, v190, v191
	v_cndmask_b32_e32 v14, 0, v14, vcc
	v_cmp_ne_u32_e64 s[98:99], v15, v11
	v_max3_u32 v12, v12, v13, v14
	v_cmp_ne_u32_e64 s[100:101], v86, v11
	v_cndmask_b32_e64 v15, 0, v15, s[98:99]
	v_cmp_ne_u32_e32 vcc, v87, v11
	v_cndmask_b32_e64 v86, 0, v86, s[100:101]
	v_max3_u32 v12, v12, v15, v86
	v_cndmask_b32_e32 v87, 0, v87, vcc
	v_cmp_ne_u32_e64 s[98:99], v88, v11
	v_cmp_ne_u32_e64 s[100:101], v89, v11
	v_cmp_ne_u32_e32 vcc, v164, v11
	v_cndmask_b32_e64 v88, 0, v88, s[98:99]
	v_max3_u32 v12, v12, v87, v88
	v_cndmask_b32_e64 v89, 0, v89, s[100:101]
	v_cndmask_b32_e32 v164, 0, v164, vcc
	v_cmp_ne_u32_e64 s[98:99], v165, v11
	v_max3_u32 v12, v12, v89, v164
	v_cmp_ne_u32_e64 s[100:101], v166, v11
	v_cndmask_b32_e64 v165, 0, v165, s[98:99]
	v_cmp_ne_u32_e32 vcc, v167, v11
	v_cndmask_b32_e64 v166, 0, v166, s[100:101]
	v_max3_u32 v12, v12, v165, v166
	v_cndmask_b32_e32 v167, 0, v167, vcc
	v_cmp_ne_u32_e64 s[98:99], v168, v11
	v_cmp_ne_u32_e64 s[100:101], v169, v11
	v_cmp_ne_u32_e32 vcc, v171, v11
	v_cndmask_b32_e64 v168, 0, v168, s[98:99]
	v_max3_u32 v12, v12, v167, v168
	v_cndmask_b32_e64 v169, 0, v169, s[100:101]
	v_cndmask_b32_e32 v171, 0, v171, vcc
	v_cmp_ne_u32_e64 s[98:99], v172, v11
	v_max3_u32 v12, v12, v169, v171
	v_cmp_ne_u32_e64 s[100:101], v173, v11
	v_cndmask_b32_e64 v172, 0, v172, s[98:99]
	v_cmp_ne_u32_e32 vcc, v176, v11
	v_cndmask_b32_e64 v173, 0, v173, s[100:101]
	v_max3_u32 v12, v12, v172, v173
	v_cndmask_b32_e32 v176, 0, v176, vcc
	v_cmp_ne_u32_e64 s[98:99], v177, v11
	v_cmp_ne_u32_e64 s[100:101], v178, v11
	v_cmp_ne_u32_e32 vcc, v179, v11
	v_cndmask_b32_e64 v177, 0, v177, s[98:99]
	v_max3_u32 v12, v12, v176, v177
	v_cndmask_b32_e64 v178, 0, v178, s[100:101]
	v_cndmask_b32_e32 v179, 0, v179, vcc
	v_cmp_ne_u32_e64 s[98:99], v183, v11
	v_max3_u32 v12, v12, v178, v179
	v_cmp_ne_u32_e64 s[100:101], v180, v11
	v_cndmask_b32_e64 v183, 0, v183, s[98:99]
	v_cmp_ne_u32_e32 vcc, v181, v11
	v_cndmask_b32_e64 v180, 0, v180, s[100:101]
	v_max3_u32 v12, v12, v183, v180
	v_cndmask_b32_e32 v181, 0, v181, vcc
	v_cmp_ne_u32_e64 s[98:99], v182, v11
	s_nop 0
	s_nop 0
	v_cndmask_b32_e64 v182, 0, v182, s[98:99]
	v_max3_u32 v12, v12, v181, v182
	v_mov_b32_e32 v192, v12
	s_nop 1
	v_permlane16_swap_b32 v12, v192
	s_nop 1
	s_waitcnt lgkmcnt(0)
; DI void peer_topk_wave(const Params& p, int item, unsigned* lds  ) {
;     ...
;     for (int rr = 0; rr < 16; ++rr) {
;       unsigned m = 0;
; #pragma unroll
;       for (int i = 0; i < 32; ++i) m = umax(m, kk[i]);
;       m = umax(m, (unsigned)__shfl_xor((int)m, 16));
;       m = umax(m, (unsigned)__shfl_xor((int)m, 32));
;       win[pp][rr] = m;
; #pragma unroll
;       for (int i = 0; i < 32; ++i) kk[i] = (kk[i] == m) ? 0u : kk[i];
	v_max_u32_e32 v12, v12, v192
	v_mov_b32_e32 v192, v12
	s_nop 1
	v_permlane32_swap_b32 v12, v192
	s_nop 1
	s_waitcnt lgkmcnt(0)
	v_max_u32_e32 v12, v12, v192
	v_cmp_ne_u32_e32 vcc, v184, v12
	v_cmp_ne_u32_e64 s[98:99], v185, v12
	v_cmp_ne_u32_e64 s[100:101], v186, v12
	v_cndmask_b32_e32 v184, 0, v184, vcc
	v_cndmask_b32_e64 v185, 0, v185, s[98:99]
	v_cndmask_b32_e64 v186, 0, v186, s[100:101]
	v_cmp_ne_u32_e32 vcc, v187, v12
	v_cmp_ne_u32_e64 s[98:99], v188, v12
	v_cmp_ne_u32_e64 s[100:101], v189, v12
	v_cndmask_b32_e32 v187, 0, v187, vcc
	v_cndmask_b32_e64 v188, 0, v188, s[98:99]
	v_cndmask_b32_e64 v189, 0, v189, s[100:101]
	v_cmp_ne_u32_e32 vcc, v190, v12
	v_cmp_ne_u32_e64 s[98:99], v191, v12
	v_cmp_ne_u32_e64 s[100:101], v13, v12
	v_cndmask_b32_e32 v190, 0, v190, vcc
	v_cndmask_b32_e64 v191, 0, v191, s[98:99]
	v_cndmask_b32_e64 v192, 0, v13, s[100:101]
	v_cmp_ne_u32_e32 vcc, v14, v12
	v_max_u32_e32 v13, v184, v185
	v_max3_u32 v13, v13, v186, v187
	v_cndmask_b32_e32 v14, 0, v14, vcc
	v_cmp_ne_u32_e64 s[98:99], v15, v12
	v_max3_u32 v13, v13, v188, v189
	v_max3_u32 v13, v13, v190, v191
	v_cndmask_b32_e64 v15, 0, v15, s[98:99]
	v_cmp_ne_u32_e64 s[100:101], v86, v12
	v_max3_u32 v13, v13, v192, v14
	v_cmp_ne_u32_e32 vcc, v87, v12
	v_cndmask_b32_e64 v86, 0, v86, s[100:101]
	v_max3_u32 v13, v13, v15, v86
	v_cndmask_b32_e32 v87, 0, v87, vcc
	v_cmp_ne_u32_e64 s[98:99], v88, v12
	v_cmp_ne_u32_e64 s[100:101], v89, v12
	v_cmp_ne_u32_e32 vcc, v164, v12
	v_cndmask_b32_e64 v88, 0, v88, s[98:99]
	v_max3_u32 v13, v13, v87, v88
	v_cndmask_b32_e64 v89, 0, v89, s[100:101]
	v_cndmask_b32_e32 v164, 0, v164, vcc
	v_cmp_ne_u32_e64 s[98:99], v165, v12
	v_max3_u32 v13, v13, v89, v164
	v_cmp_ne_u32_e64 s[100:101], v166, v12
	v_cndmask_b32_e64 v165, 0, v165, s[98:99]
	v_cmp_ne_u32_e32 vcc, v167, v12
	v_cndmask_b32_e64 v166, 0, v166, s[100:101]
	v_max3_u32 v13, v13, v165, v166
	v_cndmask_b32_e32 v167, 0, v167, vcc
	v_cmp_ne_u32_e64 s[98:99], v168, v12
	v_cmp_ne_u32_e64 s[100:101], v169, v12
	v_cmp_ne_u32_e32 vcc, v171, v12
	v_cndmask_b32_e64 v168, 0, v168, s[98:99]
	v_max3_u32 v13, v13, v167, v168
	v_cndmask_b32_e64 v169, 0, v169, s[100:101]
	v_cndmask_b32_e32 v171, 0, v171, vcc
	v_cmp_ne_u32_e64 s[98:99], v172, v12
	v_max3_u32 v13, v13, v169, v171
	v_cmp_ne_u32_e64 s[100:101], v173, v12
	v_cndmask_b32_e64 v172, 0, v172, s[98:99]
	v_cmp_ne_u32_e32 vcc, v176, v12
	v_cndmask_b32_e64 v173, 0, v173, s[100:101]
	v_max3_u32 v13, v13, v172, v173
	v_cndmask_b32_e32 v176, 0, v176, vcc
	v_cmp_ne_u32_e64 s[98:99], v177, v12
	v_cmp_ne_u32_e64 s[100:101], v178, v12
	v_cmp_ne_u32_e32 vcc, v179, v12
	v_cndmask_b32_e64 v177, 0, v177, s[98:99]
	v_max3_u32 v13, v13, v176, v177
	v_cndmask_b32_e64 v178, 0, v178, s[100:101]
	v_cndmask_b32_e32 v179, 0, v179, vcc
	v_cmp_ne_u32_e64 s[98:99], v183, v12
	v_max3_u32 v13, v13, v178, v179
	v_cmp_ne_u32_e64 s[100:101], v180, v12
	v_cndmask_b32_e64 v183, 0, v183, s[98:99]
	v_cmp_ne_u32_e32 vcc, v181, v12
	v_cndmask_b32_e64 v180, 0, v180, s[100:101]
	v_max3_u32 v13, v13, v183, v180
	v_cndmask_b32_e32 v181, 0, v181, vcc
	v_cmp_ne_u32_e64 s[98:99], v182, v12
	s_nop 0
	s_nop 0
	v_cndmask_b32_e64 v182, 0, v182, s[98:99]
	v_max3_u32 v13, v13, v181, v182
	v_mov_b32_e32 v193, v13
	s_nop 1
	v_permlane16_swap_b32 v13, v193
	s_nop 1
	s_waitcnt lgkmcnt(0)
	v_max_u32_e32 v13, v13, v193
	v_mov_b32_e32 v193, v13
	s_nop 1
	v_permlane32_swap_b32 v13, v193
	s_nop 1
	s_waitcnt lgkmcnt(0)
	v_max_u32_e32 v13, v13, v193
	v_cmp_ne_u32_e32 vcc, v184, v13
	v_cmp_ne_u32_e64 s[98:99], v185, v13
	v_cmp_ne_u32_e64 s[100:101], v186, v13
	v_cndmask_b32_e32 v184, 0, v184, vcc
	v_cndmask_b32_e64 v185, 0, v185, s[98:99]
	v_cndmask_b32_e64 v186, 0, v186, s[100:101]
	v_cmp_ne_u32_e32 vcc, v187, v13
	v_cmp_ne_u32_e64 s[98:99], v188, v13
	v_cmp_ne_u32_e64 s[100:101], v189, v13
	v_cndmask_b32_e32 v187, 0, v187, vcc
	v_cndmask_b32_e64 v188, 0, v188, s[98:99]
	v_cndmask_b32_e64 v189, 0, v189, s[100:101]
	v_cmp_ne_u32_e32 vcc, v190, v13
	v_cmp_ne_u32_e64 s[98:99], v191, v13
	v_cmp_ne_u32_e64 s[100:101], v192, v13
	v_cndmask_b32_e32 v190, 0, v190, vcc
	v_cndmask_b32_e64 v191, 0, v191, s[98:99]
	v_cndmask_b32_e64 v192, 0, v192, s[100:101]
	v_cmp_ne_u32_e32 vcc, v14, v13
	v_cmp_ne_u32_e64 s[98:99], v15, v13
	v_cmp_ne_u32_e64 s[100:101], v86, v13
	v_cndmask_b32_e32 v193, 0, v14, vcc
	v_max_u32_e32 v14, v184, v185
	v_max3_u32 v14, v14, v186, v187
	v_cndmask_b32_e64 v15, 0, v15, s[98:99]
	v_max3_u32 v14, v14, v188, v189
	v_max3_u32 v14, v14, v190, v191
	v_cndmask_b32_e64 v86, 0, v86, s[100:101]
	v_cmp_ne_u32_e32 vcc, v87, v13
	v_max3_u32 v14, v14, v192, v193
	v_max3_u32 v14, v14, v15, v86
	v_cndmask_b32_e32 v87, 0, v87, vcc
	v_cmp_ne_u32_e64 s[98:99], v88, v13
	v_cmp_ne_u32_e64 s[100:101], v89, v13
	v_cmp_ne_u32_e32 vcc, v164, v13
	v_cndmask_b32_e64 v88, 0, v88, s[98:99]
	v_max3_u32 v14, v14, v87, v88
	v_cndmask_b32_e64 v89, 0, v89, s[100:101]
	v_cndmask_b32_e32 v164, 0, v164, vcc
	v_cmp_ne_u32_e64 s[98:99], v165, v13
	v_max3_u32 v14, v14, v89, v164
	v_cmp_ne_u32_e64 s[100:101], v166, v13
	v_cndmask_b32_e64 v165, 0, v165, s[98:99]
	v_cmp_ne_u32_e32 vcc, v167, v13
	v_cndmask_b32_e64 v166, 0, v166, s[100:101]
	v_max3_u32 v14, v14, v165, v166
	v_cndmask_b32_e32 v167, 0, v167, vcc
	v_cmp_ne_u32_e64 s[98:99], v168, v13
	v_cmp_ne_u32_e64 s[100:101], v169, v13
	v_cmp_ne_u32_e32 vcc, v171, v13
	v_cndmask_b32_e64 v168, 0, v168, s[98:99]
	v_max3_u32 v14, v14, v167, v168
	v_cndmask_b32_e64 v169, 0, v169, s[100:101]
	v_cndmask_b32_e32 v171, 0, v171, vcc
	v_cmp_ne_u32_e64 s[98:99], v172, v13
	v_max3_u32 v14, v14, v169, v171
	v_cmp_ne_u32_e64 s[100:101], v173, v13
	v_cndmask_b32_e64 v172, 0, v172, s[98:99]
	v_cmp_ne_u32_e32 vcc, v176, v13
	v_cndmask_b32_e64 v173, 0, v173, s[100:101]
	v_max3_u32 v14, v14, v172, v173
	v_cndmask_b32_e32 v176, 0, v176, vcc
	v_cmp_ne_u32_e64 s[98:99], v177, v13
	v_cmp_ne_u32_e64 s[100:101], v178, v13
	v_cmp_ne_u32_e32 vcc, v179, v13
	v_cndmask_b32_e64 v177, 0, v177, s[98:99]
	v_max3_u32 v14, v14, v176, v177
	v_cndmask_b32_e64 v178, 0, v178, s[100:101]
	v_cndmask_b32_e32 v179, 0, v179, vcc
	v_cmp_ne_u32_e64 s[98:99], v183, v13
	v_max3_u32 v14, v14, v178, v179
	v_cmp_ne_u32_e64 s[100:101], v180, v13
	v_cndmask_b32_e64 v183, 0, v183, s[98:99]
	v_cmp_ne_u32_e32 vcc, v181, v13
	v_cndmask_b32_e64 v180, 0, v180, s[100:101]
	v_max3_u32 v14, v14, v183, v180
	v_cndmask_b32_e32 v181, 0, v181, vcc
	v_cmp_ne_u32_e64 s[98:99], v182, v13
	s_nop 0
	s_nop 0
	v_cndmask_b32_e64 v182, 0, v182, s[98:99]
	v_max3_u32 v14, v14, v181, v182
	v_mov_b32_e32 v194, v14
	s_nop 1
	v_permlane16_swap_b32 v14, v194
	s_nop 1
	s_waitcnt lgkmcnt(0)
; DI float unordf(unsigned k) { unsigned u = (k & 0x80000000u) ? (k & 0x7fffffffu) : ~k; return __uint_as_float(u); }
; DI void peer_topk_wave(const Params& p, int item, unsigned* lds  ) {
;     ...
;     for (int rr = 0; rr < 16; ++rr) {
;       unsigned m = 0;
; #pragma unroll
;       for (int i = 0; i < 32; ++i) m = umax(m, kk[i]);
;       m = umax(m, (unsigned)__shfl_xor((int)m, 16));
;       m = umax(m, (unsigned)__shfl_xor((int)m, 32));
;       win[pp][rr] = m;
; #pragma unroll
;       for (int i = 0; i < 32; ++i) kk[i] = (kk[i] == m) ? 0u : kk[i];
;     }
;   }
;   float f0[16], f1[16];
; #pragma unroll
;   for (int i = 0; i < 16; ++i) { f0[i] = unordf(win[0][i] & ~127u); f1[i] = unordf(win[1][i] & ~127u); }
;   unsigned cand[13];
	v_max_u32_e32 v14, v14, v194
	ds_bpermute_b32 v194, v112, v14
	s_waitcnt lgkmcnt(0)
	v_max_u32_e32 v14, v14, v194
	v_cmp_ne_u32_e32 vcc, v185, v14
	v_cmp_eq_u32_e64 s[68:69], v184, v14
	v_cmp_eq_u32_e64 s[70:71], v186, v14
	v_cndmask_b32_e32 v185, 0, v185, vcc
	v_max_u32_e32 v184, v184, v185
	v_cndmask_b32_e64 v184, v184, v185, s[68:69]
	v_max_u32_e32 v185, v184, v186
	v_cndmask_b32_e64 v184, v185, v184, s[70:71]
	v_cmp_eq_u32_e64 s[66:67], v187, v14
	v_max_u32_e32 v185, v184, v187
	v_cmp_eq_u32_e64 s[64:65], v188, v14
	v_cndmask_b32_e64 v184, v185, v184, s[66:67]
	v_max_u32_e32 v185, v184, v188
	v_cndmask_b32_e64 v184, v185, v184, s[64:65]
	v_cmp_eq_u32_e64 s[62:63], v189, v14
	v_max_u32_e32 v185, v184, v189
	v_cmp_eq_u32_e64 s[60:61], v190, v14
	v_cndmask_b32_e64 v184, v185, v184, s[62:63]
	v_max_u32_e32 v185, v184, v190
	v_cndmask_b32_e64 v184, v185, v184, s[60:61]
	v_cmp_eq_u32_e64 s[58:59], v191, v14
	v_max_u32_e32 v185, v184, v191
	v_cmp_eq_u32_e64 s[56:57], v192, v14
	v_cndmask_b32_e64 v184, v185, v184, s[58:59]
	v_max_u32_e32 v185, v184, v192
	v_cndmask_b32_e64 v184, v185, v184, s[56:57]
	v_cmp_eq_u32_e64 s[54:55], v193, v14
	v_max_u32_e32 v185, v184, v193
	v_cmp_eq_u32_e64 s[52:53], v15, v14
	v_cndmask_b32_e64 v184, v185, v184, s[54:55]
	v_max_u32_e32 v15, v184, v15
	v_cndmask_b32_e64 v15, v15, v184, s[52:53]
	v_cmp_eq_u32_e64 s[50:51], v86, v14
	v_max_u32_e32 v86, v15, v86
	v_cmp_eq_u32_e64 s[48:49], v87, v14
	v_cndmask_b32_e64 v15, v86, v15, s[50:51]
	v_max_u32_e32 v86, v15, v87
	v_cndmask_b32_e64 v15, v86, v15, s[48:49]
	v_cmp_eq_u32_e64 s[46:47], v88, v14
	v_max_u32_e32 v86, v15, v88
	v_cmp_eq_u32_e64 s[44:45], v89, v14
	v_cndmask_b32_e64 v15, v86, v15, s[46:47]
	v_max_u32_e32 v86, v15, v89
	v_cndmask_b32_e64 v15, v86, v15, s[44:45]
	v_cmp_eq_u32_e64 s[42:43], v164, v14
	v_max_u32_e32 v86, v15, v164
	v_cmp_eq_u32_e64 s[40:41], v165, v14
	v_cndmask_b32_e64 v15, v86, v15, s[42:43]
	v_max_u32_e32 v86, v15, v165
	v_cndmask_b32_e64 v15, v86, v15, s[40:41]
	v_cmp_eq_u32_e64 s[38:39], v166, v14
	v_max_u32_e32 v86, v15, v166
	v_cmp_eq_u32_e64 s[36:37], v167, v14
	v_cndmask_b32_e64 v15, v86, v15, s[38:39]
	v_max_u32_e32 v86, v15, v167
	v_cndmask_b32_e64 v15, v86, v15, s[36:37]
	v_cmp_eq_u32_e64 s[34:35], v168, v14
	v_max_u32_e32 v86, v15, v168
	v_cmp_eq_u32_e64 s[30:31], v169, v14
	v_cndmask_b32_e64 v15, v86, v15, s[34:35]
	v_max_u32_e32 v86, v15, v169
	v_cndmask_b32_e64 v15, v86, v15, s[30:31]
	v_cmp_eq_u32_e64 s[28:29], v171, v14
	v_max_u32_e32 v86, v15, v171
	v_cmp_eq_u32_e64 s[26:27], v172, v14
	v_cndmask_b32_e64 v15, v86, v15, s[28:29]
	v_max_u32_e32 v86, v15, v172
	v_cndmask_b32_e64 v15, v86, v15, s[26:27]
	v_cmp_eq_u32_e64 s[24:25], v173, v14
	v_max_u32_e32 v86, v15, v173
	v_cmp_eq_u32_e64 s[22:23], v176, v14
	v_cndmask_b32_e64 v15, v86, v15, s[24:25]
	v_max_u32_e32 v86, v15, v176
	v_cndmask_b32_e64 v15, v86, v15, s[22:23]
	v_cmp_eq_u32_e64 s[20:21], v177, v14
	v_max_u32_e32 v86, v15, v177
	v_cmp_eq_u32_e64 s[18:19], v178, v14
	v_cndmask_b32_e64 v15, v86, v15, s[20:21]
	v_max_u32_e32 v86, v15, v178
	v_cndmask_b32_e64 v15, v86, v15, s[18:19]
	v_cmp_eq_u32_e64 s[16:17], v179, v14
	v_max_u32_e32 v86, v15, v179
	v_cmp_eq_u32_e64 s[14:15], v183, v14
	v_cndmask_b32_e64 v15, v86, v15, s[16:17]
	v_max_u32_e32 v86, v15, v183
	v_cndmask_b32_e64 v15, v86, v15, s[14:15]
	v_cmp_eq_u32_e64 s[2:3], v180, v14
	v_max_u32_e32 v86, v15, v180
	v_cmp_eq_u32_e64 s[0:1], v181, v14
	v_cndmask_b32_e64 v15, v86, v15, s[2:3]
	v_max_u32_e32 v86, v15, v181
	v_cndmask_b32_e64 v15, v86, v15, s[0:1]
	v_cmp_eq_u32_e32 vcc, v182, v14
	v_max_u32_e32 v86, v15, v182
	v_bitop3_b32 v87, v0, s81, v0 bitop3:0xcf
	v_cndmask_b32_e32 v15, v86, v15, vcc
	ds_bpermute_b32 v86, v111, v15
	v_cmp_gt_i32_e32 vcc, 0, v0
	s_waitcnt lgkmcnt(0)
	v_max_u32_e32 v15, v15, v86
	ds_bpermute_b32 v166, v112, v15
	v_and_b32_e32 v86, 0x7fffff80, v0
	v_cndmask_b32_e32 v89, v87, v86, vcc
	v_and_b32_e32 v86, 0x7fffff80, v1
	v_bitop3_b32 v87, v1, s81, v1 bitop3:0xcf
	v_cmp_gt_i32_e32 vcc, 0, v1
	s_nop 1
	v_cndmask_b32_e32 v164, v87, v86, vcc
	v_cmp_lt_i32_e32 vcc, 0, v175
	v_mov_b32_e32 v86, v89
	s_and_saveexec_b64 s[0:1], vcc
	s_cbranch_execz .LBB0_1097
	v_cmp_ne_u32_e32 vcc, 1, v175
	s_and_saveexec_b64 s[2:3], vcc
	s_xor_b64 s[2:3], exec, s[2:3]
	v_cndmask_b32_e64 v86, v164, v89, s[10:11]
	s_andn2_saveexec_b64 s[2:3], s[2:3]
	v_and_b32_e32 v86, 0x7fffff80, v13
	v_bitop3_b32 v87, v13, s81, v13 bitop3:0xcf
	v_cmp_gt_i32_e32 vcc, 0, v13
	s_nop 1
	v_cndmask_b32_e32 v86, v87, v86, vcc
	s_or_b64 exec, exec, s[2:3]
